# half-0 WKV scan inner loop rewritten: 8 lanes per state row, two row groups per wave sharing each LDS operand fetch (half the LDS reads), 32-step unroll
# speedup vs baseline: 1.0143x; 1.0143x over previous
; #define LAS __attribute__((address_space(3)))
; template <int L, int NSW, int PW0, int NPAIR, int PD> ...
;     ...
;     } else {
;         float St[EPL];
; #pragma unroll
;         for (int e = 0; e < EPL; ++e) St[e] = 0.f;
;         float ykeep = 0.f;
;         for (int c = 0; c < NC; ++c) {
;         if (wid < NSW && !(pm & 2)) {
;             const LAS float* buf = bufs + (c & 1) * BUF_FLOATS;
;             const LAS float* lb = buf + 4 * s; const LAS float* lv = buf + 320 + row;
;             asm volatile("" : "+v"(lb), "+v"(lv));
;             f32x4 naA[NG], wrA[NG], naB[NG], wrB[NG], w[NG], b[NG], kd[NG]; float vi; f32x2 sc;
.LBB0_668:
	s_mov_b64 s[8:9], -1
	s_and_b64 vcc, exec, s[6:7]
	s_waitcnt lgkmcnt(0)
	s_barrier
	s_cbranch_vccz .LBB0_680
	s_cmp_lt_i32 s48, 4
	s_cselect_b64 s[8:9], -1, 0
	s_add_i32 s6, s19, 0x7f
	s_cmpk_lt_u32 s6, 0xff
	s_cselect_b64 s[6:7], -1, 0
	s_ashr_i32 s71, s70, 31
	v_or_b32_e32 v208, s36, v241
	s_lshl_b64 s[36:37], s[70:71], 25
	s_add_u32 s36, s30, s36
	s_addc_u32 s37, s31, s37
	v_mov_b32_e32 v237, 0x3a27c5ac
	v_and_b32_e32 v126, 7, v240
	v_lshrrev_b32_e32 v134, 3, v240
	v_lshl_add_u32 v134, s48, 4, v134
	v_lshlrev_b32_e32 v135, 5, v126
	v_lshlrev_b32_e32 v136, 2, v134
	v_add_u32_e32 v136, 0x500, v136
	v_lshl_add_u64 v[130:131], v[182:183], 1, s[36:37]
	v_lshlrev_b32_e32 v138, 1, v134
	v_mov_b32_e32 v139, 0
	v_lshl_add_u64 v[130:131], v[130:131], 0, v[138:139]
	v_sub_u32_e32 v137, 7, v126
	v_and_b32_e32 v140, 8, v240
	v_cmp_ne_u32_e32 vcc, 0, v140
	s_nop 1
	v_cndmask_b32_e32 v137, v137, v126, vcc
	v_add_u32_e32 v140, s45, v137
	s_add_i32 s36, s18, -1
	s_add_i32 s36, s36, s45
	v_sub_u32_e32 v137, s36, v137
	v_cndmask_b32_e64 v137, v137, v140, s[6:7]
	v_lshlrev_b32_e32 v138, 11, v137
	v_lshl_add_u64 v[130:131], v[130:131], 0, v[138:139]
	v_mov_b32_e32 v132, 0x4000
	v_mov_b32_e32 v140, 0xffffc000
	v_cndmask_b32_e64 v132, v140, v132, s[6:7]
	v_cndmask_b32_e64 v133, -1, 0, s[6:7]
	s_mov_b32 s50, 0
	v_mov_b32_e32 v18, 0
	v_mov_b32_e32 v19, 0
	v_mov_b32_e32 v20, 0
	v_mov_b32_e32 v21, 0
	v_mov_b32_e32 v22, 0
	v_mov_b32_e32 v23, 0
	v_mov_b32_e32 v24, 0
	v_mov_b32_e32 v25, 0
	v_mov_b32_e32 v26, 0
	v_mov_b32_e32 v27, 0
	v_mov_b32_e32 v28, 0
	v_mov_b32_e32 v29, 0
	v_mov_b32_e32 v30, 0
	v_mov_b32_e32 v31, 0
	v_mov_b32_e32 v32, 0
	v_mov_b32_e32 v33, 0
	v_mov_b32_e32 v120, 0
	v_mov_b32_e32 v121, 0
	v_mov_b32_e32 v122, 0
	v_mov_b32_e32 v123, 0
.Lsc8_chunk:
	s_andn2_b64 vcc, exec, s[8:9]
	s_cbranch_vccnz .Lsc8_bar
	s_bitcmp1_b32 s50, 0
	s_cselect_b32 s36, 0xc800, 0
	v_add_u32_e32 v127, s36, v135
	v_add_u32_e32 v128, s36, v136
	s_addk_i32 s36, 0x600
	v_mov_b32_e32 v129, s36
	ds_read_b128 v[34:37], v127 offset:0
	ds_read_b128 v[38:41], v127 offset:16
	ds_read_b128 v[42:45], v127 offset:1024
	ds_read_b128 v[46:49], v127 offset:1040
	ds_read_b128 v[82:85], v127 offset:768
	ds_read_b128 v[86:89], v127 offset:784
	ds_read2_b32 v[90:91], v128 offset1:8
	ds_read_b128 v[66:69], v127 offset:256
	ds_read_b128 v[70:73], v127 offset:272
	s_waitcnt lgkmcnt(5)
	ds_read_b128 v[50:53], v127 offset:1600
	ds_read_b128 v[54:57], v127 offset:1616
	ds_read_b128 v[58:61], v127 offset:2624
	ds_read_b128 v[62:65], v127 offset:2640
	ds_read_b128 v[74:77], v127 offset:512
	ds_read_b128 v[78:81], v127 offset:528
	ds_read_b64 v[94:95], v129 offset:0
	v_pk_mul_f32 v[96:97], v[18:19], v[34:35]
	v_pk_mul_f32 v[98:99], v[18:19], v[42:43]
	v_pk_fma_f32 v[96:97], v[20:21], v[36:37], v[96:97]
	v_pk_fma_f32 v[98:99], v[20:21], v[44:45], v[98:99]
	v_pk_fma_f32 v[96:97], v[22:23], v[38:39], v[96:97]
	v_pk_fma_f32 v[98:99], v[22:23], v[46:47], v[98:99]
	v_pk_fma_f32 v[96:97], v[24:25], v[40:41], v[96:97]
	v_pk_fma_f32 v[98:99], v[24:25], v[48:49], v[98:99]
	v_pk_mul_f32 v[100:101], v[26:27], v[34:35]
	v_pk_mul_f32 v[102:103], v[26:27], v[42:43]
	v_pk_fma_f32 v[100:101], v[28:29], v[36:37], v[100:101]
	v_pk_fma_f32 v[102:103], v[28:29], v[44:45], v[102:103]
	v_pk_fma_f32 v[100:101], v[30:31], v[38:39], v[100:101]
	v_pk_fma_f32 v[102:103], v[30:31], v[46:47], v[102:103]
	v_pk_fma_f32 v[100:101], v[32:33], v[40:41], v[100:101]
	v_pk_fma_f32 v[102:103], v[32:33], v[48:49], v[102:103]
	v_add_f32_e32 v96, v96, v97
	v_add_f32_e32 v98, v98, v99
	v_add_f32_e32 v100, v100, v101
	v_add_f32_e32 v102, v102, v103
	s_waitcnt lgkmcnt(7)
	v_add_f32_dpp v96, v96, v96 quad_perm:[1,0,3,2] row_mask:0xf bank_mask:0xf bound_ctrl:1
	v_add_f32_dpp v98, v98, v98 quad_perm:[1,0,3,2] row_mask:0xf bank_mask:0xf bound_ctrl:1
	v_add_f32_dpp v100, v100, v100 quad_perm:[1,0,3,2] row_mask:0xf bank_mask:0xf bound_ctrl:1
	v_add_f32_dpp v102, v102, v102 quad_perm:[1,0,3,2] row_mask:0xf bank_mask:0xf bound_ctrl:1
	v_pk_mul_f32 v[104:105], v[82:83], v[90:91] op_sel_hi:[1,0]
	v_pk_mul_f32 v[106:107], v[84:85], v[90:91] op_sel_hi:[1,0]
	v_pk_mul_f32 v[108:109], v[86:87], v[90:91] op_sel_hi:[1,0]
	v_pk_mul_f32 v[110:111], v[88:89], v[90:91] op_sel_hi:[1,0]
	v_add_f32_dpp v96, v96, v96 quad_perm:[2,3,0,1] row_mask:0xf bank_mask:0xf bound_ctrl:1
	v_add_f32_dpp v98, v98, v98 quad_perm:[2,3,0,1] row_mask:0xf bank_mask:0xf bound_ctrl:1
	v_add_f32_dpp v100, v100, v100 quad_perm:[2,3,0,1] row_mask:0xf bank_mask:0xf bound_ctrl:1
	v_add_f32_dpp v102, v102, v102 quad_perm:[2,3,0,1] row_mask:0xf bank_mask:0xf bound_ctrl:1
	v_pk_mul_f32 v[112:113], v[82:83], v[90:91] op_sel:[0,1] op_sel_hi:[1,1]
	v_pk_mul_f32 v[114:115], v[84:85], v[90:91] op_sel:[0,1] op_sel_hi:[1,1]
	v_pk_mul_f32 v[116:117], v[86:87], v[90:91] op_sel:[0,1] op_sel_hi:[1,1]
	v_pk_mul_f32 v[118:119], v[88:89], v[90:91] op_sel:[0,1] op_sel_hi:[1,1]
	ds_read_b128 v[82:85], v127 offset:2368
	ds_read_b128 v[86:89], v127 offset:2384
	v_add_f32_dpp v96, v96, v96 row_half_mirror row_mask:0xf bank_mask:0xf bound_ctrl:1
	v_add_f32_dpp v98, v98, v98 row_half_mirror row_mask:0xf bank_mask:0xf bound_ctrl:1
	v_add_f32_dpp v100, v100, v100 row_half_mirror row_mask:0xf bank_mask:0xf bound_ctrl:1
	v_add_f32_dpp v102, v102, v102 row_half_mirror row_mask:0xf bank_mask:0xf bound_ctrl:1
	v_pk_fma_f32 v[104:105], v[18:19], v[66:67], v[104:105]
	v_pk_fma_f32 v[106:107], v[20:21], v[68:69], v[106:107]
	v_pk_fma_f32 v[108:109], v[22:23], v[70:71], v[108:109]
	v_pk_fma_f32 v[110:111], v[24:25], v[72:73], v[110:111]
	v_pk_fma_f32 v[112:113], v[26:27], v[66:67], v[112:113]
	v_pk_fma_f32 v[114:115], v[28:29], v[68:69], v[114:115]
	v_pk_fma_f32 v[116:117], v[30:31], v[70:71], v[116:117]
	v_pk_fma_f32 v[118:119], v[32:33], v[72:73], v[118:119]
	ds_read_b128 v[66:69], v127 offset:1856
	ds_read_b128 v[70:73], v127 offset:1872
	ds_read_b32 v92, v128 offset:1600
	ds_read_b32 v93, v128 offset:1632
	s_waitcnt lgkmcnt(6)
	v_pk_fma_f32 v[18:19], v[96:97], v[74:75], v[104:105] op_sel_hi:[0,1,1]
	v_pk_fma_f32 v[20:21], v[96:97], v[76:77], v[106:107] op_sel_hi:[0,1,1]
	v_pk_fma_f32 v[22:23], v[96:97], v[78:79], v[108:109] op_sel_hi:[0,1,1]
	v_pk_fma_f32 v[24:25], v[96:97], v[80:81], v[110:111] op_sel_hi:[0,1,1]
	v_pk_fma_f32 v[26:27], v[100:101], v[74:75], v[112:113] op_sel_hi:[0,1,1]
	v_pk_fma_f32 v[28:29], v[100:101], v[76:77], v[114:115] op_sel_hi:[0,1,1]
	v_pk_fma_f32 v[30:31], v[100:101], v[78:79], v[116:117] op_sel_hi:[0,1,1]
	v_pk_fma_f32 v[32:33], v[100:101], v[80:81], v[118:119] op_sel_hi:[0,1,1]
	v_fma_f32 v124, v90, v95, v98
	v_fma_f32 v125, v91, v95, v102
	v_fma_f32 v121, v96, v94, v124
	v_fma_f32 v123, v100, v94, v125
	v_mov_b32_dpp v121, v120 row_shr:1 row_mask:0xf bank_mask:0x3
	v_mov_b32_dpp v121, v120 row_shl:1 row_mask:0xf bank_mask:0xc
	v_mov_b32_dpp v123, v122 row_shr:1 row_mask:0xf bank_mask:0x3
	v_mov_b32_dpp v123, v122 row_shl:1 row_mask:0xf bank_mask:0xc
	ds_read_b128 v[34:37], v127 offset:3200
	ds_read_b128 v[38:41], v127 offset:3216
	ds_read_b128 v[42:45], v127 offset:4224
	ds_read_b128 v[46:49], v127 offset:4240
	ds_read_b128 v[74:77], v127 offset:2112
	ds_read_b128 v[78:81], v127 offset:2128
	ds_read_b64 v[94:95], v129 offset:1600
	v_pk_mul_f32 v[96:97], v[18:19], v[50:51]
	v_pk_mul_f32 v[98:99], v[18:19], v[58:59]
	v_pk_fma_f32 v[96:97], v[20:21], v[52:53], v[96:97]
	v_pk_fma_f32 v[98:99], v[20:21], v[60:61], v[98:99]
	v_pk_fma_f32 v[96:97], v[22:23], v[54:55], v[96:97]
	v_pk_fma_f32 v[98:99], v[22:23], v[62:63], v[98:99]
	v_pk_fma_f32 v[96:97], v[24:25], v[56:57], v[96:97]
	v_pk_fma_f32 v[98:99], v[24:25], v[64:65], v[98:99]
	v_pk_mul_f32 v[100:101], v[26:27], v[50:51]
	v_pk_mul_f32 v[102:103], v[26:27], v[58:59]
	v_pk_fma_f32 v[100:101], v[28:29], v[52:53], v[100:101]
	v_pk_fma_f32 v[102:103], v[28:29], v[60:61], v[102:103]
	v_pk_fma_f32 v[100:101], v[30:31], v[54:55], v[100:101]
	v_pk_fma_f32 v[102:103], v[30:31], v[62:63], v[102:103]
	v_pk_fma_f32 v[100:101], v[32:33], v[56:57], v[100:101]
	v_pk_fma_f32 v[102:103], v[32:33], v[64:65], v[102:103]
	v_add_f32_e32 v96, v96, v97
	v_add_f32_e32 v98, v98, v99
	v_add_f32_e32 v100, v100, v101
	v_add_f32_e32 v102, v102, v103
	s_waitcnt lgkmcnt(7)
	v_add_f32_dpp v96, v96, v96 quad_perm:[1,0,3,2] row_mask:0xf bank_mask:0xf bound_ctrl:1
	v_add_f32_dpp v98, v98, v98 quad_perm:[1,0,3,2] row_mask:0xf bank_mask:0xf bound_ctrl:1
	v_add_f32_dpp v100, v100, v100 quad_perm:[1,0,3,2] row_mask:0xf bank_mask:0xf bound_ctrl:1
	v_add_f32_dpp v102, v102, v102 quad_perm:[1,0,3,2] row_mask:0xf bank_mask:0xf bound_ctrl:1
	v_pk_mul_f32 v[104:105], v[82:83], v[92:93] op_sel_hi:[1,0]
	v_pk_mul_f32 v[106:107], v[84:85], v[92:93] op_sel_hi:[1,0]
	v_pk_mul_f32 v[108:109], v[86:87], v[92:93] op_sel_hi:[1,0]
	v_pk_mul_f32 v[110:111], v[88:89], v[92:93] op_sel_hi:[1,0]
	v_add_f32_dpp v96, v96, v96 quad_perm:[2,3,0,1] row_mask:0xf bank_mask:0xf bound_ctrl:1
	v_add_f32_dpp v98, v98, v98 quad_perm:[2,3,0,1] row_mask:0xf bank_mask:0xf bound_ctrl:1
	v_add_f32_dpp v100, v100, v100 quad_perm:[2,3,0,1] row_mask:0xf bank_mask:0xf bound_ctrl:1
	v_add_f32_dpp v102, v102, v102 quad_perm:[2,3,0,1] row_mask:0xf bank_mask:0xf bound_ctrl:1
	v_pk_mul_f32 v[112:113], v[82:83], v[92:93] op_sel:[0,1] op_sel_hi:[1,1]
	v_pk_mul_f32 v[114:115], v[84:85], v[92:93] op_sel:[0,1] op_sel_hi:[1,1]
	v_pk_mul_f32 v[116:117], v[86:87], v[92:93] op_sel:[0,1] op_sel_hi:[1,1]
	v_pk_mul_f32 v[118:119], v[88:89], v[92:93] op_sel:[0,1] op_sel_hi:[1,1]
	ds_read_b128 v[82:85], v127 offset:3968
	ds_read_b128 v[86:89], v127 offset:3984
	v_add_f32_dpp v96, v96, v96 row_half_mirror row_mask:0xf bank_mask:0xf bound_ctrl:1
	v_add_f32_dpp v98, v98, v98 row_half_mirror row_mask:0xf bank_mask:0xf bound_ctrl:1
	v_add_f32_dpp v100, v100, v100 row_half_mirror row_mask:0xf bank_mask:0xf bound_ctrl:1
	v_add_f32_dpp v102, v102, v102 row_half_mirror row_mask:0xf bank_mask:0xf bound_ctrl:1
	v_pk_fma_f32 v[104:105], v[18:19], v[66:67], v[104:105]
	v_pk_fma_f32 v[106:107], v[20:21], v[68:69], v[106:107]
	v_pk_fma_f32 v[108:109], v[22:23], v[70:71], v[108:109]
	v_pk_fma_f32 v[110:111], v[24:25], v[72:73], v[110:111]
	v_pk_fma_f32 v[112:113], v[26:27], v[66:67], v[112:113]
	v_pk_fma_f32 v[114:115], v[28:29], v[68:69], v[114:115]
	v_pk_fma_f32 v[116:117], v[30:31], v[70:71], v[116:117]
	v_pk_fma_f32 v[118:119], v[32:33], v[72:73], v[118:119]
	ds_read_b128 v[66:69], v127 offset:3456
	ds_read_b128 v[70:73], v127 offset:3472
	ds_read_b32 v90, v128 offset:3200
	ds_read_b32 v91, v128 offset:3232
	s_waitcnt lgkmcnt(6)
	v_pk_fma_f32 v[18:19], v[96:97], v[74:75], v[104:105] op_sel_hi:[0,1,1]
	v_pk_fma_f32 v[20:21], v[96:97], v[76:77], v[106:107] op_sel_hi:[0,1,1]
	v_pk_fma_f32 v[22:23], v[96:97], v[78:79], v[108:109] op_sel_hi:[0,1,1]
	v_pk_fma_f32 v[24:25], v[96:97], v[80:81], v[110:111] op_sel_hi:[0,1,1]
	v_pk_fma_f32 v[26:27], v[100:101], v[74:75], v[112:113] op_sel_hi:[0,1,1]
	v_pk_fma_f32 v[28:29], v[100:101], v[76:77], v[114:115] op_sel_hi:[0,1,1]
	v_pk_fma_f32 v[30:31], v[100:101], v[78:79], v[116:117] op_sel_hi:[0,1,1]
	v_pk_fma_f32 v[32:33], v[100:101], v[80:81], v[118:119] op_sel_hi:[0,1,1]
	v_fma_f32 v124, v92, v95, v98
	v_fma_f32 v125, v93, v95, v102
	v_fma_f32 v120, v96, v94, v124
	v_fma_f32 v122, v100, v94, v125
	v_mov_b32_dpp v120, v121 row_shr:1 row_mask:0xf bank_mask:0x3
	v_mov_b32_dpp v120, v121 row_shl:1 row_mask:0xf bank_mask:0xc
	v_mov_b32_dpp v122, v123 row_shr:1 row_mask:0xf bank_mask:0x3
	v_mov_b32_dpp v122, v123 row_shl:1 row_mask:0xf bank_mask:0xc
	ds_read_b128 v[50:53], v127 offset:4800
	ds_read_b128 v[54:57], v127 offset:4816
	ds_read_b128 v[58:61], v127 offset:5824
	ds_read_b128 v[62:65], v127 offset:5840
	ds_read_b128 v[74:77], v127 offset:3712
	ds_read_b128 v[78:81], v127 offset:3728
	ds_read_b64 v[94:95], v129 offset:3200
	v_pk_mul_f32 v[96:97], v[18:19], v[34:35]
	v_pk_mul_f32 v[98:99], v[18:19], v[42:43]
	v_pk_fma_f32 v[96:97], v[20:21], v[36:37], v[96:97]
	v_pk_fma_f32 v[98:99], v[20:21], v[44:45], v[98:99]
	v_pk_fma_f32 v[96:97], v[22:23], v[38:39], v[96:97]
	v_pk_fma_f32 v[98:99], v[22:23], v[46:47], v[98:99]
	v_pk_fma_f32 v[96:97], v[24:25], v[40:41], v[96:97]
	v_pk_fma_f32 v[98:99], v[24:25], v[48:49], v[98:99]
	v_pk_mul_f32 v[100:101], v[26:27], v[34:35]
	v_pk_mul_f32 v[102:103], v[26:27], v[42:43]
	v_pk_fma_f32 v[100:101], v[28:29], v[36:37], v[100:101]
	v_pk_fma_f32 v[102:103], v[28:29], v[44:45], v[102:103]
	v_pk_fma_f32 v[100:101], v[30:31], v[38:39], v[100:101]
	v_pk_fma_f32 v[102:103], v[30:31], v[46:47], v[102:103]
	v_pk_fma_f32 v[100:101], v[32:33], v[40:41], v[100:101]
	v_pk_fma_f32 v[102:103], v[32:33], v[48:49], v[102:103]
	v_add_f32_e32 v96, v96, v97
	v_add_f32_e32 v98, v98, v99
	v_add_f32_e32 v100, v100, v101
	v_add_f32_e32 v102, v102, v103
	s_waitcnt lgkmcnt(7)
	v_add_f32_dpp v96, v96, v96 quad_perm:[1,0,3,2] row_mask:0xf bank_mask:0xf bound_ctrl:1
	v_add_f32_dpp v98, v98, v98 quad_perm:[1,0,3,2] row_mask:0xf bank_mask:0xf bound_ctrl:1
	v_add_f32_dpp v100, v100, v100 quad_perm:[1,0,3,2] row_mask:0xf bank_mask:0xf bound_ctrl:1
	v_add_f32_dpp v102, v102, v102 quad_perm:[1,0,3,2] row_mask:0xf bank_mask:0xf bound_ctrl:1
	v_pk_mul_f32 v[104:105], v[82:83], v[90:91] op_sel_hi:[1,0]
	v_pk_mul_f32 v[106:107], v[84:85], v[90:91] op_sel_hi:[1,0]
	v_pk_mul_f32 v[108:109], v[86:87], v[90:91] op_sel_hi:[1,0]
	v_pk_mul_f32 v[110:111], v[88:89], v[90:91] op_sel_hi:[1,0]
	v_add_f32_dpp v96, v96, v96 quad_perm:[2,3,0,1] row_mask:0xf bank_mask:0xf bound_ctrl:1
	v_add_f32_dpp v98, v98, v98 quad_perm:[2,3,0,1] row_mask:0xf bank_mask:0xf bound_ctrl:1
	v_add_f32_dpp v100, v100, v100 quad_perm:[2,3,0,1] row_mask:0xf bank_mask:0xf bound_ctrl:1
	v_add_f32_dpp v102, v102, v102 quad_perm:[2,3,0,1] row_mask:0xf bank_mask:0xf bound_ctrl:1
	v_pk_mul_f32 v[112:113], v[82:83], v[90:91] op_sel:[0,1] op_sel_hi:[1,1]
	v_pk_mul_f32 v[114:115], v[84:85], v[90:91] op_sel:[0,1] op_sel_hi:[1,1]
	v_pk_mul_f32 v[116:117], v[86:87], v[90:91] op_sel:[0,1] op_sel_hi:[1,1]
	v_pk_mul_f32 v[118:119], v[88:89], v[90:91] op_sel:[0,1] op_sel_hi:[1,1]
	ds_read_b128 v[82:85], v127 offset:5568
	ds_read_b128 v[86:89], v127 offset:5584
	v_add_f32_dpp v96, v96, v96 row_half_mirror row_mask:0xf bank_mask:0xf bound_ctrl:1
	v_add_f32_dpp v98, v98, v98 row_half_mirror row_mask:0xf bank_mask:0xf bound_ctrl:1
	v_add_f32_dpp v100, v100, v100 row_half_mirror row_mask:0xf bank_mask:0xf bound_ctrl:1
	v_add_f32_dpp v102, v102, v102 row_half_mirror row_mask:0xf bank_mask:0xf bound_ctrl:1
	v_pk_fma_f32 v[104:105], v[18:19], v[66:67], v[104:105]
	v_pk_fma_f32 v[106:107], v[20:21], v[68:69], v[106:107]
	v_pk_fma_f32 v[108:109], v[22:23], v[70:71], v[108:109]
	v_pk_fma_f32 v[110:111], v[24:25], v[72:73], v[110:111]
	v_pk_fma_f32 v[112:113], v[26:27], v[66:67], v[112:113]
	v_pk_fma_f32 v[114:115], v[28:29], v[68:69], v[114:115]
	v_pk_fma_f32 v[116:117], v[30:31], v[70:71], v[116:117]
	v_pk_fma_f32 v[118:119], v[32:33], v[72:73], v[118:119]
	ds_read_b128 v[66:69], v127 offset:5056
	ds_read_b128 v[70:73], v127 offset:5072
	ds_read_b32 v92, v128 offset:4800
	ds_read_b32 v93, v128 offset:4832
	s_waitcnt lgkmcnt(6)
	v_pk_fma_f32 v[18:19], v[96:97], v[74:75], v[104:105] op_sel_hi:[0,1,1]
	v_pk_fma_f32 v[20:21], v[96:97], v[76:77], v[106:107] op_sel_hi:[0,1,1]
	v_pk_fma_f32 v[22:23], v[96:97], v[78:79], v[108:109] op_sel_hi:[0,1,1]
	v_pk_fma_f32 v[24:25], v[96:97], v[80:81], v[110:111] op_sel_hi:[0,1,1]
	v_pk_fma_f32 v[26:27], v[100:101], v[74:75], v[112:113] op_sel_hi:[0,1,1]
	v_pk_fma_f32 v[28:29], v[100:101], v[76:77], v[114:115] op_sel_hi:[0,1,1]
	v_pk_fma_f32 v[30:31], v[100:101], v[78:79], v[116:117] op_sel_hi:[0,1,1]
	v_pk_fma_f32 v[32:33], v[100:101], v[80:81], v[118:119] op_sel_hi:[0,1,1]
	v_fma_f32 v124, v90, v95, v98
	v_fma_f32 v125, v91, v95, v102
	v_fma_f32 v121, v96, v94, v124
	v_fma_f32 v123, v100, v94, v125
	v_mov_b32_dpp v121, v120 row_shr:1 row_mask:0xf bank_mask:0x3
	v_mov_b32_dpp v121, v120 row_shl:1 row_mask:0xf bank_mask:0xc
	v_mov_b32_dpp v123, v122 row_shr:1 row_mask:0xf bank_mask:0x3
	v_mov_b32_dpp v123, v122 row_shl:1 row_mask:0xf bank_mask:0xc
	ds_read_b128 v[34:37], v127 offset:6400
	ds_read_b128 v[38:41], v127 offset:6416
	ds_read_b128 v[42:45], v127 offset:7424
	ds_read_b128 v[46:49], v127 offset:7440
	ds_read_b128 v[74:77], v127 offset:5312
	ds_read_b128 v[78:81], v127 offset:5328
	ds_read_b64 v[94:95], v129 offset:4800
	v_pk_mul_f32 v[96:97], v[18:19], v[50:51]
	v_pk_mul_f32 v[98:99], v[18:19], v[58:59]
	v_pk_fma_f32 v[96:97], v[20:21], v[52:53], v[96:97]
	v_pk_fma_f32 v[98:99], v[20:21], v[60:61], v[98:99]
	v_pk_fma_f32 v[96:97], v[22:23], v[54:55], v[96:97]
	v_pk_fma_f32 v[98:99], v[22:23], v[62:63], v[98:99]
	v_pk_fma_f32 v[96:97], v[24:25], v[56:57], v[96:97]
	v_pk_fma_f32 v[98:99], v[24:25], v[64:65], v[98:99]
	v_pk_mul_f32 v[100:101], v[26:27], v[50:51]
	v_pk_mul_f32 v[102:103], v[26:27], v[58:59]
	v_pk_fma_f32 v[100:101], v[28:29], v[52:53], v[100:101]
	v_pk_fma_f32 v[102:103], v[28:29], v[60:61], v[102:103]
	v_pk_fma_f32 v[100:101], v[30:31], v[54:55], v[100:101]
	v_pk_fma_f32 v[102:103], v[30:31], v[62:63], v[102:103]
	v_pk_fma_f32 v[100:101], v[32:33], v[56:57], v[100:101]
	v_pk_fma_f32 v[102:103], v[32:33], v[64:65], v[102:103]
	v_add_f32_e32 v96, v96, v97
	v_add_f32_e32 v98, v98, v99
	v_add_f32_e32 v100, v100, v101
	v_add_f32_e32 v102, v102, v103
	s_waitcnt lgkmcnt(7)
	v_add_f32_dpp v96, v96, v96 quad_perm:[1,0,3,2] row_mask:0xf bank_mask:0xf bound_ctrl:1
	v_add_f32_dpp v98, v98, v98 quad_perm:[1,0,3,2] row_mask:0xf bank_mask:0xf bound_ctrl:1
	v_add_f32_dpp v100, v100, v100 quad_perm:[1,0,3,2] row_mask:0xf bank_mask:0xf bound_ctrl:1
	v_add_f32_dpp v102, v102, v102 quad_perm:[1,0,3,2] row_mask:0xf bank_mask:0xf bound_ctrl:1
	v_pk_mul_f32 v[104:105], v[82:83], v[92:93] op_sel_hi:[1,0]
	v_pk_mul_f32 v[106:107], v[84:85], v[92:93] op_sel_hi:[1,0]
	v_pk_mul_f32 v[108:109], v[86:87], v[92:93] op_sel_hi:[1,0]
	v_pk_mul_f32 v[110:111], v[88:89], v[92:93] op_sel_hi:[1,0]
	v_add_f32_dpp v96, v96, v96 quad_perm:[2,3,0,1] row_mask:0xf bank_mask:0xf bound_ctrl:1
	v_add_f32_dpp v98, v98, v98 quad_perm:[2,3,0,1] row_mask:0xf bank_mask:0xf bound_ctrl:1
	v_add_f32_dpp v100, v100, v100 quad_perm:[2,3,0,1] row_mask:0xf bank_mask:0xf bound_ctrl:1
	v_add_f32_dpp v102, v102, v102 quad_perm:[2,3,0,1] row_mask:0xf bank_mask:0xf bound_ctrl:1
	v_pk_mul_f32 v[112:113], v[82:83], v[92:93] op_sel:[0,1] op_sel_hi:[1,1]
	v_pk_mul_f32 v[114:115], v[84:85], v[92:93] op_sel:[0,1] op_sel_hi:[1,1]
	v_pk_mul_f32 v[116:117], v[86:87], v[92:93] op_sel:[0,1] op_sel_hi:[1,1]
	v_pk_mul_f32 v[118:119], v[88:89], v[92:93] op_sel:[0,1] op_sel_hi:[1,1]
	ds_read_b128 v[82:85], v127 offset:7168
	ds_read_b128 v[86:89], v127 offset:7184
	v_add_f32_dpp v96, v96, v96 row_half_mirror row_mask:0xf bank_mask:0xf bound_ctrl:1
	v_add_f32_dpp v98, v98, v98 row_half_mirror row_mask:0xf bank_mask:0xf bound_ctrl:1
	v_add_f32_dpp v100, v100, v100 row_half_mirror row_mask:0xf bank_mask:0xf bound_ctrl:1
	v_add_f32_dpp v102, v102, v102 row_half_mirror row_mask:0xf bank_mask:0xf bound_ctrl:1
	v_pk_fma_f32 v[104:105], v[18:19], v[66:67], v[104:105]
	v_pk_fma_f32 v[106:107], v[20:21], v[68:69], v[106:107]
	v_pk_fma_f32 v[108:109], v[22:23], v[70:71], v[108:109]
	v_pk_fma_f32 v[110:111], v[24:25], v[72:73], v[110:111]
	v_pk_fma_f32 v[112:113], v[26:27], v[66:67], v[112:113]
	v_pk_fma_f32 v[114:115], v[28:29], v[68:69], v[114:115]
	v_pk_fma_f32 v[116:117], v[30:31], v[70:71], v[116:117]
	v_pk_fma_f32 v[118:119], v[32:33], v[72:73], v[118:119]
	ds_read_b128 v[66:69], v127 offset:6656
	ds_read_b128 v[70:73], v127 offset:6672
	ds_read_b32 v90, v128 offset:6400
	ds_read_b32 v91, v128 offset:6432
	s_waitcnt lgkmcnt(6)
	v_pk_fma_f32 v[18:19], v[96:97], v[74:75], v[104:105] op_sel_hi:[0,1,1]
	v_pk_fma_f32 v[20:21], v[96:97], v[76:77], v[106:107] op_sel_hi:[0,1,1]
	v_pk_fma_f32 v[22:23], v[96:97], v[78:79], v[108:109] op_sel_hi:[0,1,1]
	v_pk_fma_f32 v[24:25], v[96:97], v[80:81], v[110:111] op_sel_hi:[0,1,1]
	v_pk_fma_f32 v[26:27], v[100:101], v[74:75], v[112:113] op_sel_hi:[0,1,1]
	v_pk_fma_f32 v[28:29], v[100:101], v[76:77], v[114:115] op_sel_hi:[0,1,1]
	v_pk_fma_f32 v[30:31], v[100:101], v[78:79], v[116:117] op_sel_hi:[0,1,1]
	v_pk_fma_f32 v[32:33], v[100:101], v[80:81], v[118:119] op_sel_hi:[0,1,1]
	v_fma_f32 v124, v92, v95, v98
	v_fma_f32 v125, v93, v95, v102
	v_fma_f32 v120, v96, v94, v124
	v_fma_f32 v122, v100, v94, v125
	v_mov_b32_dpp v120, v121 row_shr:1 row_mask:0xf bank_mask:0x3
	v_mov_b32_dpp v120, v121 row_shl:1 row_mask:0xf bank_mask:0xc
	v_mov_b32_dpp v122, v123 row_shr:1 row_mask:0xf bank_mask:0x3
	v_mov_b32_dpp v122, v123 row_shl:1 row_mask:0xf bank_mask:0xc
	ds_read_b128 v[50:53], v127 offset:8000
	ds_read_b128 v[54:57], v127 offset:8016
	ds_read_b128 v[58:61], v127 offset:9024
	ds_read_b128 v[62:65], v127 offset:9040
	ds_read_b128 v[74:77], v127 offset:6912
	ds_read_b128 v[78:81], v127 offset:6928
	ds_read_b64 v[94:95], v129 offset:6400
	v_pk_mul_f32 v[96:97], v[18:19], v[34:35]
	v_pk_mul_f32 v[98:99], v[18:19], v[42:43]
	v_pk_fma_f32 v[96:97], v[20:21], v[36:37], v[96:97]
	v_pk_fma_f32 v[98:99], v[20:21], v[44:45], v[98:99]
	v_pk_fma_f32 v[96:97], v[22:23], v[38:39], v[96:97]
	v_pk_fma_f32 v[98:99], v[22:23], v[46:47], v[98:99]
	v_pk_fma_f32 v[96:97], v[24:25], v[40:41], v[96:97]
	v_pk_fma_f32 v[98:99], v[24:25], v[48:49], v[98:99]
	v_pk_mul_f32 v[100:101], v[26:27], v[34:35]
	v_pk_mul_f32 v[102:103], v[26:27], v[42:43]
	v_pk_fma_f32 v[100:101], v[28:29], v[36:37], v[100:101]
	v_pk_fma_f32 v[102:103], v[28:29], v[44:45], v[102:103]
	v_pk_fma_f32 v[100:101], v[30:31], v[38:39], v[100:101]
	v_pk_fma_f32 v[102:103], v[30:31], v[46:47], v[102:103]
	v_pk_fma_f32 v[100:101], v[32:33], v[40:41], v[100:101]
	v_pk_fma_f32 v[102:103], v[32:33], v[48:49], v[102:103]
	v_add_f32_e32 v96, v96, v97
	v_add_f32_e32 v98, v98, v99
	v_add_f32_e32 v100, v100, v101
	v_add_f32_e32 v102, v102, v103
	s_waitcnt lgkmcnt(7)
	v_add_f32_dpp v96, v96, v96 quad_perm:[1,0,3,2] row_mask:0xf bank_mask:0xf bound_ctrl:1
	v_add_f32_dpp v98, v98, v98 quad_perm:[1,0,3,2] row_mask:0xf bank_mask:0xf bound_ctrl:1
	v_add_f32_dpp v100, v100, v100 quad_perm:[1,0,3,2] row_mask:0xf bank_mask:0xf bound_ctrl:1
	v_add_f32_dpp v102, v102, v102 quad_perm:[1,0,3,2] row_mask:0xf bank_mask:0xf bound_ctrl:1
	v_pk_mul_f32 v[104:105], v[82:83], v[90:91] op_sel_hi:[1,0]
	v_pk_mul_f32 v[106:107], v[84:85], v[90:91] op_sel_hi:[1,0]
	v_pk_mul_f32 v[108:109], v[86:87], v[90:91] op_sel_hi:[1,0]
	v_pk_mul_f32 v[110:111], v[88:89], v[90:91] op_sel_hi:[1,0]
	v_add_f32_dpp v96, v96, v96 quad_perm:[2,3,0,1] row_mask:0xf bank_mask:0xf bound_ctrl:1
	v_add_f32_dpp v98, v98, v98 quad_perm:[2,3,0,1] row_mask:0xf bank_mask:0xf bound_ctrl:1
	v_add_f32_dpp v100, v100, v100 quad_perm:[2,3,0,1] row_mask:0xf bank_mask:0xf bound_ctrl:1
	v_add_f32_dpp v102, v102, v102 quad_perm:[2,3,0,1] row_mask:0xf bank_mask:0xf bound_ctrl:1
	v_pk_mul_f32 v[112:113], v[82:83], v[90:91] op_sel:[0,1] op_sel_hi:[1,1]
	v_pk_mul_f32 v[114:115], v[84:85], v[90:91] op_sel:[0,1] op_sel_hi:[1,1]
	v_pk_mul_f32 v[116:117], v[86:87], v[90:91] op_sel:[0,1] op_sel_hi:[1,1]
	v_pk_mul_f32 v[118:119], v[88:89], v[90:91] op_sel:[0,1] op_sel_hi:[1,1]
	ds_read_b128 v[82:85], v127 offset:8768
	ds_read_b128 v[86:89], v127 offset:8784
	v_add_f32_dpp v96, v96, v96 row_half_mirror row_mask:0xf bank_mask:0xf bound_ctrl:1
	v_add_f32_dpp v98, v98, v98 row_half_mirror row_mask:0xf bank_mask:0xf bound_ctrl:1
	v_add_f32_dpp v100, v100, v100 row_half_mirror row_mask:0xf bank_mask:0xf bound_ctrl:1
	v_add_f32_dpp v102, v102, v102 row_half_mirror row_mask:0xf bank_mask:0xf bound_ctrl:1
	v_pk_fma_f32 v[104:105], v[18:19], v[66:67], v[104:105]
	v_pk_fma_f32 v[106:107], v[20:21], v[68:69], v[106:107]
	v_pk_fma_f32 v[108:109], v[22:23], v[70:71], v[108:109]
	v_pk_fma_f32 v[110:111], v[24:25], v[72:73], v[110:111]
	v_pk_fma_f32 v[112:113], v[26:27], v[66:67], v[112:113]
	v_pk_fma_f32 v[114:115], v[28:29], v[68:69], v[114:115]
	v_pk_fma_f32 v[116:117], v[30:31], v[70:71], v[116:117]
	v_pk_fma_f32 v[118:119], v[32:33], v[72:73], v[118:119]
	ds_read_b128 v[66:69], v127 offset:8256
	ds_read_b128 v[70:73], v127 offset:8272
	ds_read_b32 v92, v128 offset:8000
	ds_read_b32 v93, v128 offset:8032
	s_waitcnt lgkmcnt(6)
	v_pk_fma_f32 v[18:19], v[96:97], v[74:75], v[104:105] op_sel_hi:[0,1,1]
	v_pk_fma_f32 v[20:21], v[96:97], v[76:77], v[106:107] op_sel_hi:[0,1,1]
	v_pk_fma_f32 v[22:23], v[96:97], v[78:79], v[108:109] op_sel_hi:[0,1,1]
	v_pk_fma_f32 v[24:25], v[96:97], v[80:81], v[110:111] op_sel_hi:[0,1,1]
	v_pk_fma_f32 v[26:27], v[100:101], v[74:75], v[112:113] op_sel_hi:[0,1,1]
	v_pk_fma_f32 v[28:29], v[100:101], v[76:77], v[114:115] op_sel_hi:[0,1,1]
	v_pk_fma_f32 v[30:31], v[100:101], v[78:79], v[116:117] op_sel_hi:[0,1,1]
	v_pk_fma_f32 v[32:33], v[100:101], v[80:81], v[118:119] op_sel_hi:[0,1,1]
	v_fma_f32 v124, v90, v95, v98
	v_fma_f32 v125, v91, v95, v102
	v_fma_f32 v121, v96, v94, v124
	v_fma_f32 v123, v100, v94, v125
	v_mov_b32_dpp v121, v120 row_shr:1 row_mask:0xf bank_mask:0x3
	v_mov_b32_dpp v121, v120 row_shl:1 row_mask:0xf bank_mask:0xc
	v_mov_b32_dpp v123, v122 row_shr:1 row_mask:0xf bank_mask:0x3
	v_mov_b32_dpp v123, v122 row_shl:1 row_mask:0xf bank_mask:0xc
	ds_read_b128 v[34:37], v127 offset:9600
	ds_read_b128 v[38:41], v127 offset:9616
	ds_read_b128 v[42:45], v127 offset:10624
	ds_read_b128 v[46:49], v127 offset:10640
	ds_read_b128 v[74:77], v127 offset:8512
	ds_read_b128 v[78:81], v127 offset:8528
	ds_read_b64 v[94:95], v129 offset:8000
	v_pk_mul_f32 v[96:97], v[18:19], v[50:51]
	v_pk_mul_f32 v[98:99], v[18:19], v[58:59]
	v_pk_fma_f32 v[96:97], v[20:21], v[52:53], v[96:97]
	v_pk_fma_f32 v[98:99], v[20:21], v[60:61], v[98:99]
	v_pk_fma_f32 v[96:97], v[22:23], v[54:55], v[96:97]
	v_pk_fma_f32 v[98:99], v[22:23], v[62:63], v[98:99]
	v_pk_fma_f32 v[96:97], v[24:25], v[56:57], v[96:97]
	v_pk_fma_f32 v[98:99], v[24:25], v[64:65], v[98:99]
	v_pk_mul_f32 v[100:101], v[26:27], v[50:51]
	v_pk_mul_f32 v[102:103], v[26:27], v[58:59]
	v_pk_fma_f32 v[100:101], v[28:29], v[52:53], v[100:101]
	v_pk_fma_f32 v[102:103], v[28:29], v[60:61], v[102:103]
	v_pk_fma_f32 v[100:101], v[30:31], v[54:55], v[100:101]
	v_pk_fma_f32 v[102:103], v[30:31], v[62:63], v[102:103]
	v_pk_fma_f32 v[100:101], v[32:33], v[56:57], v[100:101]
	v_pk_fma_f32 v[102:103], v[32:33], v[64:65], v[102:103]
	v_add_f32_e32 v96, v96, v97
	v_add_f32_e32 v98, v98, v99
	v_add_f32_e32 v100, v100, v101
	v_add_f32_e32 v102, v102, v103
	s_waitcnt lgkmcnt(7)
	v_add_f32_dpp v96, v96, v96 quad_perm:[1,0,3,2] row_mask:0xf bank_mask:0xf bound_ctrl:1
	v_add_f32_dpp v98, v98, v98 quad_perm:[1,0,3,2] row_mask:0xf bank_mask:0xf bound_ctrl:1
	v_add_f32_dpp v100, v100, v100 quad_perm:[1,0,3,2] row_mask:0xf bank_mask:0xf bound_ctrl:1
	v_add_f32_dpp v102, v102, v102 quad_perm:[1,0,3,2] row_mask:0xf bank_mask:0xf bound_ctrl:1
	v_pk_mul_f32 v[104:105], v[82:83], v[92:93] op_sel_hi:[1,0]
	v_pk_mul_f32 v[106:107], v[84:85], v[92:93] op_sel_hi:[1,0]
	v_pk_mul_f32 v[108:109], v[86:87], v[92:93] op_sel_hi:[1,0]
	v_pk_mul_f32 v[110:111], v[88:89], v[92:93] op_sel_hi:[1,0]
	v_add_f32_dpp v96, v96, v96 quad_perm:[2,3,0,1] row_mask:0xf bank_mask:0xf bound_ctrl:1
	v_add_f32_dpp v98, v98, v98 quad_perm:[2,3,0,1] row_mask:0xf bank_mask:0xf bound_ctrl:1
	v_add_f32_dpp v100, v100, v100 quad_perm:[2,3,0,1] row_mask:0xf bank_mask:0xf bound_ctrl:1
	v_add_f32_dpp v102, v102, v102 quad_perm:[2,3,0,1] row_mask:0xf bank_mask:0xf bound_ctrl:1
	v_pk_mul_f32 v[112:113], v[82:83], v[92:93] op_sel:[0,1] op_sel_hi:[1,1]
	v_pk_mul_f32 v[114:115], v[84:85], v[92:93] op_sel:[0,1] op_sel_hi:[1,1]
	v_pk_mul_f32 v[116:117], v[86:87], v[92:93] op_sel:[0,1] op_sel_hi:[1,1]
	v_pk_mul_f32 v[118:119], v[88:89], v[92:93] op_sel:[0,1] op_sel_hi:[1,1]
	ds_read_b128 v[82:85], v127 offset:10368
	ds_read_b128 v[86:89], v127 offset:10384
	v_add_f32_dpp v96, v96, v96 row_half_mirror row_mask:0xf bank_mask:0xf bound_ctrl:1
	v_add_f32_dpp v98, v98, v98 row_half_mirror row_mask:0xf bank_mask:0xf bound_ctrl:1
	v_add_f32_dpp v100, v100, v100 row_half_mirror row_mask:0xf bank_mask:0xf bound_ctrl:1
	v_add_f32_dpp v102, v102, v102 row_half_mirror row_mask:0xf bank_mask:0xf bound_ctrl:1
	v_pk_fma_f32 v[104:105], v[18:19], v[66:67], v[104:105]
	v_pk_fma_f32 v[106:107], v[20:21], v[68:69], v[106:107]
	v_pk_fma_f32 v[108:109], v[22:23], v[70:71], v[108:109]
	v_pk_fma_f32 v[110:111], v[24:25], v[72:73], v[110:111]
	v_pk_fma_f32 v[112:113], v[26:27], v[66:67], v[112:113]
	v_pk_fma_f32 v[114:115], v[28:29], v[68:69], v[114:115]
	v_pk_fma_f32 v[116:117], v[30:31], v[70:71], v[116:117]
	v_pk_fma_f32 v[118:119], v[32:33], v[72:73], v[118:119]
	ds_read_b128 v[66:69], v127 offset:9856
	ds_read_b128 v[70:73], v127 offset:9872
	ds_read_b32 v90, v128 offset:9600
	ds_read_b32 v91, v128 offset:9632
	s_waitcnt lgkmcnt(6)
	v_pk_fma_f32 v[18:19], v[96:97], v[74:75], v[104:105] op_sel_hi:[0,1,1]
	v_pk_fma_f32 v[20:21], v[96:97], v[76:77], v[106:107] op_sel_hi:[0,1,1]
	v_pk_fma_f32 v[22:23], v[96:97], v[78:79], v[108:109] op_sel_hi:[0,1,1]
	v_pk_fma_f32 v[24:25], v[96:97], v[80:81], v[110:111] op_sel_hi:[0,1,1]
	v_pk_fma_f32 v[26:27], v[100:101], v[74:75], v[112:113] op_sel_hi:[0,1,1]
	v_pk_fma_f32 v[28:29], v[100:101], v[76:77], v[114:115] op_sel_hi:[0,1,1]
	v_pk_fma_f32 v[30:31], v[100:101], v[78:79], v[116:117] op_sel_hi:[0,1,1]
	v_pk_fma_f32 v[32:33], v[100:101], v[80:81], v[118:119] op_sel_hi:[0,1,1]
	v_fma_f32 v124, v92, v95, v98
	v_fma_f32 v125, v93, v95, v102
	v_fma_f32 v120, v96, v94, v124
	v_fma_f32 v122, v100, v94, v125
	v_mov_b32_dpp v120, v121 row_shr:1 row_mask:0xf bank_mask:0x3
	v_mov_b32_dpp v120, v121 row_shl:1 row_mask:0xf bank_mask:0xc
	v_mov_b32_dpp v122, v123 row_shr:1 row_mask:0xf bank_mask:0x3
	v_mov_b32_dpp v122, v123 row_shl:1 row_mask:0xf bank_mask:0xc
	ds_read_b128 v[50:53], v127 offset:11200
	ds_read_b128 v[54:57], v127 offset:11216
	ds_read_b128 v[58:61], v127 offset:12224
	ds_read_b128 v[62:65], v127 offset:12240
	ds_read_b128 v[74:77], v127 offset:10112
	ds_read_b128 v[78:81], v127 offset:10128
	ds_read_b64 v[94:95], v129 offset:9600
	v_pk_mul_f32 v[96:97], v[18:19], v[34:35]
	v_pk_mul_f32 v[98:99], v[18:19], v[42:43]
	v_pk_fma_f32 v[96:97], v[20:21], v[36:37], v[96:97]
	v_pk_fma_f32 v[98:99], v[20:21], v[44:45], v[98:99]
	v_pk_fma_f32 v[96:97], v[22:23], v[38:39], v[96:97]
	v_pk_fma_f32 v[98:99], v[22:23], v[46:47], v[98:99]
	v_pk_fma_f32 v[96:97], v[24:25], v[40:41], v[96:97]
	v_pk_fma_f32 v[98:99], v[24:25], v[48:49], v[98:99]
	v_pk_mul_f32 v[100:101], v[26:27], v[34:35]
	v_pk_mul_f32 v[102:103], v[26:27], v[42:43]
	v_pk_fma_f32 v[100:101], v[28:29], v[36:37], v[100:101]
	v_pk_fma_f32 v[102:103], v[28:29], v[44:45], v[102:103]
	v_pk_fma_f32 v[100:101], v[30:31], v[38:39], v[100:101]
	v_pk_fma_f32 v[102:103], v[30:31], v[46:47], v[102:103]
	v_pk_fma_f32 v[100:101], v[32:33], v[40:41], v[100:101]
	v_pk_fma_f32 v[102:103], v[32:33], v[48:49], v[102:103]
	v_add_f32_e32 v96, v96, v97
	v_add_f32_e32 v98, v98, v99
	v_add_f32_e32 v100, v100, v101
	v_add_f32_e32 v102, v102, v103
	s_waitcnt lgkmcnt(7)
	v_add_f32_dpp v96, v96, v96 quad_perm:[1,0,3,2] row_mask:0xf bank_mask:0xf bound_ctrl:1
	v_add_f32_dpp v98, v98, v98 quad_perm:[1,0,3,2] row_mask:0xf bank_mask:0xf bound_ctrl:1
	v_add_f32_dpp v100, v100, v100 quad_perm:[1,0,3,2] row_mask:0xf bank_mask:0xf bound_ctrl:1
	v_add_f32_dpp v102, v102, v102 quad_perm:[1,0,3,2] row_mask:0xf bank_mask:0xf bound_ctrl:1
	v_pk_mul_f32 v[104:105], v[82:83], v[90:91] op_sel_hi:[1,0]
	v_pk_mul_f32 v[106:107], v[84:85], v[90:91] op_sel_hi:[1,0]
	v_pk_mul_f32 v[108:109], v[86:87], v[90:91] op_sel_hi:[1,0]
	v_pk_mul_f32 v[110:111], v[88:89], v[90:91] op_sel_hi:[1,0]
	v_add_f32_dpp v96, v96, v96 quad_perm:[2,3,0,1] row_mask:0xf bank_mask:0xf bound_ctrl:1
	v_add_f32_dpp v98, v98, v98 quad_perm:[2,3,0,1] row_mask:0xf bank_mask:0xf bound_ctrl:1
	v_add_f32_dpp v100, v100, v100 quad_perm:[2,3,0,1] row_mask:0xf bank_mask:0xf bound_ctrl:1
	v_add_f32_dpp v102, v102, v102 quad_perm:[2,3,0,1] row_mask:0xf bank_mask:0xf bound_ctrl:1
	v_pk_mul_f32 v[112:113], v[82:83], v[90:91] op_sel:[0,1] op_sel_hi:[1,1]
	v_pk_mul_f32 v[114:115], v[84:85], v[90:91] op_sel:[0,1] op_sel_hi:[1,1]
	v_pk_mul_f32 v[116:117], v[86:87], v[90:91] op_sel:[0,1] op_sel_hi:[1,1]
	v_pk_mul_f32 v[118:119], v[88:89], v[90:91] op_sel:[0,1] op_sel_hi:[1,1]
	ds_read_b128 v[82:85], v127 offset:11968
	ds_read_b128 v[86:89], v127 offset:11984
	v_add_f32_dpp v96, v96, v96 row_half_mirror row_mask:0xf bank_mask:0xf bound_ctrl:1
	v_add_f32_dpp v98, v98, v98 row_half_mirror row_mask:0xf bank_mask:0xf bound_ctrl:1
	v_add_f32_dpp v100, v100, v100 row_half_mirror row_mask:0xf bank_mask:0xf bound_ctrl:1
	v_add_f32_dpp v102, v102, v102 row_half_mirror row_mask:0xf bank_mask:0xf bound_ctrl:1
	v_pk_fma_f32 v[104:105], v[18:19], v[66:67], v[104:105]
	v_pk_fma_f32 v[106:107], v[20:21], v[68:69], v[106:107]
	v_pk_fma_f32 v[108:109], v[22:23], v[70:71], v[108:109]
	v_pk_fma_f32 v[110:111], v[24:25], v[72:73], v[110:111]
	v_pk_fma_f32 v[112:113], v[26:27], v[66:67], v[112:113]
	v_pk_fma_f32 v[114:115], v[28:29], v[68:69], v[114:115]
	v_pk_fma_f32 v[116:117], v[30:31], v[70:71], v[116:117]
	v_pk_fma_f32 v[118:119], v[32:33], v[72:73], v[118:119]
	ds_read_b128 v[66:69], v127 offset:11456
	ds_read_b128 v[70:73], v127 offset:11472
	ds_read_b32 v92, v128 offset:11200
	ds_read_b32 v93, v128 offset:11232
	s_waitcnt lgkmcnt(6)
	v_pk_fma_f32 v[18:19], v[96:97], v[74:75], v[104:105] op_sel_hi:[0,1,1]
	v_pk_fma_f32 v[20:21], v[96:97], v[76:77], v[106:107] op_sel_hi:[0,1,1]
	v_pk_fma_f32 v[22:23], v[96:97], v[78:79], v[108:109] op_sel_hi:[0,1,1]
	v_pk_fma_f32 v[24:25], v[96:97], v[80:81], v[110:111] op_sel_hi:[0,1,1]
	v_pk_fma_f32 v[26:27], v[100:101], v[74:75], v[112:113] op_sel_hi:[0,1,1]
	v_pk_fma_f32 v[28:29], v[100:101], v[76:77], v[114:115] op_sel_hi:[0,1,1]
	v_pk_fma_f32 v[30:31], v[100:101], v[78:79], v[116:117] op_sel_hi:[0,1,1]
	v_pk_fma_f32 v[32:33], v[100:101], v[80:81], v[118:119] op_sel_hi:[0,1,1]
	v_fma_f32 v124, v90, v95, v98
	v_fma_f32 v125, v91, v95, v102
	v_fma_f32 v121, v96, v94, v124
	v_fma_f32 v123, v100, v94, v125
	v_mov_b32_dpp v121, v120 row_shr:1 row_mask:0xf bank_mask:0x3
	v_mov_b32_dpp v121, v120 row_shl:1 row_mask:0xf bank_mask:0xc
	v_mov_b32_dpp v123, v122 row_shr:1 row_mask:0xf bank_mask:0x3
	v_mov_b32_dpp v123, v122 row_shl:1 row_mask:0xf bank_mask:0xc
	ds_read_b128 v[34:37], v127 offset:12800
	ds_read_b128 v[38:41], v127 offset:12816
	ds_read_b128 v[42:45], v127 offset:13824
	ds_read_b128 v[46:49], v127 offset:13840
	ds_read_b128 v[74:77], v127 offset:11712
	ds_read_b128 v[78:81], v127 offset:11728
	ds_read_b64 v[94:95], v129 offset:11200
	v_pk_mul_f32 v[96:97], v[18:19], v[50:51]
	v_pk_mul_f32 v[98:99], v[18:19], v[58:59]
	v_pk_fma_f32 v[96:97], v[20:21], v[52:53], v[96:97]
	v_pk_fma_f32 v[98:99], v[20:21], v[60:61], v[98:99]
	v_pk_fma_f32 v[96:97], v[22:23], v[54:55], v[96:97]
	v_pk_fma_f32 v[98:99], v[22:23], v[62:63], v[98:99]
	v_pk_fma_f32 v[96:97], v[24:25], v[56:57], v[96:97]
	v_pk_fma_f32 v[98:99], v[24:25], v[64:65], v[98:99]
	v_pk_mul_f32 v[100:101], v[26:27], v[50:51]
	v_pk_mul_f32 v[102:103], v[26:27], v[58:59]
	v_pk_fma_f32 v[100:101], v[28:29], v[52:53], v[100:101]
	v_pk_fma_f32 v[102:103], v[28:29], v[60:61], v[102:103]
	v_pk_fma_f32 v[100:101], v[30:31], v[54:55], v[100:101]
	v_pk_fma_f32 v[102:103], v[30:31], v[62:63], v[102:103]
	v_pk_fma_f32 v[100:101], v[32:33], v[56:57], v[100:101]
	v_pk_fma_f32 v[102:103], v[32:33], v[64:65], v[102:103]
	v_add_f32_e32 v96, v96, v97
	v_add_f32_e32 v98, v98, v99
	v_add_f32_e32 v100, v100, v101
	v_add_f32_e32 v102, v102, v103
	s_waitcnt lgkmcnt(7)
	v_add_f32_dpp v96, v96, v96 quad_perm:[1,0,3,2] row_mask:0xf bank_mask:0xf bound_ctrl:1
	v_add_f32_dpp v98, v98, v98 quad_perm:[1,0,3,2] row_mask:0xf bank_mask:0xf bound_ctrl:1
	v_add_f32_dpp v100, v100, v100 quad_perm:[1,0,3,2] row_mask:0xf bank_mask:0xf bound_ctrl:1
	v_add_f32_dpp v102, v102, v102 quad_perm:[1,0,3,2] row_mask:0xf bank_mask:0xf bound_ctrl:1
	v_pk_mul_f32 v[104:105], v[82:83], v[92:93] op_sel_hi:[1,0]
	v_pk_mul_f32 v[106:107], v[84:85], v[92:93] op_sel_hi:[1,0]
	v_pk_mul_f32 v[108:109], v[86:87], v[92:93] op_sel_hi:[1,0]
	v_pk_mul_f32 v[110:111], v[88:89], v[92:93] op_sel_hi:[1,0]
	v_add_f32_dpp v96, v96, v96 quad_perm:[2,3,0,1] row_mask:0xf bank_mask:0xf bound_ctrl:1
	v_add_f32_dpp v98, v98, v98 quad_perm:[2,3,0,1] row_mask:0xf bank_mask:0xf bound_ctrl:1
	v_add_f32_dpp v100, v100, v100 quad_perm:[2,3,0,1] row_mask:0xf bank_mask:0xf bound_ctrl:1
	v_add_f32_dpp v102, v102, v102 quad_perm:[2,3,0,1] row_mask:0xf bank_mask:0xf bound_ctrl:1
	v_pk_mul_f32 v[112:113], v[82:83], v[92:93] op_sel:[0,1] op_sel_hi:[1,1]
	v_pk_mul_f32 v[114:115], v[84:85], v[92:93] op_sel:[0,1] op_sel_hi:[1,1]
	v_pk_mul_f32 v[116:117], v[86:87], v[92:93] op_sel:[0,1] op_sel_hi:[1,1]
	v_pk_mul_f32 v[118:119], v[88:89], v[92:93] op_sel:[0,1] op_sel_hi:[1,1]
	ds_read_b128 v[82:85], v127 offset:13568
	ds_read_b128 v[86:89], v127 offset:13584
	v_add_f32_dpp v96, v96, v96 row_half_mirror row_mask:0xf bank_mask:0xf bound_ctrl:1
	v_add_f32_dpp v98, v98, v98 row_half_mirror row_mask:0xf bank_mask:0xf bound_ctrl:1
	v_add_f32_dpp v100, v100, v100 row_half_mirror row_mask:0xf bank_mask:0xf bound_ctrl:1
	v_add_f32_dpp v102, v102, v102 row_half_mirror row_mask:0xf bank_mask:0xf bound_ctrl:1
	v_pk_fma_f32 v[104:105], v[18:19], v[66:67], v[104:105]
	v_pk_fma_f32 v[106:107], v[20:21], v[68:69], v[106:107]
	v_pk_fma_f32 v[108:109], v[22:23], v[70:71], v[108:109]
	v_pk_fma_f32 v[110:111], v[24:25], v[72:73], v[110:111]
	v_pk_fma_f32 v[112:113], v[26:27], v[66:67], v[112:113]
	v_pk_fma_f32 v[114:115], v[28:29], v[68:69], v[114:115]
	v_pk_fma_f32 v[116:117], v[30:31], v[70:71], v[116:117]
	v_pk_fma_f32 v[118:119], v[32:33], v[72:73], v[118:119]
	ds_read_b128 v[66:69], v127 offset:13056
	ds_read_b128 v[70:73], v127 offset:13072
	ds_read_b32 v90, v128 offset:12800
	ds_read_b32 v91, v128 offset:12832
	s_waitcnt lgkmcnt(6)
	v_pk_fma_f32 v[18:19], v[96:97], v[74:75], v[104:105] op_sel_hi:[0,1,1]
	v_pk_fma_f32 v[20:21], v[96:97], v[76:77], v[106:107] op_sel_hi:[0,1,1]
	v_pk_fma_f32 v[22:23], v[96:97], v[78:79], v[108:109] op_sel_hi:[0,1,1]
	v_pk_fma_f32 v[24:25], v[96:97], v[80:81], v[110:111] op_sel_hi:[0,1,1]
	v_pk_fma_f32 v[26:27], v[100:101], v[74:75], v[112:113] op_sel_hi:[0,1,1]
	v_pk_fma_f32 v[28:29], v[100:101], v[76:77], v[114:115] op_sel_hi:[0,1,1]
	v_pk_fma_f32 v[30:31], v[100:101], v[78:79], v[116:117] op_sel_hi:[0,1,1]
	v_pk_fma_f32 v[32:33], v[100:101], v[80:81], v[118:119] op_sel_hi:[0,1,1]
	v_fma_f32 v124, v92, v95, v98
	v_fma_f32 v125, v93, v95, v102
	v_fma_f32 v120, v96, v94, v124
	v_fma_f32 v122, v100, v94, v125
	v_mov_b32_dpp v120, v121 row_shr:1 row_mask:0xf bank_mask:0x3
	v_mov_b32_dpp v120, v121 row_shl:1 row_mask:0xf bank_mask:0xc
	v_mov_b32_dpp v122, v123 row_shr:1 row_mask:0xf bank_mask:0x3
	v_mov_b32_dpp v122, v123 row_shl:1 row_mask:0xf bank_mask:0xc
	v_cvt_pk_bf16_f32 v126, v120, v120
	v_cvt_pk_bf16_f32 v139, v122, v122
	global_store_short v[130:131], v126, off
	global_store_short v[130:131], v139, off offset:16
	v_lshl_add_u64 v[130:131], v[130:131], 0, v[132:133]
	ds_read_b128 v[50:53], v127 offset:14400
	ds_read_b128 v[54:57], v127 offset:14416
	ds_read_b128 v[58:61], v127 offset:15424
	ds_read_b128 v[62:65], v127 offset:15440
	ds_read_b128 v[74:77], v127 offset:13312
	ds_read_b128 v[78:81], v127 offset:13328
	ds_read_b64 v[94:95], v129 offset:12800
	v_pk_mul_f32 v[96:97], v[18:19], v[34:35]
	v_pk_mul_f32 v[98:99], v[18:19], v[42:43]
	v_pk_fma_f32 v[96:97], v[20:21], v[36:37], v[96:97]
	v_pk_fma_f32 v[98:99], v[20:21], v[44:45], v[98:99]
	v_pk_fma_f32 v[96:97], v[22:23], v[38:39], v[96:97]
	v_pk_fma_f32 v[98:99], v[22:23], v[46:47], v[98:99]
	v_pk_fma_f32 v[96:97], v[24:25], v[40:41], v[96:97]
	v_pk_fma_f32 v[98:99], v[24:25], v[48:49], v[98:99]
	v_pk_mul_f32 v[100:101], v[26:27], v[34:35]
	v_pk_mul_f32 v[102:103], v[26:27], v[42:43]
	v_pk_fma_f32 v[100:101], v[28:29], v[36:37], v[100:101]
	v_pk_fma_f32 v[102:103], v[28:29], v[44:45], v[102:103]
	v_pk_fma_f32 v[100:101], v[30:31], v[38:39], v[100:101]
	v_pk_fma_f32 v[102:103], v[30:31], v[46:47], v[102:103]
	v_pk_fma_f32 v[100:101], v[32:33], v[40:41], v[100:101]
	v_pk_fma_f32 v[102:103], v[32:33], v[48:49], v[102:103]
	v_add_f32_e32 v96, v96, v97
	v_add_f32_e32 v98, v98, v99
	v_add_f32_e32 v100, v100, v101
	v_add_f32_e32 v102, v102, v103
	s_waitcnt lgkmcnt(7)
	v_add_f32_dpp v96, v96, v96 quad_perm:[1,0,3,2] row_mask:0xf bank_mask:0xf bound_ctrl:1
	v_add_f32_dpp v98, v98, v98 quad_perm:[1,0,3,2] row_mask:0xf bank_mask:0xf bound_ctrl:1
	v_add_f32_dpp v100, v100, v100 quad_perm:[1,0,3,2] row_mask:0xf bank_mask:0xf bound_ctrl:1
	v_add_f32_dpp v102, v102, v102 quad_perm:[1,0,3,2] row_mask:0xf bank_mask:0xf bound_ctrl:1
	v_pk_mul_f32 v[104:105], v[82:83], v[90:91] op_sel_hi:[1,0]
	v_pk_mul_f32 v[106:107], v[84:85], v[90:91] op_sel_hi:[1,0]
	v_pk_mul_f32 v[108:109], v[86:87], v[90:91] op_sel_hi:[1,0]
	v_pk_mul_f32 v[110:111], v[88:89], v[90:91] op_sel_hi:[1,0]
	v_add_f32_dpp v96, v96, v96 quad_perm:[2,3,0,1] row_mask:0xf bank_mask:0xf bound_ctrl:1
	v_add_f32_dpp v98, v98, v98 quad_perm:[2,3,0,1] row_mask:0xf bank_mask:0xf bound_ctrl:1
	v_add_f32_dpp v100, v100, v100 quad_perm:[2,3,0,1] row_mask:0xf bank_mask:0xf bound_ctrl:1
	v_add_f32_dpp v102, v102, v102 quad_perm:[2,3,0,1] row_mask:0xf bank_mask:0xf bound_ctrl:1
	v_pk_mul_f32 v[112:113], v[82:83], v[90:91] op_sel:[0,1] op_sel_hi:[1,1]
	v_pk_mul_f32 v[114:115], v[84:85], v[90:91] op_sel:[0,1] op_sel_hi:[1,1]
	v_pk_mul_f32 v[116:117], v[86:87], v[90:91] op_sel:[0,1] op_sel_hi:[1,1]
	v_pk_mul_f32 v[118:119], v[88:89], v[90:91] op_sel:[0,1] op_sel_hi:[1,1]
	ds_read_b128 v[82:85], v127 offset:15168
	ds_read_b128 v[86:89], v127 offset:15184
	v_add_f32_dpp v96, v96, v96 row_half_mirror row_mask:0xf bank_mask:0xf bound_ctrl:1
	v_add_f32_dpp v98, v98, v98 row_half_mirror row_mask:0xf bank_mask:0xf bound_ctrl:1
	v_add_f32_dpp v100, v100, v100 row_half_mirror row_mask:0xf bank_mask:0xf bound_ctrl:1
	v_add_f32_dpp v102, v102, v102 row_half_mirror row_mask:0xf bank_mask:0xf bound_ctrl:1
	v_pk_fma_f32 v[104:105], v[18:19], v[66:67], v[104:105]
	v_pk_fma_f32 v[106:107], v[20:21], v[68:69], v[106:107]
	v_pk_fma_f32 v[108:109], v[22:23], v[70:71], v[108:109]
	v_pk_fma_f32 v[110:111], v[24:25], v[72:73], v[110:111]
	v_pk_fma_f32 v[112:113], v[26:27], v[66:67], v[112:113]
	v_pk_fma_f32 v[114:115], v[28:29], v[68:69], v[114:115]
	v_pk_fma_f32 v[116:117], v[30:31], v[70:71], v[116:117]
	v_pk_fma_f32 v[118:119], v[32:33], v[72:73], v[118:119]
	ds_read_b128 v[66:69], v127 offset:14656
	ds_read_b128 v[70:73], v127 offset:14672
	ds_read_b32 v92, v128 offset:14400
	ds_read_b32 v93, v128 offset:14432
	s_waitcnt lgkmcnt(6)
	v_pk_fma_f32 v[18:19], v[96:97], v[74:75], v[104:105] op_sel_hi:[0,1,1]
	v_pk_fma_f32 v[20:21], v[96:97], v[76:77], v[106:107] op_sel_hi:[0,1,1]
	v_pk_fma_f32 v[22:23], v[96:97], v[78:79], v[108:109] op_sel_hi:[0,1,1]
	v_pk_fma_f32 v[24:25], v[96:97], v[80:81], v[110:111] op_sel_hi:[0,1,1]
	v_pk_fma_f32 v[26:27], v[100:101], v[74:75], v[112:113] op_sel_hi:[0,1,1]
	v_pk_fma_f32 v[28:29], v[100:101], v[76:77], v[114:115] op_sel_hi:[0,1,1]
	v_pk_fma_f32 v[30:31], v[100:101], v[78:79], v[116:117] op_sel_hi:[0,1,1]
	v_pk_fma_f32 v[32:33], v[100:101], v[80:81], v[118:119] op_sel_hi:[0,1,1]
	v_fma_f32 v124, v90, v95, v98
	v_fma_f32 v125, v91, v95, v102
	v_fma_f32 v121, v96, v94, v124
	v_fma_f32 v123, v100, v94, v125
	v_mov_b32_dpp v121, v120 row_shr:1 row_mask:0xf bank_mask:0x3
	v_mov_b32_dpp v121, v120 row_shl:1 row_mask:0xf bank_mask:0xc
	v_mov_b32_dpp v123, v122 row_shr:1 row_mask:0xf bank_mask:0x3
	v_mov_b32_dpp v123, v122 row_shl:1 row_mask:0xf bank_mask:0xc
	ds_read_b128 v[34:37], v127 offset:16000
	ds_read_b128 v[38:41], v127 offset:16016
	ds_read_b128 v[42:45], v127 offset:17024
	ds_read_b128 v[46:49], v127 offset:17040
	ds_read_b128 v[74:77], v127 offset:14912
	ds_read_b128 v[78:81], v127 offset:14928
	ds_read_b64 v[94:95], v129 offset:14400
	v_pk_mul_f32 v[96:97], v[18:19], v[50:51]
	v_pk_mul_f32 v[98:99], v[18:19], v[58:59]
	v_pk_fma_f32 v[96:97], v[20:21], v[52:53], v[96:97]
	v_pk_fma_f32 v[98:99], v[20:21], v[60:61], v[98:99]
	v_pk_fma_f32 v[96:97], v[22:23], v[54:55], v[96:97]
	v_pk_fma_f32 v[98:99], v[22:23], v[62:63], v[98:99]
	v_pk_fma_f32 v[96:97], v[24:25], v[56:57], v[96:97]
	v_pk_fma_f32 v[98:99], v[24:25], v[64:65], v[98:99]
	v_pk_mul_f32 v[100:101], v[26:27], v[50:51]
	v_pk_mul_f32 v[102:103], v[26:27], v[58:59]
	v_pk_fma_f32 v[100:101], v[28:29], v[52:53], v[100:101]
	v_pk_fma_f32 v[102:103], v[28:29], v[60:61], v[102:103]
	v_pk_fma_f32 v[100:101], v[30:31], v[54:55], v[100:101]
	v_pk_fma_f32 v[102:103], v[30:31], v[62:63], v[102:103]
	v_pk_fma_f32 v[100:101], v[32:33], v[56:57], v[100:101]
	v_pk_fma_f32 v[102:103], v[32:33], v[64:65], v[102:103]
	v_add_f32_e32 v96, v96, v97
	v_add_f32_e32 v98, v98, v99
	v_add_f32_e32 v100, v100, v101
	v_add_f32_e32 v102, v102, v103
	s_waitcnt lgkmcnt(7)
	v_add_f32_dpp v96, v96, v96 quad_perm:[1,0,3,2] row_mask:0xf bank_mask:0xf bound_ctrl:1
	v_add_f32_dpp v98, v98, v98 quad_perm:[1,0,3,2] row_mask:0xf bank_mask:0xf bound_ctrl:1
	v_add_f32_dpp v100, v100, v100 quad_perm:[1,0,3,2] row_mask:0xf bank_mask:0xf bound_ctrl:1
	v_add_f32_dpp v102, v102, v102 quad_perm:[1,0,3,2] row_mask:0xf bank_mask:0xf bound_ctrl:1
	v_pk_mul_f32 v[104:105], v[82:83], v[92:93] op_sel_hi:[1,0]
	v_pk_mul_f32 v[106:107], v[84:85], v[92:93] op_sel_hi:[1,0]
	v_pk_mul_f32 v[108:109], v[86:87], v[92:93] op_sel_hi:[1,0]
	v_pk_mul_f32 v[110:111], v[88:89], v[92:93] op_sel_hi:[1,0]
	v_add_f32_dpp v96, v96, v96 quad_perm:[2,3,0,1] row_mask:0xf bank_mask:0xf bound_ctrl:1
	v_add_f32_dpp v98, v98, v98 quad_perm:[2,3,0,1] row_mask:0xf bank_mask:0xf bound_ctrl:1
	v_add_f32_dpp v100, v100, v100 quad_perm:[2,3,0,1] row_mask:0xf bank_mask:0xf bound_ctrl:1
	v_add_f32_dpp v102, v102, v102 quad_perm:[2,3,0,1] row_mask:0xf bank_mask:0xf bound_ctrl:1
	v_pk_mul_f32 v[112:113], v[82:83], v[92:93] op_sel:[0,1] op_sel_hi:[1,1]
	v_pk_mul_f32 v[114:115], v[84:85], v[92:93] op_sel:[0,1] op_sel_hi:[1,1]
	v_pk_mul_f32 v[116:117], v[86:87], v[92:93] op_sel:[0,1] op_sel_hi:[1,1]
	v_pk_mul_f32 v[118:119], v[88:89], v[92:93] op_sel:[0,1] op_sel_hi:[1,1]
	ds_read_b128 v[82:85], v127 offset:16768
	ds_read_b128 v[86:89], v127 offset:16784
	v_add_f32_dpp v96, v96, v96 row_half_mirror row_mask:0xf bank_mask:0xf bound_ctrl:1
	v_add_f32_dpp v98, v98, v98 row_half_mirror row_mask:0xf bank_mask:0xf bound_ctrl:1
	v_add_f32_dpp v100, v100, v100 row_half_mirror row_mask:0xf bank_mask:0xf bound_ctrl:1
	v_add_f32_dpp v102, v102, v102 row_half_mirror row_mask:0xf bank_mask:0xf bound_ctrl:1
	v_pk_fma_f32 v[104:105], v[18:19], v[66:67], v[104:105]
	v_pk_fma_f32 v[106:107], v[20:21], v[68:69], v[106:107]
	v_pk_fma_f32 v[108:109], v[22:23], v[70:71], v[108:109]
	v_pk_fma_f32 v[110:111], v[24:25], v[72:73], v[110:111]
	v_pk_fma_f32 v[112:113], v[26:27], v[66:67], v[112:113]
	v_pk_fma_f32 v[114:115], v[28:29], v[68:69], v[114:115]
	v_pk_fma_f32 v[116:117], v[30:31], v[70:71], v[116:117]
	v_pk_fma_f32 v[118:119], v[32:33], v[72:73], v[118:119]
	ds_read_b128 v[66:69], v127 offset:16256
	ds_read_b128 v[70:73], v127 offset:16272
	ds_read_b32 v90, v128 offset:16000
	ds_read_b32 v91, v128 offset:16032
	s_waitcnt lgkmcnt(6)
	v_pk_fma_f32 v[18:19], v[96:97], v[74:75], v[104:105] op_sel_hi:[0,1,1]
	v_pk_fma_f32 v[20:21], v[96:97], v[76:77], v[106:107] op_sel_hi:[0,1,1]
	v_pk_fma_f32 v[22:23], v[96:97], v[78:79], v[108:109] op_sel_hi:[0,1,1]
	v_pk_fma_f32 v[24:25], v[96:97], v[80:81], v[110:111] op_sel_hi:[0,1,1]
	v_pk_fma_f32 v[26:27], v[100:101], v[74:75], v[112:113] op_sel_hi:[0,1,1]
	v_pk_fma_f32 v[28:29], v[100:101], v[76:77], v[114:115] op_sel_hi:[0,1,1]
	v_pk_fma_f32 v[30:31], v[100:101], v[78:79], v[116:117] op_sel_hi:[0,1,1]
	v_pk_fma_f32 v[32:33], v[100:101], v[80:81], v[118:119] op_sel_hi:[0,1,1]
	v_fma_f32 v124, v92, v95, v98
	v_fma_f32 v125, v93, v95, v102
	v_fma_f32 v120, v96, v94, v124
	v_fma_f32 v122, v100, v94, v125
	v_mov_b32_dpp v120, v121 row_shr:1 row_mask:0xf bank_mask:0x3
	v_mov_b32_dpp v120, v121 row_shl:1 row_mask:0xf bank_mask:0xc
	v_mov_b32_dpp v122, v123 row_shr:1 row_mask:0xf bank_mask:0x3
	v_mov_b32_dpp v122, v123 row_shl:1 row_mask:0xf bank_mask:0xc
	ds_read_b128 v[50:53], v127 offset:17600
	ds_read_b128 v[54:57], v127 offset:17616
	ds_read_b128 v[58:61], v127 offset:18624
	ds_read_b128 v[62:65], v127 offset:18640
	ds_read_b128 v[74:77], v127 offset:16512
	ds_read_b128 v[78:81], v127 offset:16528
	ds_read_b64 v[94:95], v129 offset:16000
	v_pk_mul_f32 v[96:97], v[18:19], v[34:35]
	v_pk_mul_f32 v[98:99], v[18:19], v[42:43]
	v_pk_fma_f32 v[96:97], v[20:21], v[36:37], v[96:97]
	v_pk_fma_f32 v[98:99], v[20:21], v[44:45], v[98:99]
	v_pk_fma_f32 v[96:97], v[22:23], v[38:39], v[96:97]
	v_pk_fma_f32 v[98:99], v[22:23], v[46:47], v[98:99]
	v_pk_fma_f32 v[96:97], v[24:25], v[40:41], v[96:97]
	v_pk_fma_f32 v[98:99], v[24:25], v[48:49], v[98:99]
	v_pk_mul_f32 v[100:101], v[26:27], v[34:35]
	v_pk_mul_f32 v[102:103], v[26:27], v[42:43]
	v_pk_fma_f32 v[100:101], v[28:29], v[36:37], v[100:101]
	v_pk_fma_f32 v[102:103], v[28:29], v[44:45], v[102:103]
	v_pk_fma_f32 v[100:101], v[30:31], v[38:39], v[100:101]
	v_pk_fma_f32 v[102:103], v[30:31], v[46:47], v[102:103]
	v_pk_fma_f32 v[100:101], v[32:33], v[40:41], v[100:101]
	v_pk_fma_f32 v[102:103], v[32:33], v[48:49], v[102:103]
	v_add_f32_e32 v96, v96, v97
	v_add_f32_e32 v98, v98, v99
	v_add_f32_e32 v100, v100, v101
	v_add_f32_e32 v102, v102, v103
	s_waitcnt lgkmcnt(7)
	v_add_f32_dpp v96, v96, v96 quad_perm:[1,0,3,2] row_mask:0xf bank_mask:0xf bound_ctrl:1
	v_add_f32_dpp v98, v98, v98 quad_perm:[1,0,3,2] row_mask:0xf bank_mask:0xf bound_ctrl:1
	v_add_f32_dpp v100, v100, v100 quad_perm:[1,0,3,2] row_mask:0xf bank_mask:0xf bound_ctrl:1
	v_add_f32_dpp v102, v102, v102 quad_perm:[1,0,3,2] row_mask:0xf bank_mask:0xf bound_ctrl:1
	v_pk_mul_f32 v[104:105], v[82:83], v[90:91] op_sel_hi:[1,0]
	v_pk_mul_f32 v[106:107], v[84:85], v[90:91] op_sel_hi:[1,0]
	v_pk_mul_f32 v[108:109], v[86:87], v[90:91] op_sel_hi:[1,0]
	v_pk_mul_f32 v[110:111], v[88:89], v[90:91] op_sel_hi:[1,0]
	v_add_f32_dpp v96, v96, v96 quad_perm:[2,3,0,1] row_mask:0xf bank_mask:0xf bound_ctrl:1
	v_add_f32_dpp v98, v98, v98 quad_perm:[2,3,0,1] row_mask:0xf bank_mask:0xf bound_ctrl:1
	v_add_f32_dpp v100, v100, v100 quad_perm:[2,3,0,1] row_mask:0xf bank_mask:0xf bound_ctrl:1
	v_add_f32_dpp v102, v102, v102 quad_perm:[2,3,0,1] row_mask:0xf bank_mask:0xf bound_ctrl:1
	v_pk_mul_f32 v[112:113], v[82:83], v[90:91] op_sel:[0,1] op_sel_hi:[1,1]
	v_pk_mul_f32 v[114:115], v[84:85], v[90:91] op_sel:[0,1] op_sel_hi:[1,1]
	v_pk_mul_f32 v[116:117], v[86:87], v[90:91] op_sel:[0,1] op_sel_hi:[1,1]
	v_pk_mul_f32 v[118:119], v[88:89], v[90:91] op_sel:[0,1] op_sel_hi:[1,1]
	ds_read_b128 v[82:85], v127 offset:18368
	ds_read_b128 v[86:89], v127 offset:18384
	v_add_f32_dpp v96, v96, v96 row_half_mirror row_mask:0xf bank_mask:0xf bound_ctrl:1
	v_add_f32_dpp v98, v98, v98 row_half_mirror row_mask:0xf bank_mask:0xf bound_ctrl:1
	v_add_f32_dpp v100, v100, v100 row_half_mirror row_mask:0xf bank_mask:0xf bound_ctrl:1
	v_add_f32_dpp v102, v102, v102 row_half_mirror row_mask:0xf bank_mask:0xf bound_ctrl:1
	v_pk_fma_f32 v[104:105], v[18:19], v[66:67], v[104:105]
	v_pk_fma_f32 v[106:107], v[20:21], v[68:69], v[106:107]
	v_pk_fma_f32 v[108:109], v[22:23], v[70:71], v[108:109]
	v_pk_fma_f32 v[110:111], v[24:25], v[72:73], v[110:111]
	v_pk_fma_f32 v[112:113], v[26:27], v[66:67], v[112:113]
	v_pk_fma_f32 v[114:115], v[28:29], v[68:69], v[114:115]
	v_pk_fma_f32 v[116:117], v[30:31], v[70:71], v[116:117]
	v_pk_fma_f32 v[118:119], v[32:33], v[72:73], v[118:119]
	ds_read_b128 v[66:69], v127 offset:17856
	ds_read_b128 v[70:73], v127 offset:17872
	ds_read_b32 v92, v128 offset:17600
	ds_read_b32 v93, v128 offset:17632
	s_waitcnt lgkmcnt(6)
	v_pk_fma_f32 v[18:19], v[96:97], v[74:75], v[104:105] op_sel_hi:[0,1,1]
	v_pk_fma_f32 v[20:21], v[96:97], v[76:77], v[106:107] op_sel_hi:[0,1,1]
	v_pk_fma_f32 v[22:23], v[96:97], v[78:79], v[108:109] op_sel_hi:[0,1,1]
	v_pk_fma_f32 v[24:25], v[96:97], v[80:81], v[110:111] op_sel_hi:[0,1,1]
	v_pk_fma_f32 v[26:27], v[100:101], v[74:75], v[112:113] op_sel_hi:[0,1,1]
	v_pk_fma_f32 v[28:29], v[100:101], v[76:77], v[114:115] op_sel_hi:[0,1,1]
	v_pk_fma_f32 v[30:31], v[100:101], v[78:79], v[116:117] op_sel_hi:[0,1,1]
	v_pk_fma_f32 v[32:33], v[100:101], v[80:81], v[118:119] op_sel_hi:[0,1,1]
	v_fma_f32 v124, v90, v95, v98
	v_fma_f32 v125, v91, v95, v102
	v_fma_f32 v121, v96, v94, v124
	v_fma_f32 v123, v100, v94, v125
	v_mov_b32_dpp v121, v120 row_shr:1 row_mask:0xf bank_mask:0x3
	v_mov_b32_dpp v121, v120 row_shl:1 row_mask:0xf bank_mask:0xc
	v_mov_b32_dpp v123, v122 row_shr:1 row_mask:0xf bank_mask:0x3
	v_mov_b32_dpp v123, v122 row_shl:1 row_mask:0xf bank_mask:0xc
	ds_read_b128 v[34:37], v127 offset:19200
	ds_read_b128 v[38:41], v127 offset:19216
	ds_read_b128 v[42:45], v127 offset:20224
	ds_read_b128 v[46:49], v127 offset:20240
	ds_read_b128 v[74:77], v127 offset:18112
	ds_read_b128 v[78:81], v127 offset:18128
	ds_read_b64 v[94:95], v129 offset:17600
	v_pk_mul_f32 v[96:97], v[18:19], v[50:51]
	v_pk_mul_f32 v[98:99], v[18:19], v[58:59]
	v_pk_fma_f32 v[96:97], v[20:21], v[52:53], v[96:97]
	v_pk_fma_f32 v[98:99], v[20:21], v[60:61], v[98:99]
	v_pk_fma_f32 v[96:97], v[22:23], v[54:55], v[96:97]
	v_pk_fma_f32 v[98:99], v[22:23], v[62:63], v[98:99]
	v_pk_fma_f32 v[96:97], v[24:25], v[56:57], v[96:97]
	v_pk_fma_f32 v[98:99], v[24:25], v[64:65], v[98:99]
	v_pk_mul_f32 v[100:101], v[26:27], v[50:51]
	v_pk_mul_f32 v[102:103], v[26:27], v[58:59]
	v_pk_fma_f32 v[100:101], v[28:29], v[52:53], v[100:101]
	v_pk_fma_f32 v[102:103], v[28:29], v[60:61], v[102:103]
	v_pk_fma_f32 v[100:101], v[30:31], v[54:55], v[100:101]
	v_pk_fma_f32 v[102:103], v[30:31], v[62:63], v[102:103]
	v_pk_fma_f32 v[100:101], v[32:33], v[56:57], v[100:101]
	v_pk_fma_f32 v[102:103], v[32:33], v[64:65], v[102:103]
	v_add_f32_e32 v96, v96, v97
	v_add_f32_e32 v98, v98, v99
	v_add_f32_e32 v100, v100, v101
	v_add_f32_e32 v102, v102, v103
	s_waitcnt lgkmcnt(7)
	v_add_f32_dpp v96, v96, v96 quad_perm:[1,0,3,2] row_mask:0xf bank_mask:0xf bound_ctrl:1
	v_add_f32_dpp v98, v98, v98 quad_perm:[1,0,3,2] row_mask:0xf bank_mask:0xf bound_ctrl:1
	v_add_f32_dpp v100, v100, v100 quad_perm:[1,0,3,2] row_mask:0xf bank_mask:0xf bound_ctrl:1
	v_add_f32_dpp v102, v102, v102 quad_perm:[1,0,3,2] row_mask:0xf bank_mask:0xf bound_ctrl:1
	v_pk_mul_f32 v[104:105], v[82:83], v[92:93] op_sel_hi:[1,0]
	v_pk_mul_f32 v[106:107], v[84:85], v[92:93] op_sel_hi:[1,0]
	v_pk_mul_f32 v[108:109], v[86:87], v[92:93] op_sel_hi:[1,0]
	v_pk_mul_f32 v[110:111], v[88:89], v[92:93] op_sel_hi:[1,0]
	v_add_f32_dpp v96, v96, v96 quad_perm:[2,3,0,1] row_mask:0xf bank_mask:0xf bound_ctrl:1
	v_add_f32_dpp v98, v98, v98 quad_perm:[2,3,0,1] row_mask:0xf bank_mask:0xf bound_ctrl:1
	v_add_f32_dpp v100, v100, v100 quad_perm:[2,3,0,1] row_mask:0xf bank_mask:0xf bound_ctrl:1
	v_add_f32_dpp v102, v102, v102 quad_perm:[2,3,0,1] row_mask:0xf bank_mask:0xf bound_ctrl:1
	v_pk_mul_f32 v[112:113], v[82:83], v[92:93] op_sel:[0,1] op_sel_hi:[1,1]
	v_pk_mul_f32 v[114:115], v[84:85], v[92:93] op_sel:[0,1] op_sel_hi:[1,1]
	v_pk_mul_f32 v[116:117], v[86:87], v[92:93] op_sel:[0,1] op_sel_hi:[1,1]
	v_pk_mul_f32 v[118:119], v[88:89], v[92:93] op_sel:[0,1] op_sel_hi:[1,1]
	ds_read_b128 v[82:85], v127 offset:19968
	ds_read_b128 v[86:89], v127 offset:19984
	v_add_f32_dpp v96, v96, v96 row_half_mirror row_mask:0xf bank_mask:0xf bound_ctrl:1
	v_add_f32_dpp v98, v98, v98 row_half_mirror row_mask:0xf bank_mask:0xf bound_ctrl:1
	v_add_f32_dpp v100, v100, v100 row_half_mirror row_mask:0xf bank_mask:0xf bound_ctrl:1
	v_add_f32_dpp v102, v102, v102 row_half_mirror row_mask:0xf bank_mask:0xf bound_ctrl:1
	v_pk_fma_f32 v[104:105], v[18:19], v[66:67], v[104:105]
	v_pk_fma_f32 v[106:107], v[20:21], v[68:69], v[106:107]
	v_pk_fma_f32 v[108:109], v[22:23], v[70:71], v[108:109]
	v_pk_fma_f32 v[110:111], v[24:25], v[72:73], v[110:111]
	v_pk_fma_f32 v[112:113], v[26:27], v[66:67], v[112:113]
	v_pk_fma_f32 v[114:115], v[28:29], v[68:69], v[114:115]
	v_pk_fma_f32 v[116:117], v[30:31], v[70:71], v[116:117]
	v_pk_fma_f32 v[118:119], v[32:33], v[72:73], v[118:119]
	ds_read_b128 v[66:69], v127 offset:19456
	ds_read_b128 v[70:73], v127 offset:19472
	ds_read_b32 v90, v128 offset:19200
	ds_read_b32 v91, v128 offset:19232
	s_waitcnt lgkmcnt(6)
	v_pk_fma_f32 v[18:19], v[96:97], v[74:75], v[104:105] op_sel_hi:[0,1,1]
	v_pk_fma_f32 v[20:21], v[96:97], v[76:77], v[106:107] op_sel_hi:[0,1,1]
	v_pk_fma_f32 v[22:23], v[96:97], v[78:79], v[108:109] op_sel_hi:[0,1,1]
	v_pk_fma_f32 v[24:25], v[96:97], v[80:81], v[110:111] op_sel_hi:[0,1,1]
	v_pk_fma_f32 v[26:27], v[100:101], v[74:75], v[112:113] op_sel_hi:[0,1,1]
	v_pk_fma_f32 v[28:29], v[100:101], v[76:77], v[114:115] op_sel_hi:[0,1,1]
	v_pk_fma_f32 v[30:31], v[100:101], v[78:79], v[116:117] op_sel_hi:[0,1,1]
	v_pk_fma_f32 v[32:33], v[100:101], v[80:81], v[118:119] op_sel_hi:[0,1,1]
	v_fma_f32 v124, v92, v95, v98
	v_fma_f32 v125, v93, v95, v102
	v_fma_f32 v120, v96, v94, v124
	v_fma_f32 v122, v100, v94, v125
	v_mov_b32_dpp v120, v121 row_shr:1 row_mask:0xf bank_mask:0x3
	v_mov_b32_dpp v120, v121 row_shl:1 row_mask:0xf bank_mask:0xc
	v_mov_b32_dpp v122, v123 row_shr:1 row_mask:0xf bank_mask:0x3
	v_mov_b32_dpp v122, v123 row_shl:1 row_mask:0xf bank_mask:0xc
	ds_read_b128 v[50:53], v127 offset:20800
	ds_read_b128 v[54:57], v127 offset:20816
	ds_read_b128 v[58:61], v127 offset:21824
	ds_read_b128 v[62:65], v127 offset:21840
	ds_read_b128 v[74:77], v127 offset:19712
	ds_read_b128 v[78:81], v127 offset:19728
	ds_read_b64 v[94:95], v129 offset:19200
	v_pk_mul_f32 v[96:97], v[18:19], v[34:35]
	v_pk_mul_f32 v[98:99], v[18:19], v[42:43]
	v_pk_fma_f32 v[96:97], v[20:21], v[36:37], v[96:97]
	v_pk_fma_f32 v[98:99], v[20:21], v[44:45], v[98:99]
	v_pk_fma_f32 v[96:97], v[22:23], v[38:39], v[96:97]
	v_pk_fma_f32 v[98:99], v[22:23], v[46:47], v[98:99]
	v_pk_fma_f32 v[96:97], v[24:25], v[40:41], v[96:97]
	v_pk_fma_f32 v[98:99], v[24:25], v[48:49], v[98:99]
	v_pk_mul_f32 v[100:101], v[26:27], v[34:35]
	v_pk_mul_f32 v[102:103], v[26:27], v[42:43]
	v_pk_fma_f32 v[100:101], v[28:29], v[36:37], v[100:101]
	v_pk_fma_f32 v[102:103], v[28:29], v[44:45], v[102:103]
	v_pk_fma_f32 v[100:101], v[30:31], v[38:39], v[100:101]
	v_pk_fma_f32 v[102:103], v[30:31], v[46:47], v[102:103]
	v_pk_fma_f32 v[100:101], v[32:33], v[40:41], v[100:101]
	v_pk_fma_f32 v[102:103], v[32:33], v[48:49], v[102:103]
	v_add_f32_e32 v96, v96, v97
	v_add_f32_e32 v98, v98, v99
	v_add_f32_e32 v100, v100, v101
	v_add_f32_e32 v102, v102, v103
	s_waitcnt lgkmcnt(7)
	v_add_f32_dpp v96, v96, v96 quad_perm:[1,0,3,2] row_mask:0xf bank_mask:0xf bound_ctrl:1
	v_add_f32_dpp v98, v98, v98 quad_perm:[1,0,3,2] row_mask:0xf bank_mask:0xf bound_ctrl:1
	v_add_f32_dpp v100, v100, v100 quad_perm:[1,0,3,2] row_mask:0xf bank_mask:0xf bound_ctrl:1
	v_add_f32_dpp v102, v102, v102 quad_perm:[1,0,3,2] row_mask:0xf bank_mask:0xf bound_ctrl:1
	v_pk_mul_f32 v[104:105], v[82:83], v[90:91] op_sel_hi:[1,0]
	v_pk_mul_f32 v[106:107], v[84:85], v[90:91] op_sel_hi:[1,0]
	v_pk_mul_f32 v[108:109], v[86:87], v[90:91] op_sel_hi:[1,0]
	v_pk_mul_f32 v[110:111], v[88:89], v[90:91] op_sel_hi:[1,0]
	v_add_f32_dpp v96, v96, v96 quad_perm:[2,3,0,1] row_mask:0xf bank_mask:0xf bound_ctrl:1
	v_add_f32_dpp v98, v98, v98 quad_perm:[2,3,0,1] row_mask:0xf bank_mask:0xf bound_ctrl:1
	v_add_f32_dpp v100, v100, v100 quad_perm:[2,3,0,1] row_mask:0xf bank_mask:0xf bound_ctrl:1
	v_add_f32_dpp v102, v102, v102 quad_perm:[2,3,0,1] row_mask:0xf bank_mask:0xf bound_ctrl:1
	v_pk_mul_f32 v[112:113], v[82:83], v[90:91] op_sel:[0,1] op_sel_hi:[1,1]
	v_pk_mul_f32 v[114:115], v[84:85], v[90:91] op_sel:[0,1] op_sel_hi:[1,1]
	v_pk_mul_f32 v[116:117], v[86:87], v[90:91] op_sel:[0,1] op_sel_hi:[1,1]
	v_pk_mul_f32 v[118:119], v[88:89], v[90:91] op_sel:[0,1] op_sel_hi:[1,1]
	ds_read_b128 v[82:85], v127 offset:21568
	ds_read_b128 v[86:89], v127 offset:21584
	v_add_f32_dpp v96, v96, v96 row_half_mirror row_mask:0xf bank_mask:0xf bound_ctrl:1
	v_add_f32_dpp v98, v98, v98 row_half_mirror row_mask:0xf bank_mask:0xf bound_ctrl:1
	v_add_f32_dpp v100, v100, v100 row_half_mirror row_mask:0xf bank_mask:0xf bound_ctrl:1
	v_add_f32_dpp v102, v102, v102 row_half_mirror row_mask:0xf bank_mask:0xf bound_ctrl:1
	v_pk_fma_f32 v[104:105], v[18:19], v[66:67], v[104:105]
	v_pk_fma_f32 v[106:107], v[20:21], v[68:69], v[106:107]
	v_pk_fma_f32 v[108:109], v[22:23], v[70:71], v[108:109]
	v_pk_fma_f32 v[110:111], v[24:25], v[72:73], v[110:111]
	v_pk_fma_f32 v[112:113], v[26:27], v[66:67], v[112:113]
	v_pk_fma_f32 v[114:115], v[28:29], v[68:69], v[114:115]
	v_pk_fma_f32 v[116:117], v[30:31], v[70:71], v[116:117]
	v_pk_fma_f32 v[118:119], v[32:33], v[72:73], v[118:119]
	ds_read_b128 v[66:69], v127 offset:21056
	ds_read_b128 v[70:73], v127 offset:21072
	ds_read_b32 v92, v128 offset:20800
	ds_read_b32 v93, v128 offset:20832
	s_waitcnt lgkmcnt(6)
	v_pk_fma_f32 v[18:19], v[96:97], v[74:75], v[104:105] op_sel_hi:[0,1,1]
	v_pk_fma_f32 v[20:21], v[96:97], v[76:77], v[106:107] op_sel_hi:[0,1,1]
	v_pk_fma_f32 v[22:23], v[96:97], v[78:79], v[108:109] op_sel_hi:[0,1,1]
	v_pk_fma_f32 v[24:25], v[96:97], v[80:81], v[110:111] op_sel_hi:[0,1,1]
	v_pk_fma_f32 v[26:27], v[100:101], v[74:75], v[112:113] op_sel_hi:[0,1,1]
	v_pk_fma_f32 v[28:29], v[100:101], v[76:77], v[114:115] op_sel_hi:[0,1,1]
	v_pk_fma_f32 v[30:31], v[100:101], v[78:79], v[116:117] op_sel_hi:[0,1,1]
	v_pk_fma_f32 v[32:33], v[100:101], v[80:81], v[118:119] op_sel_hi:[0,1,1]
	v_fma_f32 v124, v90, v95, v98
	v_fma_f32 v125, v91, v95, v102
	v_fma_f32 v121, v96, v94, v124
	v_fma_f32 v123, v100, v94, v125
	v_mov_b32_dpp v121, v120 row_shr:1 row_mask:0xf bank_mask:0x3
	v_mov_b32_dpp v121, v120 row_shl:1 row_mask:0xf bank_mask:0xc
	v_mov_b32_dpp v123, v122 row_shr:1 row_mask:0xf bank_mask:0x3
	v_mov_b32_dpp v123, v122 row_shl:1 row_mask:0xf bank_mask:0xc
	ds_read_b128 v[34:37], v127 offset:22400
	ds_read_b128 v[38:41], v127 offset:22416
	ds_read_b128 v[42:45], v127 offset:23424
	ds_read_b128 v[46:49], v127 offset:23440
	ds_read_b128 v[74:77], v127 offset:21312
	ds_read_b128 v[78:81], v127 offset:21328
	ds_read_b64 v[94:95], v129 offset:20800
	v_pk_mul_f32 v[96:97], v[18:19], v[50:51]
	v_pk_mul_f32 v[98:99], v[18:19], v[58:59]
	v_pk_fma_f32 v[96:97], v[20:21], v[52:53], v[96:97]
	v_pk_fma_f32 v[98:99], v[20:21], v[60:61], v[98:99]
	v_pk_fma_f32 v[96:97], v[22:23], v[54:55], v[96:97]
	v_pk_fma_f32 v[98:99], v[22:23], v[62:63], v[98:99]
	v_pk_fma_f32 v[96:97], v[24:25], v[56:57], v[96:97]
	v_pk_fma_f32 v[98:99], v[24:25], v[64:65], v[98:99]
	v_pk_mul_f32 v[100:101], v[26:27], v[50:51]
	v_pk_mul_f32 v[102:103], v[26:27], v[58:59]
	v_pk_fma_f32 v[100:101], v[28:29], v[52:53], v[100:101]
	v_pk_fma_f32 v[102:103], v[28:29], v[60:61], v[102:103]
	v_pk_fma_f32 v[100:101], v[30:31], v[54:55], v[100:101]
	v_pk_fma_f32 v[102:103], v[30:31], v[62:63], v[102:103]
	v_pk_fma_f32 v[100:101], v[32:33], v[56:57], v[100:101]
	v_pk_fma_f32 v[102:103], v[32:33], v[64:65], v[102:103]
	v_add_f32_e32 v96, v96, v97
	v_add_f32_e32 v98, v98, v99
	v_add_f32_e32 v100, v100, v101
	v_add_f32_e32 v102, v102, v103
	s_waitcnt lgkmcnt(7)
	v_add_f32_dpp v96, v96, v96 quad_perm:[1,0,3,2] row_mask:0xf bank_mask:0xf bound_ctrl:1
	v_add_f32_dpp v98, v98, v98 quad_perm:[1,0,3,2] row_mask:0xf bank_mask:0xf bound_ctrl:1
	v_add_f32_dpp v100, v100, v100 quad_perm:[1,0,3,2] row_mask:0xf bank_mask:0xf bound_ctrl:1
	v_add_f32_dpp v102, v102, v102 quad_perm:[1,0,3,2] row_mask:0xf bank_mask:0xf bound_ctrl:1
	v_pk_mul_f32 v[104:105], v[82:83], v[92:93] op_sel_hi:[1,0]
	v_pk_mul_f32 v[106:107], v[84:85], v[92:93] op_sel_hi:[1,0]
	v_pk_mul_f32 v[108:109], v[86:87], v[92:93] op_sel_hi:[1,0]
	v_pk_mul_f32 v[110:111], v[88:89], v[92:93] op_sel_hi:[1,0]
	v_add_f32_dpp v96, v96, v96 quad_perm:[2,3,0,1] row_mask:0xf bank_mask:0xf bound_ctrl:1
	v_add_f32_dpp v98, v98, v98 quad_perm:[2,3,0,1] row_mask:0xf bank_mask:0xf bound_ctrl:1
	v_add_f32_dpp v100, v100, v100 quad_perm:[2,3,0,1] row_mask:0xf bank_mask:0xf bound_ctrl:1
	v_add_f32_dpp v102, v102, v102 quad_perm:[2,3,0,1] row_mask:0xf bank_mask:0xf bound_ctrl:1
	v_pk_mul_f32 v[112:113], v[82:83], v[92:93] op_sel:[0,1] op_sel_hi:[1,1]
	v_pk_mul_f32 v[114:115], v[84:85], v[92:93] op_sel:[0,1] op_sel_hi:[1,1]
	v_pk_mul_f32 v[116:117], v[86:87], v[92:93] op_sel:[0,1] op_sel_hi:[1,1]
	v_pk_mul_f32 v[118:119], v[88:89], v[92:93] op_sel:[0,1] op_sel_hi:[1,1]
	ds_read_b128 v[82:85], v127 offset:23168
	ds_read_b128 v[86:89], v127 offset:23184
	v_add_f32_dpp v96, v96, v96 row_half_mirror row_mask:0xf bank_mask:0xf bound_ctrl:1
	v_add_f32_dpp v98, v98, v98 row_half_mirror row_mask:0xf bank_mask:0xf bound_ctrl:1
	v_add_f32_dpp v100, v100, v100 row_half_mirror row_mask:0xf bank_mask:0xf bound_ctrl:1
	v_add_f32_dpp v102, v102, v102 row_half_mirror row_mask:0xf bank_mask:0xf bound_ctrl:1
	v_pk_fma_f32 v[104:105], v[18:19], v[66:67], v[104:105]
	v_pk_fma_f32 v[106:107], v[20:21], v[68:69], v[106:107]
	v_pk_fma_f32 v[108:109], v[22:23], v[70:71], v[108:109]
	v_pk_fma_f32 v[110:111], v[24:25], v[72:73], v[110:111]
	v_pk_fma_f32 v[112:113], v[26:27], v[66:67], v[112:113]
	v_pk_fma_f32 v[114:115], v[28:29], v[68:69], v[114:115]
	v_pk_fma_f32 v[116:117], v[30:31], v[70:71], v[116:117]
	v_pk_fma_f32 v[118:119], v[32:33], v[72:73], v[118:119]
	ds_read_b128 v[66:69], v127 offset:22656
	ds_read_b128 v[70:73], v127 offset:22672
	ds_read_b32 v90, v128 offset:22400
	ds_read_b32 v91, v128 offset:22432
	s_waitcnt lgkmcnt(6)
	v_pk_fma_f32 v[18:19], v[96:97], v[74:75], v[104:105] op_sel_hi:[0,1,1]
	v_pk_fma_f32 v[20:21], v[96:97], v[76:77], v[106:107] op_sel_hi:[0,1,1]
	v_pk_fma_f32 v[22:23], v[96:97], v[78:79], v[108:109] op_sel_hi:[0,1,1]
	v_pk_fma_f32 v[24:25], v[96:97], v[80:81], v[110:111] op_sel_hi:[0,1,1]
	v_pk_fma_f32 v[26:27], v[100:101], v[74:75], v[112:113] op_sel_hi:[0,1,1]
	v_pk_fma_f32 v[28:29], v[100:101], v[76:77], v[114:115] op_sel_hi:[0,1,1]
	v_pk_fma_f32 v[30:31], v[100:101], v[78:79], v[116:117] op_sel_hi:[0,1,1]
	v_pk_fma_f32 v[32:33], v[100:101], v[80:81], v[118:119] op_sel_hi:[0,1,1]
	v_fma_f32 v124, v92, v95, v98
	v_fma_f32 v125, v93, v95, v102
	v_fma_f32 v120, v96, v94, v124
	v_fma_f32 v122, v100, v94, v125
	v_mov_b32_dpp v120, v121 row_shr:1 row_mask:0xf bank_mask:0x3
	v_mov_b32_dpp v120, v121 row_shl:1 row_mask:0xf bank_mask:0xc
	v_mov_b32_dpp v122, v123 row_shr:1 row_mask:0xf bank_mask:0x3
	v_mov_b32_dpp v122, v123 row_shl:1 row_mask:0xf bank_mask:0xc
	ds_read_b128 v[50:53], v127 offset:24000
	ds_read_b128 v[54:57], v127 offset:24016
	ds_read_b128 v[58:61], v127 offset:25024
	ds_read_b128 v[62:65], v127 offset:25040
	ds_read_b128 v[74:77], v127 offset:22912
	ds_read_b128 v[78:81], v127 offset:22928
	ds_read_b64 v[94:95], v129 offset:22400
	v_pk_mul_f32 v[96:97], v[18:19], v[34:35]
	v_pk_mul_f32 v[98:99], v[18:19], v[42:43]
	v_pk_fma_f32 v[96:97], v[20:21], v[36:37], v[96:97]
	v_pk_fma_f32 v[98:99], v[20:21], v[44:45], v[98:99]
	v_pk_fma_f32 v[96:97], v[22:23], v[38:39], v[96:97]
	v_pk_fma_f32 v[98:99], v[22:23], v[46:47], v[98:99]
	v_pk_fma_f32 v[96:97], v[24:25], v[40:41], v[96:97]
	v_pk_fma_f32 v[98:99], v[24:25], v[48:49], v[98:99]
	v_pk_mul_f32 v[100:101], v[26:27], v[34:35]
	v_pk_mul_f32 v[102:103], v[26:27], v[42:43]
	v_pk_fma_f32 v[100:101], v[28:29], v[36:37], v[100:101]
	v_pk_fma_f32 v[102:103], v[28:29], v[44:45], v[102:103]
	v_pk_fma_f32 v[100:101], v[30:31], v[38:39], v[100:101]
	v_pk_fma_f32 v[102:103], v[30:31], v[46:47], v[102:103]
	v_pk_fma_f32 v[100:101], v[32:33], v[40:41], v[100:101]
	v_pk_fma_f32 v[102:103], v[32:33], v[48:49], v[102:103]
	v_add_f32_e32 v96, v96, v97
	v_add_f32_e32 v98, v98, v99
	v_add_f32_e32 v100, v100, v101
	v_add_f32_e32 v102, v102, v103
	s_waitcnt lgkmcnt(7)
	v_add_f32_dpp v96, v96, v96 quad_perm:[1,0,3,2] row_mask:0xf bank_mask:0xf bound_ctrl:1
	v_add_f32_dpp v98, v98, v98 quad_perm:[1,0,3,2] row_mask:0xf bank_mask:0xf bound_ctrl:1
	v_add_f32_dpp v100, v100, v100 quad_perm:[1,0,3,2] row_mask:0xf bank_mask:0xf bound_ctrl:1
	v_add_f32_dpp v102, v102, v102 quad_perm:[1,0,3,2] row_mask:0xf bank_mask:0xf bound_ctrl:1
	v_pk_mul_f32 v[104:105], v[82:83], v[90:91] op_sel_hi:[1,0]
	v_pk_mul_f32 v[106:107], v[84:85], v[90:91] op_sel_hi:[1,0]
	v_pk_mul_f32 v[108:109], v[86:87], v[90:91] op_sel_hi:[1,0]
	v_pk_mul_f32 v[110:111], v[88:89], v[90:91] op_sel_hi:[1,0]
	v_add_f32_dpp v96, v96, v96 quad_perm:[2,3,0,1] row_mask:0xf bank_mask:0xf bound_ctrl:1
	v_add_f32_dpp v98, v98, v98 quad_perm:[2,3,0,1] row_mask:0xf bank_mask:0xf bound_ctrl:1
	v_add_f32_dpp v100, v100, v100 quad_perm:[2,3,0,1] row_mask:0xf bank_mask:0xf bound_ctrl:1
	v_add_f32_dpp v102, v102, v102 quad_perm:[2,3,0,1] row_mask:0xf bank_mask:0xf bound_ctrl:1
	v_pk_mul_f32 v[112:113], v[82:83], v[90:91] op_sel:[0,1] op_sel_hi:[1,1]
	v_pk_mul_f32 v[114:115], v[84:85], v[90:91] op_sel:[0,1] op_sel_hi:[1,1]
	v_pk_mul_f32 v[116:117], v[86:87], v[90:91] op_sel:[0,1] op_sel_hi:[1,1]
	v_pk_mul_f32 v[118:119], v[88:89], v[90:91] op_sel:[0,1] op_sel_hi:[1,1]
	ds_read_b128 v[82:85], v127 offset:24768
	ds_read_b128 v[86:89], v127 offset:24784
	v_add_f32_dpp v96, v96, v96 row_half_mirror row_mask:0xf bank_mask:0xf bound_ctrl:1
	v_add_f32_dpp v98, v98, v98 row_half_mirror row_mask:0xf bank_mask:0xf bound_ctrl:1
	v_add_f32_dpp v100, v100, v100 row_half_mirror row_mask:0xf bank_mask:0xf bound_ctrl:1
	v_add_f32_dpp v102, v102, v102 row_half_mirror row_mask:0xf bank_mask:0xf bound_ctrl:1
	v_pk_fma_f32 v[104:105], v[18:19], v[66:67], v[104:105]
	v_pk_fma_f32 v[106:107], v[20:21], v[68:69], v[106:107]
	v_pk_fma_f32 v[108:109], v[22:23], v[70:71], v[108:109]
	v_pk_fma_f32 v[110:111], v[24:25], v[72:73], v[110:111]
	v_pk_fma_f32 v[112:113], v[26:27], v[66:67], v[112:113]
	v_pk_fma_f32 v[114:115], v[28:29], v[68:69], v[114:115]
	v_pk_fma_f32 v[116:117], v[30:31], v[70:71], v[116:117]
	v_pk_fma_f32 v[118:119], v[32:33], v[72:73], v[118:119]
	ds_read_b128 v[66:69], v127 offset:24256
	ds_read_b128 v[70:73], v127 offset:24272
	ds_read_b32 v92, v128 offset:24000
	ds_read_b32 v93, v128 offset:24032
	s_waitcnt lgkmcnt(6)
	v_pk_fma_f32 v[18:19], v[96:97], v[74:75], v[104:105] op_sel_hi:[0,1,1]
	v_pk_fma_f32 v[20:21], v[96:97], v[76:77], v[106:107] op_sel_hi:[0,1,1]
	v_pk_fma_f32 v[22:23], v[96:97], v[78:79], v[108:109] op_sel_hi:[0,1,1]
	v_pk_fma_f32 v[24:25], v[96:97], v[80:81], v[110:111] op_sel_hi:[0,1,1]
	v_pk_fma_f32 v[26:27], v[100:101], v[74:75], v[112:113] op_sel_hi:[0,1,1]
	v_pk_fma_f32 v[28:29], v[100:101], v[76:77], v[114:115] op_sel_hi:[0,1,1]
	v_pk_fma_f32 v[30:31], v[100:101], v[78:79], v[116:117] op_sel_hi:[0,1,1]
	v_pk_fma_f32 v[32:33], v[100:101], v[80:81], v[118:119] op_sel_hi:[0,1,1]
	v_fma_f32 v124, v90, v95, v98
	v_fma_f32 v125, v91, v95, v102
	v_fma_f32 v121, v96, v94, v124
	v_fma_f32 v123, v100, v94, v125
	v_mov_b32_dpp v121, v120 row_shr:1 row_mask:0xf bank_mask:0x3
	v_mov_b32_dpp v121, v120 row_shl:1 row_mask:0xf bank_mask:0xc
	v_mov_b32_dpp v123, v122 row_shr:1 row_mask:0xf bank_mask:0x3
	v_mov_b32_dpp v123, v122 row_shl:1 row_mask:0xf bank_mask:0xc
	ds_read_b128 v[34:37], v127 offset:25600
	ds_read_b128 v[38:41], v127 offset:25616
	ds_read_b128 v[42:45], v127 offset:26624
	ds_read_b128 v[46:49], v127 offset:26640
	ds_read_b128 v[74:77], v127 offset:24512
	ds_read_b128 v[78:81], v127 offset:24528
	ds_read_b64 v[94:95], v129 offset:24000
	v_pk_mul_f32 v[96:97], v[18:19], v[50:51]
	v_pk_mul_f32 v[98:99], v[18:19], v[58:59]
	v_pk_fma_f32 v[96:97], v[20:21], v[52:53], v[96:97]
	v_pk_fma_f32 v[98:99], v[20:21], v[60:61], v[98:99]
	v_pk_fma_f32 v[96:97], v[22:23], v[54:55], v[96:97]
	v_pk_fma_f32 v[98:99], v[22:23], v[62:63], v[98:99]
	v_pk_fma_f32 v[96:97], v[24:25], v[56:57], v[96:97]
	v_pk_fma_f32 v[98:99], v[24:25], v[64:65], v[98:99]
	v_pk_mul_f32 v[100:101], v[26:27], v[50:51]
	v_pk_mul_f32 v[102:103], v[26:27], v[58:59]
	v_pk_fma_f32 v[100:101], v[28:29], v[52:53], v[100:101]
	v_pk_fma_f32 v[102:103], v[28:29], v[60:61], v[102:103]
	v_pk_fma_f32 v[100:101], v[30:31], v[54:55], v[100:101]
	v_pk_fma_f32 v[102:103], v[30:31], v[62:63], v[102:103]
	v_pk_fma_f32 v[100:101], v[32:33], v[56:57], v[100:101]
	v_pk_fma_f32 v[102:103], v[32:33], v[64:65], v[102:103]
	v_add_f32_e32 v96, v96, v97
	v_add_f32_e32 v98, v98, v99
	v_add_f32_e32 v100, v100, v101
	v_add_f32_e32 v102, v102, v103
	s_waitcnt lgkmcnt(7)
	v_add_f32_dpp v96, v96, v96 quad_perm:[1,0,3,2] row_mask:0xf bank_mask:0xf bound_ctrl:1
	v_add_f32_dpp v98, v98, v98 quad_perm:[1,0,3,2] row_mask:0xf bank_mask:0xf bound_ctrl:1
	v_add_f32_dpp v100, v100, v100 quad_perm:[1,0,3,2] row_mask:0xf bank_mask:0xf bound_ctrl:1
	v_add_f32_dpp v102, v102, v102 quad_perm:[1,0,3,2] row_mask:0xf bank_mask:0xf bound_ctrl:1
	v_pk_mul_f32 v[104:105], v[82:83], v[92:93] op_sel_hi:[1,0]
	v_pk_mul_f32 v[106:107], v[84:85], v[92:93] op_sel_hi:[1,0]
	v_pk_mul_f32 v[108:109], v[86:87], v[92:93] op_sel_hi:[1,0]
	v_pk_mul_f32 v[110:111], v[88:89], v[92:93] op_sel_hi:[1,0]
	v_add_f32_dpp v96, v96, v96 quad_perm:[2,3,0,1] row_mask:0xf bank_mask:0xf bound_ctrl:1
	v_add_f32_dpp v98, v98, v98 quad_perm:[2,3,0,1] row_mask:0xf bank_mask:0xf bound_ctrl:1
	v_add_f32_dpp v100, v100, v100 quad_perm:[2,3,0,1] row_mask:0xf bank_mask:0xf bound_ctrl:1
	v_add_f32_dpp v102, v102, v102 quad_perm:[2,3,0,1] row_mask:0xf bank_mask:0xf bound_ctrl:1
	v_pk_mul_f32 v[112:113], v[82:83], v[92:93] op_sel:[0,1] op_sel_hi:[1,1]
	v_pk_mul_f32 v[114:115], v[84:85], v[92:93] op_sel:[0,1] op_sel_hi:[1,1]
	v_pk_mul_f32 v[116:117], v[86:87], v[92:93] op_sel:[0,1] op_sel_hi:[1,1]
	v_pk_mul_f32 v[118:119], v[88:89], v[92:93] op_sel:[0,1] op_sel_hi:[1,1]
	ds_read_b128 v[82:85], v127 offset:26368
	ds_read_b128 v[86:89], v127 offset:26384
	v_add_f32_dpp v96, v96, v96 row_half_mirror row_mask:0xf bank_mask:0xf bound_ctrl:1
	v_add_f32_dpp v98, v98, v98 row_half_mirror row_mask:0xf bank_mask:0xf bound_ctrl:1
	v_add_f32_dpp v100, v100, v100 row_half_mirror row_mask:0xf bank_mask:0xf bound_ctrl:1
	v_add_f32_dpp v102, v102, v102 row_half_mirror row_mask:0xf bank_mask:0xf bound_ctrl:1
	v_pk_fma_f32 v[104:105], v[18:19], v[66:67], v[104:105]
	v_pk_fma_f32 v[106:107], v[20:21], v[68:69], v[106:107]
	v_pk_fma_f32 v[108:109], v[22:23], v[70:71], v[108:109]
	v_pk_fma_f32 v[110:111], v[24:25], v[72:73], v[110:111]
	v_pk_fma_f32 v[112:113], v[26:27], v[66:67], v[112:113]
	v_pk_fma_f32 v[114:115], v[28:29], v[68:69], v[114:115]
	v_pk_fma_f32 v[116:117], v[30:31], v[70:71], v[116:117]
	v_pk_fma_f32 v[118:119], v[32:33], v[72:73], v[118:119]
	ds_read_b128 v[66:69], v127 offset:25856
	ds_read_b128 v[70:73], v127 offset:25872
	ds_read_b32 v90, v128 offset:25600
	ds_read_b32 v91, v128 offset:25632
	s_waitcnt lgkmcnt(6)
	v_pk_fma_f32 v[18:19], v[96:97], v[74:75], v[104:105] op_sel_hi:[0,1,1]
	v_pk_fma_f32 v[20:21], v[96:97], v[76:77], v[106:107] op_sel_hi:[0,1,1]
	v_pk_fma_f32 v[22:23], v[96:97], v[78:79], v[108:109] op_sel_hi:[0,1,1]
	v_pk_fma_f32 v[24:25], v[96:97], v[80:81], v[110:111] op_sel_hi:[0,1,1]
	v_pk_fma_f32 v[26:27], v[100:101], v[74:75], v[112:113] op_sel_hi:[0,1,1]
	v_pk_fma_f32 v[28:29], v[100:101], v[76:77], v[114:115] op_sel_hi:[0,1,1]
	v_pk_fma_f32 v[30:31], v[100:101], v[78:79], v[116:117] op_sel_hi:[0,1,1]
	v_pk_fma_f32 v[32:33], v[100:101], v[80:81], v[118:119] op_sel_hi:[0,1,1]
	v_fma_f32 v124, v92, v95, v98
	v_fma_f32 v125, v93, v95, v102
	v_fma_f32 v120, v96, v94, v124
	v_fma_f32 v122, v100, v94, v125
	v_mov_b32_dpp v120, v121 row_shr:1 row_mask:0xf bank_mask:0x3
	v_mov_b32_dpp v120, v121 row_shl:1 row_mask:0xf bank_mask:0xc
	v_mov_b32_dpp v122, v123 row_shr:1 row_mask:0xf bank_mask:0x3
	v_mov_b32_dpp v122, v123 row_shl:1 row_mask:0xf bank_mask:0xc
	v_cvt_pk_bf16_f32 v126, v120, v120
	v_cvt_pk_bf16_f32 v139, v122, v122
	global_store_short v[130:131], v126, off
	global_store_short v[130:131], v139, off offset:16
	v_lshl_add_u64 v[130:131], v[130:131], 0, v[132:133]
	ds_read_b128 v[50:53], v127 offset:27200
	ds_read_b128 v[54:57], v127 offset:27216
	ds_read_b128 v[58:61], v127 offset:28224
	ds_read_b128 v[62:65], v127 offset:28240
	ds_read_b128 v[74:77], v127 offset:26112
	ds_read_b128 v[78:81], v127 offset:26128
	ds_read_b64 v[94:95], v129 offset:25600
	v_pk_mul_f32 v[96:97], v[18:19], v[34:35]
	v_pk_mul_f32 v[98:99], v[18:19], v[42:43]
	v_pk_fma_f32 v[96:97], v[20:21], v[36:37], v[96:97]
	v_pk_fma_f32 v[98:99], v[20:21], v[44:45], v[98:99]
	v_pk_fma_f32 v[96:97], v[22:23], v[38:39], v[96:97]
	v_pk_fma_f32 v[98:99], v[22:23], v[46:47], v[98:99]
	v_pk_fma_f32 v[96:97], v[24:25], v[40:41], v[96:97]
	v_pk_fma_f32 v[98:99], v[24:25], v[48:49], v[98:99]
	v_pk_mul_f32 v[100:101], v[26:27], v[34:35]
	v_pk_mul_f32 v[102:103], v[26:27], v[42:43]
	v_pk_fma_f32 v[100:101], v[28:29], v[36:37], v[100:101]
	v_pk_fma_f32 v[102:103], v[28:29], v[44:45], v[102:103]
	v_pk_fma_f32 v[100:101], v[30:31], v[38:39], v[100:101]
	v_pk_fma_f32 v[102:103], v[30:31], v[46:47], v[102:103]
	v_pk_fma_f32 v[100:101], v[32:33], v[40:41], v[100:101]
	v_pk_fma_f32 v[102:103], v[32:33], v[48:49], v[102:103]
	v_add_f32_e32 v96, v96, v97
	v_add_f32_e32 v98, v98, v99
	v_add_f32_e32 v100, v100, v101
	v_add_f32_e32 v102, v102, v103
	s_waitcnt lgkmcnt(7)
	v_add_f32_dpp v96, v96, v96 quad_perm:[1,0,3,2] row_mask:0xf bank_mask:0xf bound_ctrl:1
	v_add_f32_dpp v98, v98, v98 quad_perm:[1,0,3,2] row_mask:0xf bank_mask:0xf bound_ctrl:1
	v_add_f32_dpp v100, v100, v100 quad_perm:[1,0,3,2] row_mask:0xf bank_mask:0xf bound_ctrl:1
	v_add_f32_dpp v102, v102, v102 quad_perm:[1,0,3,2] row_mask:0xf bank_mask:0xf bound_ctrl:1
	v_pk_mul_f32 v[104:105], v[82:83], v[90:91] op_sel_hi:[1,0]
	v_pk_mul_f32 v[106:107], v[84:85], v[90:91] op_sel_hi:[1,0]
	v_pk_mul_f32 v[108:109], v[86:87], v[90:91] op_sel_hi:[1,0]
	v_pk_mul_f32 v[110:111], v[88:89], v[90:91] op_sel_hi:[1,0]
	v_add_f32_dpp v96, v96, v96 quad_perm:[2,3,0,1] row_mask:0xf bank_mask:0xf bound_ctrl:1
	v_add_f32_dpp v98, v98, v98 quad_perm:[2,3,0,1] row_mask:0xf bank_mask:0xf bound_ctrl:1
	v_add_f32_dpp v100, v100, v100 quad_perm:[2,3,0,1] row_mask:0xf bank_mask:0xf bound_ctrl:1
	v_add_f32_dpp v102, v102, v102 quad_perm:[2,3,0,1] row_mask:0xf bank_mask:0xf bound_ctrl:1
	v_pk_mul_f32 v[112:113], v[82:83], v[90:91] op_sel:[0,1] op_sel_hi:[1,1]
	v_pk_mul_f32 v[114:115], v[84:85], v[90:91] op_sel:[0,1] op_sel_hi:[1,1]
	v_pk_mul_f32 v[116:117], v[86:87], v[90:91] op_sel:[0,1] op_sel_hi:[1,1]
	v_pk_mul_f32 v[118:119], v[88:89], v[90:91] op_sel:[0,1] op_sel_hi:[1,1]
	ds_read_b128 v[82:85], v127 offset:27968
	ds_read_b128 v[86:89], v127 offset:27984
	v_add_f32_dpp v96, v96, v96 row_half_mirror row_mask:0xf bank_mask:0xf bound_ctrl:1
	v_add_f32_dpp v98, v98, v98 row_half_mirror row_mask:0xf bank_mask:0xf bound_ctrl:1
	v_add_f32_dpp v100, v100, v100 row_half_mirror row_mask:0xf bank_mask:0xf bound_ctrl:1
	v_add_f32_dpp v102, v102, v102 row_half_mirror row_mask:0xf bank_mask:0xf bound_ctrl:1
	v_pk_fma_f32 v[104:105], v[18:19], v[66:67], v[104:105]
	v_pk_fma_f32 v[106:107], v[20:21], v[68:69], v[106:107]
	v_pk_fma_f32 v[108:109], v[22:23], v[70:71], v[108:109]
	v_pk_fma_f32 v[110:111], v[24:25], v[72:73], v[110:111]
	v_pk_fma_f32 v[112:113], v[26:27], v[66:67], v[112:113]
	v_pk_fma_f32 v[114:115], v[28:29], v[68:69], v[114:115]
	v_pk_fma_f32 v[116:117], v[30:31], v[70:71], v[116:117]
	v_pk_fma_f32 v[118:119], v[32:33], v[72:73], v[118:119]
	ds_read_b128 v[66:69], v127 offset:27456
	ds_read_b128 v[70:73], v127 offset:27472
	ds_read_b32 v92, v128 offset:27200
	ds_read_b32 v93, v128 offset:27232
	s_waitcnt lgkmcnt(6)
	v_pk_fma_f32 v[18:19], v[96:97], v[74:75], v[104:105] op_sel_hi:[0,1,1]
	v_pk_fma_f32 v[20:21], v[96:97], v[76:77], v[106:107] op_sel_hi:[0,1,1]
	v_pk_fma_f32 v[22:23], v[96:97], v[78:79], v[108:109] op_sel_hi:[0,1,1]
	v_pk_fma_f32 v[24:25], v[96:97], v[80:81], v[110:111] op_sel_hi:[0,1,1]
	v_pk_fma_f32 v[26:27], v[100:101], v[74:75], v[112:113] op_sel_hi:[0,1,1]
	v_pk_fma_f32 v[28:29], v[100:101], v[76:77], v[114:115] op_sel_hi:[0,1,1]
	v_pk_fma_f32 v[30:31], v[100:101], v[78:79], v[116:117] op_sel_hi:[0,1,1]
	v_pk_fma_f32 v[32:33], v[100:101], v[80:81], v[118:119] op_sel_hi:[0,1,1]
	v_fma_f32 v124, v90, v95, v98
	v_fma_f32 v125, v91, v95, v102
	v_fma_f32 v121, v96, v94, v124
	v_fma_f32 v123, v100, v94, v125
	v_mov_b32_dpp v121, v120 row_shr:1 row_mask:0xf bank_mask:0x3
	v_mov_b32_dpp v121, v120 row_shl:1 row_mask:0xf bank_mask:0xc
	v_mov_b32_dpp v123, v122 row_shr:1 row_mask:0xf bank_mask:0x3
	v_mov_b32_dpp v123, v122 row_shl:1 row_mask:0xf bank_mask:0xc
	ds_read_b128 v[34:37], v127 offset:28800
	ds_read_b128 v[38:41], v127 offset:28816
	ds_read_b128 v[42:45], v127 offset:29824
	ds_read_b128 v[46:49], v127 offset:29840
	ds_read_b128 v[74:77], v127 offset:27712
	ds_read_b128 v[78:81], v127 offset:27728
	ds_read_b64 v[94:95], v129 offset:27200
	v_pk_mul_f32 v[96:97], v[18:19], v[50:51]
	v_pk_mul_f32 v[98:99], v[18:19], v[58:59]
	v_pk_fma_f32 v[96:97], v[20:21], v[52:53], v[96:97]
	v_pk_fma_f32 v[98:99], v[20:21], v[60:61], v[98:99]
	v_pk_fma_f32 v[96:97], v[22:23], v[54:55], v[96:97]
	v_pk_fma_f32 v[98:99], v[22:23], v[62:63], v[98:99]
	v_pk_fma_f32 v[96:97], v[24:25], v[56:57], v[96:97]
	v_pk_fma_f32 v[98:99], v[24:25], v[64:65], v[98:99]
	v_pk_mul_f32 v[100:101], v[26:27], v[50:51]
	v_pk_mul_f32 v[102:103], v[26:27], v[58:59]
	v_pk_fma_f32 v[100:101], v[28:29], v[52:53], v[100:101]
	v_pk_fma_f32 v[102:103], v[28:29], v[60:61], v[102:103]
	v_pk_fma_f32 v[100:101], v[30:31], v[54:55], v[100:101]
	v_pk_fma_f32 v[102:103], v[30:31], v[62:63], v[102:103]
	v_pk_fma_f32 v[100:101], v[32:33], v[56:57], v[100:101]
	v_pk_fma_f32 v[102:103], v[32:33], v[64:65], v[102:103]
	v_add_f32_e32 v96, v96, v97
	v_add_f32_e32 v98, v98, v99
	v_add_f32_e32 v100, v100, v101
	v_add_f32_e32 v102, v102, v103
	s_waitcnt lgkmcnt(7)
	v_add_f32_dpp v96, v96, v96 quad_perm:[1,0,3,2] row_mask:0xf bank_mask:0xf bound_ctrl:1
	v_add_f32_dpp v98, v98, v98 quad_perm:[1,0,3,2] row_mask:0xf bank_mask:0xf bound_ctrl:1
	v_add_f32_dpp v100, v100, v100 quad_perm:[1,0,3,2] row_mask:0xf bank_mask:0xf bound_ctrl:1
	v_add_f32_dpp v102, v102, v102 quad_perm:[1,0,3,2] row_mask:0xf bank_mask:0xf bound_ctrl:1
	v_pk_mul_f32 v[104:105], v[82:83], v[92:93] op_sel_hi:[1,0]
	v_pk_mul_f32 v[106:107], v[84:85], v[92:93] op_sel_hi:[1,0]
	v_pk_mul_f32 v[108:109], v[86:87], v[92:93] op_sel_hi:[1,0]
	v_pk_mul_f32 v[110:111], v[88:89], v[92:93] op_sel_hi:[1,0]
	v_add_f32_dpp v96, v96, v96 quad_perm:[2,3,0,1] row_mask:0xf bank_mask:0xf bound_ctrl:1
	v_add_f32_dpp v98, v98, v98 quad_perm:[2,3,0,1] row_mask:0xf bank_mask:0xf bound_ctrl:1
	v_add_f32_dpp v100, v100, v100 quad_perm:[2,3,0,1] row_mask:0xf bank_mask:0xf bound_ctrl:1
	v_add_f32_dpp v102, v102, v102 quad_perm:[2,3,0,1] row_mask:0xf bank_mask:0xf bound_ctrl:1
	v_pk_mul_f32 v[112:113], v[82:83], v[92:93] op_sel:[0,1] op_sel_hi:[1,1]
	v_pk_mul_f32 v[114:115], v[84:85], v[92:93] op_sel:[0,1] op_sel_hi:[1,1]
	v_pk_mul_f32 v[116:117], v[86:87], v[92:93] op_sel:[0,1] op_sel_hi:[1,1]
	v_pk_mul_f32 v[118:119], v[88:89], v[92:93] op_sel:[0,1] op_sel_hi:[1,1]
	ds_read_b128 v[82:85], v127 offset:29568
	ds_read_b128 v[86:89], v127 offset:29584
	v_add_f32_dpp v96, v96, v96 row_half_mirror row_mask:0xf bank_mask:0xf bound_ctrl:1
	v_add_f32_dpp v98, v98, v98 row_half_mirror row_mask:0xf bank_mask:0xf bound_ctrl:1
	v_add_f32_dpp v100, v100, v100 row_half_mirror row_mask:0xf bank_mask:0xf bound_ctrl:1
	v_add_f32_dpp v102, v102, v102 row_half_mirror row_mask:0xf bank_mask:0xf bound_ctrl:1
	v_pk_fma_f32 v[104:105], v[18:19], v[66:67], v[104:105]
	v_pk_fma_f32 v[106:107], v[20:21], v[68:69], v[106:107]
	v_pk_fma_f32 v[108:109], v[22:23], v[70:71], v[108:109]
	v_pk_fma_f32 v[110:111], v[24:25], v[72:73], v[110:111]
	v_pk_fma_f32 v[112:113], v[26:27], v[66:67], v[112:113]
	v_pk_fma_f32 v[114:115], v[28:29], v[68:69], v[114:115]
	v_pk_fma_f32 v[116:117], v[30:31], v[70:71], v[116:117]
	v_pk_fma_f32 v[118:119], v[32:33], v[72:73], v[118:119]
	ds_read_b128 v[66:69], v127 offset:29056
	ds_read_b128 v[70:73], v127 offset:29072
	ds_read_b32 v90, v128 offset:28800
	ds_read_b32 v91, v128 offset:28832
	s_waitcnt lgkmcnt(6)
	v_pk_fma_f32 v[18:19], v[96:97], v[74:75], v[104:105] op_sel_hi:[0,1,1]
	v_pk_fma_f32 v[20:21], v[96:97], v[76:77], v[106:107] op_sel_hi:[0,1,1]
	v_pk_fma_f32 v[22:23], v[96:97], v[78:79], v[108:109] op_sel_hi:[0,1,1]
	v_pk_fma_f32 v[24:25], v[96:97], v[80:81], v[110:111] op_sel_hi:[0,1,1]
	v_pk_fma_f32 v[26:27], v[100:101], v[74:75], v[112:113] op_sel_hi:[0,1,1]
	v_pk_fma_f32 v[28:29], v[100:101], v[76:77], v[114:115] op_sel_hi:[0,1,1]
	v_pk_fma_f32 v[30:31], v[100:101], v[78:79], v[116:117] op_sel_hi:[0,1,1]
	v_pk_fma_f32 v[32:33], v[100:101], v[80:81], v[118:119] op_sel_hi:[0,1,1]
	v_fma_f32 v124, v92, v95, v98
	v_fma_f32 v125, v93, v95, v102
	v_fma_f32 v120, v96, v94, v124
	v_fma_f32 v122, v100, v94, v125
	v_mov_b32_dpp v120, v121 row_shr:1 row_mask:0xf bank_mask:0x3
	v_mov_b32_dpp v120, v121 row_shl:1 row_mask:0xf bank_mask:0xc
	v_mov_b32_dpp v122, v123 row_shr:1 row_mask:0xf bank_mask:0x3
	v_mov_b32_dpp v122, v123 row_shl:1 row_mask:0xf bank_mask:0xc
	ds_read_b128 v[50:53], v127 offset:30400
	ds_read_b128 v[54:57], v127 offset:30416
	ds_read_b128 v[58:61], v127 offset:31424
	ds_read_b128 v[62:65], v127 offset:31440
	ds_read_b128 v[74:77], v127 offset:29312
	ds_read_b128 v[78:81], v127 offset:29328
	ds_read_b64 v[94:95], v129 offset:28800
	v_pk_mul_f32 v[96:97], v[18:19], v[34:35]
	v_pk_mul_f32 v[98:99], v[18:19], v[42:43]
	v_pk_fma_f32 v[96:97], v[20:21], v[36:37], v[96:97]
	v_pk_fma_f32 v[98:99], v[20:21], v[44:45], v[98:99]
	v_pk_fma_f32 v[96:97], v[22:23], v[38:39], v[96:97]
	v_pk_fma_f32 v[98:99], v[22:23], v[46:47], v[98:99]
	v_pk_fma_f32 v[96:97], v[24:25], v[40:41], v[96:97]
	v_pk_fma_f32 v[98:99], v[24:25], v[48:49], v[98:99]
	v_pk_mul_f32 v[100:101], v[26:27], v[34:35]
	v_pk_mul_f32 v[102:103], v[26:27], v[42:43]
	v_pk_fma_f32 v[100:101], v[28:29], v[36:37], v[100:101]
	v_pk_fma_f32 v[102:103], v[28:29], v[44:45], v[102:103]
	v_pk_fma_f32 v[100:101], v[30:31], v[38:39], v[100:101]
	v_pk_fma_f32 v[102:103], v[30:31], v[46:47], v[102:103]
	v_pk_fma_f32 v[100:101], v[32:33], v[40:41], v[100:101]
	v_pk_fma_f32 v[102:103], v[32:33], v[48:49], v[102:103]
	v_add_f32_e32 v96, v96, v97
	v_add_f32_e32 v98, v98, v99
	v_add_f32_e32 v100, v100, v101
	v_add_f32_e32 v102, v102, v103
	s_waitcnt lgkmcnt(7)
	v_add_f32_dpp v96, v96, v96 quad_perm:[1,0,3,2] row_mask:0xf bank_mask:0xf bound_ctrl:1
	v_add_f32_dpp v98, v98, v98 quad_perm:[1,0,3,2] row_mask:0xf bank_mask:0xf bound_ctrl:1
	v_add_f32_dpp v100, v100, v100 quad_perm:[1,0,3,2] row_mask:0xf bank_mask:0xf bound_ctrl:1
	v_add_f32_dpp v102, v102, v102 quad_perm:[1,0,3,2] row_mask:0xf bank_mask:0xf bound_ctrl:1
	v_pk_mul_f32 v[104:105], v[82:83], v[90:91] op_sel_hi:[1,0]
	v_pk_mul_f32 v[106:107], v[84:85], v[90:91] op_sel_hi:[1,0]
	v_pk_mul_f32 v[108:109], v[86:87], v[90:91] op_sel_hi:[1,0]
	v_pk_mul_f32 v[110:111], v[88:89], v[90:91] op_sel_hi:[1,0]
	v_add_f32_dpp v96, v96, v96 quad_perm:[2,3,0,1] row_mask:0xf bank_mask:0xf bound_ctrl:1
	v_add_f32_dpp v98, v98, v98 quad_perm:[2,3,0,1] row_mask:0xf bank_mask:0xf bound_ctrl:1
	v_add_f32_dpp v100, v100, v100 quad_perm:[2,3,0,1] row_mask:0xf bank_mask:0xf bound_ctrl:1
	v_add_f32_dpp v102, v102, v102 quad_perm:[2,3,0,1] row_mask:0xf bank_mask:0xf bound_ctrl:1
	v_pk_mul_f32 v[112:113], v[82:83], v[90:91] op_sel:[0,1] op_sel_hi:[1,1]
	v_pk_mul_f32 v[114:115], v[84:85], v[90:91] op_sel:[0,1] op_sel_hi:[1,1]
	v_pk_mul_f32 v[116:117], v[86:87], v[90:91] op_sel:[0,1] op_sel_hi:[1,1]
	v_pk_mul_f32 v[118:119], v[88:89], v[90:91] op_sel:[0,1] op_sel_hi:[1,1]
	ds_read_b128 v[82:85], v127 offset:31168
	ds_read_b128 v[86:89], v127 offset:31184
	v_add_f32_dpp v96, v96, v96 row_half_mirror row_mask:0xf bank_mask:0xf bound_ctrl:1
	v_add_f32_dpp v98, v98, v98 row_half_mirror row_mask:0xf bank_mask:0xf bound_ctrl:1
	v_add_f32_dpp v100, v100, v100 row_half_mirror row_mask:0xf bank_mask:0xf bound_ctrl:1
	v_add_f32_dpp v102, v102, v102 row_half_mirror row_mask:0xf bank_mask:0xf bound_ctrl:1
	v_pk_fma_f32 v[104:105], v[18:19], v[66:67], v[104:105]
	v_pk_fma_f32 v[106:107], v[20:21], v[68:69], v[106:107]
	v_pk_fma_f32 v[108:109], v[22:23], v[70:71], v[108:109]
	v_pk_fma_f32 v[110:111], v[24:25], v[72:73], v[110:111]
	v_pk_fma_f32 v[112:113], v[26:27], v[66:67], v[112:113]
	v_pk_fma_f32 v[114:115], v[28:29], v[68:69], v[114:115]
	v_pk_fma_f32 v[116:117], v[30:31], v[70:71], v[116:117]
	v_pk_fma_f32 v[118:119], v[32:33], v[72:73], v[118:119]
	ds_read_b128 v[66:69], v127 offset:30656
	ds_read_b128 v[70:73], v127 offset:30672
	ds_read_b32 v92, v128 offset:30400
	ds_read_b32 v93, v128 offset:30432
	s_waitcnt lgkmcnt(6)
	v_pk_fma_f32 v[18:19], v[96:97], v[74:75], v[104:105] op_sel_hi:[0,1,1]
	v_pk_fma_f32 v[20:21], v[96:97], v[76:77], v[106:107] op_sel_hi:[0,1,1]
	v_pk_fma_f32 v[22:23], v[96:97], v[78:79], v[108:109] op_sel_hi:[0,1,1]
	v_pk_fma_f32 v[24:25], v[96:97], v[80:81], v[110:111] op_sel_hi:[0,1,1]
	v_pk_fma_f32 v[26:27], v[100:101], v[74:75], v[112:113] op_sel_hi:[0,1,1]
	v_pk_fma_f32 v[28:29], v[100:101], v[76:77], v[114:115] op_sel_hi:[0,1,1]
	v_pk_fma_f32 v[30:31], v[100:101], v[78:79], v[116:117] op_sel_hi:[0,1,1]
	v_pk_fma_f32 v[32:33], v[100:101], v[80:81], v[118:119] op_sel_hi:[0,1,1]
	v_fma_f32 v124, v90, v95, v98
	v_fma_f32 v125, v91, v95, v102
	v_fma_f32 v121, v96, v94, v124
	v_fma_f32 v123, v100, v94, v125
	v_mov_b32_dpp v121, v120 row_shr:1 row_mask:0xf bank_mask:0x3
	v_mov_b32_dpp v121, v120 row_shl:1 row_mask:0xf bank_mask:0xc
	v_mov_b32_dpp v123, v122 row_shr:1 row_mask:0xf bank_mask:0x3
	v_mov_b32_dpp v123, v122 row_shl:1 row_mask:0xf bank_mask:0xc
	ds_read_b128 v[34:37], v127 offset:32000
	ds_read_b128 v[38:41], v127 offset:32016
	ds_read_b128 v[42:45], v127 offset:33024
	ds_read_b128 v[46:49], v127 offset:33040
	ds_read_b128 v[74:77], v127 offset:30912
	ds_read_b128 v[78:81], v127 offset:30928
	ds_read_b64 v[94:95], v129 offset:30400
	v_pk_mul_f32 v[96:97], v[18:19], v[50:51]
	v_pk_mul_f32 v[98:99], v[18:19], v[58:59]
	v_pk_fma_f32 v[96:97], v[20:21], v[52:53], v[96:97]
	v_pk_fma_f32 v[98:99], v[20:21], v[60:61], v[98:99]
	v_pk_fma_f32 v[96:97], v[22:23], v[54:55], v[96:97]
	v_pk_fma_f32 v[98:99], v[22:23], v[62:63], v[98:99]
	v_pk_fma_f32 v[96:97], v[24:25], v[56:57], v[96:97]
	v_pk_fma_f32 v[98:99], v[24:25], v[64:65], v[98:99]
	v_pk_mul_f32 v[100:101], v[26:27], v[50:51]
	v_pk_mul_f32 v[102:103], v[26:27], v[58:59]
	v_pk_fma_f32 v[100:101], v[28:29], v[52:53], v[100:101]
	v_pk_fma_f32 v[102:103], v[28:29], v[60:61], v[102:103]
	v_pk_fma_f32 v[100:101], v[30:31], v[54:55], v[100:101]
	v_pk_fma_f32 v[102:103], v[30:31], v[62:63], v[102:103]
	v_pk_fma_f32 v[100:101], v[32:33], v[56:57], v[100:101]
	v_pk_fma_f32 v[102:103], v[32:33], v[64:65], v[102:103]
	v_add_f32_e32 v96, v96, v97
	v_add_f32_e32 v98, v98, v99
	v_add_f32_e32 v100, v100, v101
	v_add_f32_e32 v102, v102, v103
	s_waitcnt lgkmcnt(7)
	v_add_f32_dpp v96, v96, v96 quad_perm:[1,0,3,2] row_mask:0xf bank_mask:0xf bound_ctrl:1
	v_add_f32_dpp v98, v98, v98 quad_perm:[1,0,3,2] row_mask:0xf bank_mask:0xf bound_ctrl:1
	v_add_f32_dpp v100, v100, v100 quad_perm:[1,0,3,2] row_mask:0xf bank_mask:0xf bound_ctrl:1
	v_add_f32_dpp v102, v102, v102 quad_perm:[1,0,3,2] row_mask:0xf bank_mask:0xf bound_ctrl:1
	v_pk_mul_f32 v[104:105], v[82:83], v[92:93] op_sel_hi:[1,0]
	v_pk_mul_f32 v[106:107], v[84:85], v[92:93] op_sel_hi:[1,0]
	v_pk_mul_f32 v[108:109], v[86:87], v[92:93] op_sel_hi:[1,0]
	v_pk_mul_f32 v[110:111], v[88:89], v[92:93] op_sel_hi:[1,0]
	v_add_f32_dpp v96, v96, v96 quad_perm:[2,3,0,1] row_mask:0xf bank_mask:0xf bound_ctrl:1
	v_add_f32_dpp v98, v98, v98 quad_perm:[2,3,0,1] row_mask:0xf bank_mask:0xf bound_ctrl:1
	v_add_f32_dpp v100, v100, v100 quad_perm:[2,3,0,1] row_mask:0xf bank_mask:0xf bound_ctrl:1
	v_add_f32_dpp v102, v102, v102 quad_perm:[2,3,0,1] row_mask:0xf bank_mask:0xf bound_ctrl:1
	v_pk_mul_f32 v[112:113], v[82:83], v[92:93] op_sel:[0,1] op_sel_hi:[1,1]
	v_pk_mul_f32 v[114:115], v[84:85], v[92:93] op_sel:[0,1] op_sel_hi:[1,1]
	v_pk_mul_f32 v[116:117], v[86:87], v[92:93] op_sel:[0,1] op_sel_hi:[1,1]
	v_pk_mul_f32 v[118:119], v[88:89], v[92:93] op_sel:[0,1] op_sel_hi:[1,1]
	ds_read_b128 v[82:85], v127 offset:32768
	ds_read_b128 v[86:89], v127 offset:32784
	v_add_f32_dpp v96, v96, v96 row_half_mirror row_mask:0xf bank_mask:0xf bound_ctrl:1
	v_add_f32_dpp v98, v98, v98 row_half_mirror row_mask:0xf bank_mask:0xf bound_ctrl:1
	v_add_f32_dpp v100, v100, v100 row_half_mirror row_mask:0xf bank_mask:0xf bound_ctrl:1
	v_add_f32_dpp v102, v102, v102 row_half_mirror row_mask:0xf bank_mask:0xf bound_ctrl:1
	v_pk_fma_f32 v[104:105], v[18:19], v[66:67], v[104:105]
	v_pk_fma_f32 v[106:107], v[20:21], v[68:69], v[106:107]
	v_pk_fma_f32 v[108:109], v[22:23], v[70:71], v[108:109]
	v_pk_fma_f32 v[110:111], v[24:25], v[72:73], v[110:111]
	v_pk_fma_f32 v[112:113], v[26:27], v[66:67], v[112:113]
	v_pk_fma_f32 v[114:115], v[28:29], v[68:69], v[114:115]
	v_pk_fma_f32 v[116:117], v[30:31], v[70:71], v[116:117]
	v_pk_fma_f32 v[118:119], v[32:33], v[72:73], v[118:119]
	ds_read_b128 v[66:69], v127 offset:32256
	ds_read_b128 v[70:73], v127 offset:32272
	ds_read_b32 v90, v128 offset:32000
	ds_read_b32 v91, v128 offset:32032
	s_waitcnt lgkmcnt(6)
	v_pk_fma_f32 v[18:19], v[96:97], v[74:75], v[104:105] op_sel_hi:[0,1,1]
	v_pk_fma_f32 v[20:21], v[96:97], v[76:77], v[106:107] op_sel_hi:[0,1,1]
	v_pk_fma_f32 v[22:23], v[96:97], v[78:79], v[108:109] op_sel_hi:[0,1,1]
	v_pk_fma_f32 v[24:25], v[96:97], v[80:81], v[110:111] op_sel_hi:[0,1,1]
	v_pk_fma_f32 v[26:27], v[100:101], v[74:75], v[112:113] op_sel_hi:[0,1,1]
	v_pk_fma_f32 v[28:29], v[100:101], v[76:77], v[114:115] op_sel_hi:[0,1,1]
	v_pk_fma_f32 v[30:31], v[100:101], v[78:79], v[116:117] op_sel_hi:[0,1,1]
	v_pk_fma_f32 v[32:33], v[100:101], v[80:81], v[118:119] op_sel_hi:[0,1,1]
	v_fma_f32 v124, v92, v95, v98
	v_fma_f32 v125, v93, v95, v102
	v_fma_f32 v120, v96, v94, v124
	v_fma_f32 v122, v100, v94, v125
	v_mov_b32_dpp v120, v121 row_shr:1 row_mask:0xf bank_mask:0x3
	v_mov_b32_dpp v120, v121 row_shl:1 row_mask:0xf bank_mask:0xc
	v_mov_b32_dpp v122, v123 row_shr:1 row_mask:0xf bank_mask:0x3
	v_mov_b32_dpp v122, v123 row_shl:1 row_mask:0xf bank_mask:0xc
	ds_read_b128 v[50:53], v127 offset:33600
	ds_read_b128 v[54:57], v127 offset:33616
	ds_read_b128 v[58:61], v127 offset:34624
	ds_read_b128 v[62:65], v127 offset:34640
	ds_read_b128 v[74:77], v127 offset:32512
	ds_read_b128 v[78:81], v127 offset:32528
	ds_read_b64 v[94:95], v129 offset:32000
	v_pk_mul_f32 v[96:97], v[18:19], v[34:35]
	v_pk_mul_f32 v[98:99], v[18:19], v[42:43]
	v_pk_fma_f32 v[96:97], v[20:21], v[36:37], v[96:97]
	v_pk_fma_f32 v[98:99], v[20:21], v[44:45], v[98:99]
	v_pk_fma_f32 v[96:97], v[22:23], v[38:39], v[96:97]
	v_pk_fma_f32 v[98:99], v[22:23], v[46:47], v[98:99]
	v_pk_fma_f32 v[96:97], v[24:25], v[40:41], v[96:97]
	v_pk_fma_f32 v[98:99], v[24:25], v[48:49], v[98:99]
	v_pk_mul_f32 v[100:101], v[26:27], v[34:35]
	v_pk_mul_f32 v[102:103], v[26:27], v[42:43]
	v_pk_fma_f32 v[100:101], v[28:29], v[36:37], v[100:101]
	v_pk_fma_f32 v[102:103], v[28:29], v[44:45], v[102:103]
	v_pk_fma_f32 v[100:101], v[30:31], v[38:39], v[100:101]
	v_pk_fma_f32 v[102:103], v[30:31], v[46:47], v[102:103]
	v_pk_fma_f32 v[100:101], v[32:33], v[40:41], v[100:101]
	v_pk_fma_f32 v[102:103], v[32:33], v[48:49], v[102:103]
	v_add_f32_e32 v96, v96, v97
	v_add_f32_e32 v98, v98, v99
	v_add_f32_e32 v100, v100, v101
	v_add_f32_e32 v102, v102, v103
	s_waitcnt lgkmcnt(7)
	v_add_f32_dpp v96, v96, v96 quad_perm:[1,0,3,2] row_mask:0xf bank_mask:0xf bound_ctrl:1
	v_add_f32_dpp v98, v98, v98 quad_perm:[1,0,3,2] row_mask:0xf bank_mask:0xf bound_ctrl:1
	v_add_f32_dpp v100, v100, v100 quad_perm:[1,0,3,2] row_mask:0xf bank_mask:0xf bound_ctrl:1
	v_add_f32_dpp v102, v102, v102 quad_perm:[1,0,3,2] row_mask:0xf bank_mask:0xf bound_ctrl:1
	v_pk_mul_f32 v[104:105], v[82:83], v[90:91] op_sel_hi:[1,0]
	v_pk_mul_f32 v[106:107], v[84:85], v[90:91] op_sel_hi:[1,0]
	v_pk_mul_f32 v[108:109], v[86:87], v[90:91] op_sel_hi:[1,0]
	v_pk_mul_f32 v[110:111], v[88:89], v[90:91] op_sel_hi:[1,0]
	v_add_f32_dpp v96, v96, v96 quad_perm:[2,3,0,1] row_mask:0xf bank_mask:0xf bound_ctrl:1
	v_add_f32_dpp v98, v98, v98 quad_perm:[2,3,0,1] row_mask:0xf bank_mask:0xf bound_ctrl:1
	v_add_f32_dpp v100, v100, v100 quad_perm:[2,3,0,1] row_mask:0xf bank_mask:0xf bound_ctrl:1
	v_add_f32_dpp v102, v102, v102 quad_perm:[2,3,0,1] row_mask:0xf bank_mask:0xf bound_ctrl:1
	v_pk_mul_f32 v[112:113], v[82:83], v[90:91] op_sel:[0,1] op_sel_hi:[1,1]
	v_pk_mul_f32 v[114:115], v[84:85], v[90:91] op_sel:[0,1] op_sel_hi:[1,1]
	v_pk_mul_f32 v[116:117], v[86:87], v[90:91] op_sel:[0,1] op_sel_hi:[1,1]
	v_pk_mul_f32 v[118:119], v[88:89], v[90:91] op_sel:[0,1] op_sel_hi:[1,1]
	ds_read_b128 v[82:85], v127 offset:34368
	ds_read_b128 v[86:89], v127 offset:34384
	v_add_f32_dpp v96, v96, v96 row_half_mirror row_mask:0xf bank_mask:0xf bound_ctrl:1
	v_add_f32_dpp v98, v98, v98 row_half_mirror row_mask:0xf bank_mask:0xf bound_ctrl:1
	v_add_f32_dpp v100, v100, v100 row_half_mirror row_mask:0xf bank_mask:0xf bound_ctrl:1
	v_add_f32_dpp v102, v102, v102 row_half_mirror row_mask:0xf bank_mask:0xf bound_ctrl:1
	v_pk_fma_f32 v[104:105], v[18:19], v[66:67], v[104:105]
	v_pk_fma_f32 v[106:107], v[20:21], v[68:69], v[106:107]
	v_pk_fma_f32 v[108:109], v[22:23], v[70:71], v[108:109]
	v_pk_fma_f32 v[110:111], v[24:25], v[72:73], v[110:111]
	v_pk_fma_f32 v[112:113], v[26:27], v[66:67], v[112:113]
	v_pk_fma_f32 v[114:115], v[28:29], v[68:69], v[114:115]
	v_pk_fma_f32 v[116:117], v[30:31], v[70:71], v[116:117]
	v_pk_fma_f32 v[118:119], v[32:33], v[72:73], v[118:119]
	ds_read_b128 v[66:69], v127 offset:33856
	ds_read_b128 v[70:73], v127 offset:33872
	ds_read_b32 v92, v128 offset:33600
	ds_read_b32 v93, v128 offset:33632
	s_waitcnt lgkmcnt(6)
	v_pk_fma_f32 v[18:19], v[96:97], v[74:75], v[104:105] op_sel_hi:[0,1,1]
	v_pk_fma_f32 v[20:21], v[96:97], v[76:77], v[106:107] op_sel_hi:[0,1,1]
	v_pk_fma_f32 v[22:23], v[96:97], v[78:79], v[108:109] op_sel_hi:[0,1,1]
	v_pk_fma_f32 v[24:25], v[96:97], v[80:81], v[110:111] op_sel_hi:[0,1,1]
	v_pk_fma_f32 v[26:27], v[100:101], v[74:75], v[112:113] op_sel_hi:[0,1,1]
	v_pk_fma_f32 v[28:29], v[100:101], v[76:77], v[114:115] op_sel_hi:[0,1,1]
	v_pk_fma_f32 v[30:31], v[100:101], v[78:79], v[116:117] op_sel_hi:[0,1,1]
	v_pk_fma_f32 v[32:33], v[100:101], v[80:81], v[118:119] op_sel_hi:[0,1,1]
	v_fma_f32 v124, v90, v95, v98
	v_fma_f32 v125, v91, v95, v102
	v_fma_f32 v121, v96, v94, v124
	v_fma_f32 v123, v100, v94, v125
	v_mov_b32_dpp v121, v120 row_shr:1 row_mask:0xf bank_mask:0x3
	v_mov_b32_dpp v121, v120 row_shl:1 row_mask:0xf bank_mask:0xc
	v_mov_b32_dpp v123, v122 row_shr:1 row_mask:0xf bank_mask:0x3
	v_mov_b32_dpp v123, v122 row_shl:1 row_mask:0xf bank_mask:0xc
	ds_read_b128 v[34:37], v127 offset:35200
	ds_read_b128 v[38:41], v127 offset:35216
	ds_read_b128 v[42:45], v127 offset:36224
	ds_read_b128 v[46:49], v127 offset:36240
	ds_read_b128 v[74:77], v127 offset:34112
	ds_read_b128 v[78:81], v127 offset:34128
	ds_read_b64 v[94:95], v129 offset:33600
	v_pk_mul_f32 v[96:97], v[18:19], v[50:51]
	v_pk_mul_f32 v[98:99], v[18:19], v[58:59]
	v_pk_fma_f32 v[96:97], v[20:21], v[52:53], v[96:97]
	v_pk_fma_f32 v[98:99], v[20:21], v[60:61], v[98:99]
	v_pk_fma_f32 v[96:97], v[22:23], v[54:55], v[96:97]
	v_pk_fma_f32 v[98:99], v[22:23], v[62:63], v[98:99]
	v_pk_fma_f32 v[96:97], v[24:25], v[56:57], v[96:97]
	v_pk_fma_f32 v[98:99], v[24:25], v[64:65], v[98:99]
	v_pk_mul_f32 v[100:101], v[26:27], v[50:51]
	v_pk_mul_f32 v[102:103], v[26:27], v[58:59]
	v_pk_fma_f32 v[100:101], v[28:29], v[52:53], v[100:101]
	v_pk_fma_f32 v[102:103], v[28:29], v[60:61], v[102:103]
	v_pk_fma_f32 v[100:101], v[30:31], v[54:55], v[100:101]
	v_pk_fma_f32 v[102:103], v[30:31], v[62:63], v[102:103]
	v_pk_fma_f32 v[100:101], v[32:33], v[56:57], v[100:101]
	v_pk_fma_f32 v[102:103], v[32:33], v[64:65], v[102:103]
	v_add_f32_e32 v96, v96, v97
	v_add_f32_e32 v98, v98, v99
	v_add_f32_e32 v100, v100, v101
	v_add_f32_e32 v102, v102, v103
	s_waitcnt lgkmcnt(7)
	v_add_f32_dpp v96, v96, v96 quad_perm:[1,0,3,2] row_mask:0xf bank_mask:0xf bound_ctrl:1
	v_add_f32_dpp v98, v98, v98 quad_perm:[1,0,3,2] row_mask:0xf bank_mask:0xf bound_ctrl:1
	v_add_f32_dpp v100, v100, v100 quad_perm:[1,0,3,2] row_mask:0xf bank_mask:0xf bound_ctrl:1
	v_add_f32_dpp v102, v102, v102 quad_perm:[1,0,3,2] row_mask:0xf bank_mask:0xf bound_ctrl:1
	v_pk_mul_f32 v[104:105], v[82:83], v[92:93] op_sel_hi:[1,0]
	v_pk_mul_f32 v[106:107], v[84:85], v[92:93] op_sel_hi:[1,0]
	v_pk_mul_f32 v[108:109], v[86:87], v[92:93] op_sel_hi:[1,0]
	v_pk_mul_f32 v[110:111], v[88:89], v[92:93] op_sel_hi:[1,0]
	v_add_f32_dpp v96, v96, v96 quad_perm:[2,3,0,1] row_mask:0xf bank_mask:0xf bound_ctrl:1
	v_add_f32_dpp v98, v98, v98 quad_perm:[2,3,0,1] row_mask:0xf bank_mask:0xf bound_ctrl:1
	v_add_f32_dpp v100, v100, v100 quad_perm:[2,3,0,1] row_mask:0xf bank_mask:0xf bound_ctrl:1
	v_add_f32_dpp v102, v102, v102 quad_perm:[2,3,0,1] row_mask:0xf bank_mask:0xf bound_ctrl:1
	v_pk_mul_f32 v[112:113], v[82:83], v[92:93] op_sel:[0,1] op_sel_hi:[1,1]
	v_pk_mul_f32 v[114:115], v[84:85], v[92:93] op_sel:[0,1] op_sel_hi:[1,1]
	v_pk_mul_f32 v[116:117], v[86:87], v[92:93] op_sel:[0,1] op_sel_hi:[1,1]
	v_pk_mul_f32 v[118:119], v[88:89], v[92:93] op_sel:[0,1] op_sel_hi:[1,1]
	ds_read_b128 v[82:85], v127 offset:35968
	ds_read_b128 v[86:89], v127 offset:35984
	v_add_f32_dpp v96, v96, v96 row_half_mirror row_mask:0xf bank_mask:0xf bound_ctrl:1
	v_add_f32_dpp v98, v98, v98 row_half_mirror row_mask:0xf bank_mask:0xf bound_ctrl:1
	v_add_f32_dpp v100, v100, v100 row_half_mirror row_mask:0xf bank_mask:0xf bound_ctrl:1
	v_add_f32_dpp v102, v102, v102 row_half_mirror row_mask:0xf bank_mask:0xf bound_ctrl:1
	v_pk_fma_f32 v[104:105], v[18:19], v[66:67], v[104:105]
	v_pk_fma_f32 v[106:107], v[20:21], v[68:69], v[106:107]
	v_pk_fma_f32 v[108:109], v[22:23], v[70:71], v[108:109]
	v_pk_fma_f32 v[110:111], v[24:25], v[72:73], v[110:111]
	v_pk_fma_f32 v[112:113], v[26:27], v[66:67], v[112:113]
	v_pk_fma_f32 v[114:115], v[28:29], v[68:69], v[114:115]
	v_pk_fma_f32 v[116:117], v[30:31], v[70:71], v[116:117]
	v_pk_fma_f32 v[118:119], v[32:33], v[72:73], v[118:119]
	ds_read_b128 v[66:69], v127 offset:35456
	ds_read_b128 v[70:73], v127 offset:35472
	ds_read_b32 v90, v128 offset:35200
	ds_read_b32 v91, v128 offset:35232
	s_waitcnt lgkmcnt(6)
	v_pk_fma_f32 v[18:19], v[96:97], v[74:75], v[104:105] op_sel_hi:[0,1,1]
	v_pk_fma_f32 v[20:21], v[96:97], v[76:77], v[106:107] op_sel_hi:[0,1,1]
	v_pk_fma_f32 v[22:23], v[96:97], v[78:79], v[108:109] op_sel_hi:[0,1,1]
	v_pk_fma_f32 v[24:25], v[96:97], v[80:81], v[110:111] op_sel_hi:[0,1,1]
	v_pk_fma_f32 v[26:27], v[100:101], v[74:75], v[112:113] op_sel_hi:[0,1,1]
	v_pk_fma_f32 v[28:29], v[100:101], v[76:77], v[114:115] op_sel_hi:[0,1,1]
	v_pk_fma_f32 v[30:31], v[100:101], v[78:79], v[116:117] op_sel_hi:[0,1,1]
	v_pk_fma_f32 v[32:33], v[100:101], v[80:81], v[118:119] op_sel_hi:[0,1,1]
	v_fma_f32 v124, v92, v95, v98
	v_fma_f32 v125, v93, v95, v102
	v_fma_f32 v120, v96, v94, v124
	v_fma_f32 v122, v100, v94, v125
	v_mov_b32_dpp v120, v121 row_shr:1 row_mask:0xf bank_mask:0x3
	v_mov_b32_dpp v120, v121 row_shl:1 row_mask:0xf bank_mask:0xc
	v_mov_b32_dpp v122, v123 row_shr:1 row_mask:0xf bank_mask:0x3
	v_mov_b32_dpp v122, v123 row_shl:1 row_mask:0xf bank_mask:0xc
	ds_read_b128 v[50:53], v127 offset:36800
	ds_read_b128 v[54:57], v127 offset:36816
	ds_read_b128 v[58:61], v127 offset:37824
	ds_read_b128 v[62:65], v127 offset:37840
	ds_read_b128 v[74:77], v127 offset:35712
	ds_read_b128 v[78:81], v127 offset:35728
	ds_read_b64 v[94:95], v129 offset:35200
	v_pk_mul_f32 v[96:97], v[18:19], v[34:35]
	v_pk_mul_f32 v[98:99], v[18:19], v[42:43]
	v_pk_fma_f32 v[96:97], v[20:21], v[36:37], v[96:97]
	v_pk_fma_f32 v[98:99], v[20:21], v[44:45], v[98:99]
	v_pk_fma_f32 v[96:97], v[22:23], v[38:39], v[96:97]
	v_pk_fma_f32 v[98:99], v[22:23], v[46:47], v[98:99]
	v_pk_fma_f32 v[96:97], v[24:25], v[40:41], v[96:97]
	v_pk_fma_f32 v[98:99], v[24:25], v[48:49], v[98:99]
	v_pk_mul_f32 v[100:101], v[26:27], v[34:35]
	v_pk_mul_f32 v[102:103], v[26:27], v[42:43]
	v_pk_fma_f32 v[100:101], v[28:29], v[36:37], v[100:101]
	v_pk_fma_f32 v[102:103], v[28:29], v[44:45], v[102:103]
	v_pk_fma_f32 v[100:101], v[30:31], v[38:39], v[100:101]
	v_pk_fma_f32 v[102:103], v[30:31], v[46:47], v[102:103]
	v_pk_fma_f32 v[100:101], v[32:33], v[40:41], v[100:101]
	v_pk_fma_f32 v[102:103], v[32:33], v[48:49], v[102:103]
	v_add_f32_e32 v96, v96, v97
	v_add_f32_e32 v98, v98, v99
	v_add_f32_e32 v100, v100, v101
	v_add_f32_e32 v102, v102, v103
	s_waitcnt lgkmcnt(7)
	v_add_f32_dpp v96, v96, v96 quad_perm:[1,0,3,2] row_mask:0xf bank_mask:0xf bound_ctrl:1
	v_add_f32_dpp v98, v98, v98 quad_perm:[1,0,3,2] row_mask:0xf bank_mask:0xf bound_ctrl:1
	v_add_f32_dpp v100, v100, v100 quad_perm:[1,0,3,2] row_mask:0xf bank_mask:0xf bound_ctrl:1
	v_add_f32_dpp v102, v102, v102 quad_perm:[1,0,3,2] row_mask:0xf bank_mask:0xf bound_ctrl:1
	v_pk_mul_f32 v[104:105], v[82:83], v[90:91] op_sel_hi:[1,0]
	v_pk_mul_f32 v[106:107], v[84:85], v[90:91] op_sel_hi:[1,0]
	v_pk_mul_f32 v[108:109], v[86:87], v[90:91] op_sel_hi:[1,0]
	v_pk_mul_f32 v[110:111], v[88:89], v[90:91] op_sel_hi:[1,0]
	v_add_f32_dpp v96, v96, v96 quad_perm:[2,3,0,1] row_mask:0xf bank_mask:0xf bound_ctrl:1
	v_add_f32_dpp v98, v98, v98 quad_perm:[2,3,0,1] row_mask:0xf bank_mask:0xf bound_ctrl:1
	v_add_f32_dpp v100, v100, v100 quad_perm:[2,3,0,1] row_mask:0xf bank_mask:0xf bound_ctrl:1
	v_add_f32_dpp v102, v102, v102 quad_perm:[2,3,0,1] row_mask:0xf bank_mask:0xf bound_ctrl:1
	v_pk_mul_f32 v[112:113], v[82:83], v[90:91] op_sel:[0,1] op_sel_hi:[1,1]
	v_pk_mul_f32 v[114:115], v[84:85], v[90:91] op_sel:[0,1] op_sel_hi:[1,1]
	v_pk_mul_f32 v[116:117], v[86:87], v[90:91] op_sel:[0,1] op_sel_hi:[1,1]
	v_pk_mul_f32 v[118:119], v[88:89], v[90:91] op_sel:[0,1] op_sel_hi:[1,1]
	ds_read_b128 v[82:85], v127 offset:37568
	ds_read_b128 v[86:89], v127 offset:37584
	v_add_f32_dpp v96, v96, v96 row_half_mirror row_mask:0xf bank_mask:0xf bound_ctrl:1
	v_add_f32_dpp v98, v98, v98 row_half_mirror row_mask:0xf bank_mask:0xf bound_ctrl:1
	v_add_f32_dpp v100, v100, v100 row_half_mirror row_mask:0xf bank_mask:0xf bound_ctrl:1
	v_add_f32_dpp v102, v102, v102 row_half_mirror row_mask:0xf bank_mask:0xf bound_ctrl:1
	v_pk_fma_f32 v[104:105], v[18:19], v[66:67], v[104:105]
	v_pk_fma_f32 v[106:107], v[20:21], v[68:69], v[106:107]
	v_pk_fma_f32 v[108:109], v[22:23], v[70:71], v[108:109]
	v_pk_fma_f32 v[110:111], v[24:25], v[72:73], v[110:111]
	v_pk_fma_f32 v[112:113], v[26:27], v[66:67], v[112:113]
	v_pk_fma_f32 v[114:115], v[28:29], v[68:69], v[114:115]
	v_pk_fma_f32 v[116:117], v[30:31], v[70:71], v[116:117]
	v_pk_fma_f32 v[118:119], v[32:33], v[72:73], v[118:119]
	ds_read_b128 v[66:69], v127 offset:37056
	ds_read_b128 v[70:73], v127 offset:37072
	ds_read_b32 v92, v128 offset:36800
	ds_read_b32 v93, v128 offset:36832
	s_waitcnt lgkmcnt(6)
	v_pk_fma_f32 v[18:19], v[96:97], v[74:75], v[104:105] op_sel_hi:[0,1,1]
	v_pk_fma_f32 v[20:21], v[96:97], v[76:77], v[106:107] op_sel_hi:[0,1,1]
	v_pk_fma_f32 v[22:23], v[96:97], v[78:79], v[108:109] op_sel_hi:[0,1,1]
	v_pk_fma_f32 v[24:25], v[96:97], v[80:81], v[110:111] op_sel_hi:[0,1,1]
	v_pk_fma_f32 v[26:27], v[100:101], v[74:75], v[112:113] op_sel_hi:[0,1,1]
	v_pk_fma_f32 v[28:29], v[100:101], v[76:77], v[114:115] op_sel_hi:[0,1,1]
	v_pk_fma_f32 v[30:31], v[100:101], v[78:79], v[116:117] op_sel_hi:[0,1,1]
	v_pk_fma_f32 v[32:33], v[100:101], v[80:81], v[118:119] op_sel_hi:[0,1,1]
	v_fma_f32 v124, v90, v95, v98
	v_fma_f32 v125, v91, v95, v102
	v_fma_f32 v121, v96, v94, v124
	v_fma_f32 v123, v100, v94, v125
	v_mov_b32_dpp v121, v120 row_shr:1 row_mask:0xf bank_mask:0x3
	v_mov_b32_dpp v121, v120 row_shl:1 row_mask:0xf bank_mask:0xc
	v_mov_b32_dpp v123, v122 row_shr:1 row_mask:0xf bank_mask:0x3
	v_mov_b32_dpp v123, v122 row_shl:1 row_mask:0xf bank_mask:0xc
	ds_read_b128 v[34:37], v127 offset:38400
	ds_read_b128 v[38:41], v127 offset:38416
	ds_read_b128 v[42:45], v127 offset:39424
	ds_read_b128 v[46:49], v127 offset:39440
	ds_read_b128 v[74:77], v127 offset:37312
	ds_read_b128 v[78:81], v127 offset:37328
	ds_read_b64 v[94:95], v129 offset:36800
	v_pk_mul_f32 v[96:97], v[18:19], v[50:51]
	v_pk_mul_f32 v[98:99], v[18:19], v[58:59]
	v_pk_fma_f32 v[96:97], v[20:21], v[52:53], v[96:97]
	v_pk_fma_f32 v[98:99], v[20:21], v[60:61], v[98:99]
	v_pk_fma_f32 v[96:97], v[22:23], v[54:55], v[96:97]
	v_pk_fma_f32 v[98:99], v[22:23], v[62:63], v[98:99]
	v_pk_fma_f32 v[96:97], v[24:25], v[56:57], v[96:97]
	v_pk_fma_f32 v[98:99], v[24:25], v[64:65], v[98:99]
	v_pk_mul_f32 v[100:101], v[26:27], v[50:51]
	v_pk_mul_f32 v[102:103], v[26:27], v[58:59]
	v_pk_fma_f32 v[100:101], v[28:29], v[52:53], v[100:101]
	v_pk_fma_f32 v[102:103], v[28:29], v[60:61], v[102:103]
	v_pk_fma_f32 v[100:101], v[30:31], v[54:55], v[100:101]
	v_pk_fma_f32 v[102:103], v[30:31], v[62:63], v[102:103]
	v_pk_fma_f32 v[100:101], v[32:33], v[56:57], v[100:101]
	v_pk_fma_f32 v[102:103], v[32:33], v[64:65], v[102:103]
	v_add_f32_e32 v96, v96, v97
	v_add_f32_e32 v98, v98, v99
	v_add_f32_e32 v100, v100, v101
	v_add_f32_e32 v102, v102, v103
	s_waitcnt lgkmcnt(7)
	v_add_f32_dpp v96, v96, v96 quad_perm:[1,0,3,2] row_mask:0xf bank_mask:0xf bound_ctrl:1
	v_add_f32_dpp v98, v98, v98 quad_perm:[1,0,3,2] row_mask:0xf bank_mask:0xf bound_ctrl:1
	v_add_f32_dpp v100, v100, v100 quad_perm:[1,0,3,2] row_mask:0xf bank_mask:0xf bound_ctrl:1
	v_add_f32_dpp v102, v102, v102 quad_perm:[1,0,3,2] row_mask:0xf bank_mask:0xf bound_ctrl:1
	v_pk_mul_f32 v[104:105], v[82:83], v[92:93] op_sel_hi:[1,0]
	v_pk_mul_f32 v[106:107], v[84:85], v[92:93] op_sel_hi:[1,0]
	v_pk_mul_f32 v[108:109], v[86:87], v[92:93] op_sel_hi:[1,0]
	v_pk_mul_f32 v[110:111], v[88:89], v[92:93] op_sel_hi:[1,0]
	v_add_f32_dpp v96, v96, v96 quad_perm:[2,3,0,1] row_mask:0xf bank_mask:0xf bound_ctrl:1
	v_add_f32_dpp v98, v98, v98 quad_perm:[2,3,0,1] row_mask:0xf bank_mask:0xf bound_ctrl:1
	v_add_f32_dpp v100, v100, v100 quad_perm:[2,3,0,1] row_mask:0xf bank_mask:0xf bound_ctrl:1
	v_add_f32_dpp v102, v102, v102 quad_perm:[2,3,0,1] row_mask:0xf bank_mask:0xf bound_ctrl:1
	v_pk_mul_f32 v[112:113], v[82:83], v[92:93] op_sel:[0,1] op_sel_hi:[1,1]
	v_pk_mul_f32 v[114:115], v[84:85], v[92:93] op_sel:[0,1] op_sel_hi:[1,1]
	v_pk_mul_f32 v[116:117], v[86:87], v[92:93] op_sel:[0,1] op_sel_hi:[1,1]
	v_pk_mul_f32 v[118:119], v[88:89], v[92:93] op_sel:[0,1] op_sel_hi:[1,1]
	ds_read_b128 v[82:85], v127 offset:39168
	ds_read_b128 v[86:89], v127 offset:39184
	v_add_f32_dpp v96, v96, v96 row_half_mirror row_mask:0xf bank_mask:0xf bound_ctrl:1
	v_add_f32_dpp v98, v98, v98 row_half_mirror row_mask:0xf bank_mask:0xf bound_ctrl:1
	v_add_f32_dpp v100, v100, v100 row_half_mirror row_mask:0xf bank_mask:0xf bound_ctrl:1
	v_add_f32_dpp v102, v102, v102 row_half_mirror row_mask:0xf bank_mask:0xf bound_ctrl:1
	v_pk_fma_f32 v[104:105], v[18:19], v[66:67], v[104:105]
	v_pk_fma_f32 v[106:107], v[20:21], v[68:69], v[106:107]
	v_pk_fma_f32 v[108:109], v[22:23], v[70:71], v[108:109]
	v_pk_fma_f32 v[110:111], v[24:25], v[72:73], v[110:111]
	v_pk_fma_f32 v[112:113], v[26:27], v[66:67], v[112:113]
	v_pk_fma_f32 v[114:115], v[28:29], v[68:69], v[114:115]
	v_pk_fma_f32 v[116:117], v[30:31], v[70:71], v[116:117]
	v_pk_fma_f32 v[118:119], v[32:33], v[72:73], v[118:119]
	ds_read_b128 v[66:69], v127 offset:38656
	ds_read_b128 v[70:73], v127 offset:38672
	ds_read_b32 v90, v128 offset:38400
	ds_read_b32 v91, v128 offset:38432
	s_waitcnt lgkmcnt(6)
	v_pk_fma_f32 v[18:19], v[96:97], v[74:75], v[104:105] op_sel_hi:[0,1,1]
	v_pk_fma_f32 v[20:21], v[96:97], v[76:77], v[106:107] op_sel_hi:[0,1,1]
	v_pk_fma_f32 v[22:23], v[96:97], v[78:79], v[108:109] op_sel_hi:[0,1,1]
	v_pk_fma_f32 v[24:25], v[96:97], v[80:81], v[110:111] op_sel_hi:[0,1,1]
	v_pk_fma_f32 v[26:27], v[100:101], v[74:75], v[112:113] op_sel_hi:[0,1,1]
	v_pk_fma_f32 v[28:29], v[100:101], v[76:77], v[114:115] op_sel_hi:[0,1,1]
	v_pk_fma_f32 v[30:31], v[100:101], v[78:79], v[116:117] op_sel_hi:[0,1,1]
	v_pk_fma_f32 v[32:33], v[100:101], v[80:81], v[118:119] op_sel_hi:[0,1,1]
	v_fma_f32 v124, v92, v95, v98
	v_fma_f32 v125, v93, v95, v102
	v_fma_f32 v120, v96, v94, v124
	v_fma_f32 v122, v100, v94, v125
	v_mov_b32_dpp v120, v121 row_shr:1 row_mask:0xf bank_mask:0x3
	v_mov_b32_dpp v120, v121 row_shl:1 row_mask:0xf bank_mask:0xc
	v_mov_b32_dpp v122, v123 row_shr:1 row_mask:0xf bank_mask:0x3
	v_mov_b32_dpp v122, v123 row_shl:1 row_mask:0xf bank_mask:0xc
	v_cvt_pk_bf16_f32 v126, v120, v120
	v_cvt_pk_bf16_f32 v139, v122, v122
	global_store_short v[130:131], v126, off
	global_store_short v[130:131], v139, off offset:16
	v_lshl_add_u64 v[130:131], v[130:131], 0, v[132:133]
	ds_read_b128 v[50:53], v127 offset:40000
	ds_read_b128 v[54:57], v127 offset:40016
	ds_read_b128 v[58:61], v127 offset:41024
	ds_read_b128 v[62:65], v127 offset:41040
	ds_read_b128 v[74:77], v127 offset:38912
	ds_read_b128 v[78:81], v127 offset:38928
	ds_read_b64 v[94:95], v129 offset:38400
	v_pk_mul_f32 v[96:97], v[18:19], v[34:35]
	v_pk_mul_f32 v[98:99], v[18:19], v[42:43]
	v_pk_fma_f32 v[96:97], v[20:21], v[36:37], v[96:97]
	v_pk_fma_f32 v[98:99], v[20:21], v[44:45], v[98:99]
	v_pk_fma_f32 v[96:97], v[22:23], v[38:39], v[96:97]
	v_pk_fma_f32 v[98:99], v[22:23], v[46:47], v[98:99]
	v_pk_fma_f32 v[96:97], v[24:25], v[40:41], v[96:97]
	v_pk_fma_f32 v[98:99], v[24:25], v[48:49], v[98:99]
	v_pk_mul_f32 v[100:101], v[26:27], v[34:35]
	v_pk_mul_f32 v[102:103], v[26:27], v[42:43]
	v_pk_fma_f32 v[100:101], v[28:29], v[36:37], v[100:101]
	v_pk_fma_f32 v[102:103], v[28:29], v[44:45], v[102:103]
	v_pk_fma_f32 v[100:101], v[30:31], v[38:39], v[100:101]
	v_pk_fma_f32 v[102:103], v[30:31], v[46:47], v[102:103]
	v_pk_fma_f32 v[100:101], v[32:33], v[40:41], v[100:101]
	v_pk_fma_f32 v[102:103], v[32:33], v[48:49], v[102:103]
	v_add_f32_e32 v96, v96, v97
	v_add_f32_e32 v98, v98, v99
	v_add_f32_e32 v100, v100, v101
	v_add_f32_e32 v102, v102, v103
	s_waitcnt lgkmcnt(7)
	v_add_f32_dpp v96, v96, v96 quad_perm:[1,0,3,2] row_mask:0xf bank_mask:0xf bound_ctrl:1
	v_add_f32_dpp v98, v98, v98 quad_perm:[1,0,3,2] row_mask:0xf bank_mask:0xf bound_ctrl:1
	v_add_f32_dpp v100, v100, v100 quad_perm:[1,0,3,2] row_mask:0xf bank_mask:0xf bound_ctrl:1
	v_add_f32_dpp v102, v102, v102 quad_perm:[1,0,3,2] row_mask:0xf bank_mask:0xf bound_ctrl:1
	v_pk_mul_f32 v[104:105], v[82:83], v[90:91] op_sel_hi:[1,0]
	v_pk_mul_f32 v[106:107], v[84:85], v[90:91] op_sel_hi:[1,0]
	v_pk_mul_f32 v[108:109], v[86:87], v[90:91] op_sel_hi:[1,0]
	v_pk_mul_f32 v[110:111], v[88:89], v[90:91] op_sel_hi:[1,0]
	v_add_f32_dpp v96, v96, v96 quad_perm:[2,3,0,1] row_mask:0xf bank_mask:0xf bound_ctrl:1
	v_add_f32_dpp v98, v98, v98 quad_perm:[2,3,0,1] row_mask:0xf bank_mask:0xf bound_ctrl:1
	v_add_f32_dpp v100, v100, v100 quad_perm:[2,3,0,1] row_mask:0xf bank_mask:0xf bound_ctrl:1
	v_add_f32_dpp v102, v102, v102 quad_perm:[2,3,0,1] row_mask:0xf bank_mask:0xf bound_ctrl:1
	v_pk_mul_f32 v[112:113], v[82:83], v[90:91] op_sel:[0,1] op_sel_hi:[1,1]
	v_pk_mul_f32 v[114:115], v[84:85], v[90:91] op_sel:[0,1] op_sel_hi:[1,1]
	v_pk_mul_f32 v[116:117], v[86:87], v[90:91] op_sel:[0,1] op_sel_hi:[1,1]
	v_pk_mul_f32 v[118:119], v[88:89], v[90:91] op_sel:[0,1] op_sel_hi:[1,1]
	ds_read_b128 v[82:85], v127 offset:40768
	ds_read_b128 v[86:89], v127 offset:40784
	v_add_f32_dpp v96, v96, v96 row_half_mirror row_mask:0xf bank_mask:0xf bound_ctrl:1
	v_add_f32_dpp v98, v98, v98 row_half_mirror row_mask:0xf bank_mask:0xf bound_ctrl:1
	v_add_f32_dpp v100, v100, v100 row_half_mirror row_mask:0xf bank_mask:0xf bound_ctrl:1
	v_add_f32_dpp v102, v102, v102 row_half_mirror row_mask:0xf bank_mask:0xf bound_ctrl:1
	v_pk_fma_f32 v[104:105], v[18:19], v[66:67], v[104:105]
	v_pk_fma_f32 v[106:107], v[20:21], v[68:69], v[106:107]
	v_pk_fma_f32 v[108:109], v[22:23], v[70:71], v[108:109]
	v_pk_fma_f32 v[110:111], v[24:25], v[72:73], v[110:111]
	v_pk_fma_f32 v[112:113], v[26:27], v[66:67], v[112:113]
	v_pk_fma_f32 v[114:115], v[28:29], v[68:69], v[114:115]
	v_pk_fma_f32 v[116:117], v[30:31], v[70:71], v[116:117]
	v_pk_fma_f32 v[118:119], v[32:33], v[72:73], v[118:119]
	ds_read_b128 v[66:69], v127 offset:40256
	ds_read_b128 v[70:73], v127 offset:40272
	ds_read_b32 v92, v128 offset:40000
	ds_read_b32 v93, v128 offset:40032
	s_waitcnt lgkmcnt(6)
	v_pk_fma_f32 v[18:19], v[96:97], v[74:75], v[104:105] op_sel_hi:[0,1,1]
	v_pk_fma_f32 v[20:21], v[96:97], v[76:77], v[106:107] op_sel_hi:[0,1,1]
	v_pk_fma_f32 v[22:23], v[96:97], v[78:79], v[108:109] op_sel_hi:[0,1,1]
	v_pk_fma_f32 v[24:25], v[96:97], v[80:81], v[110:111] op_sel_hi:[0,1,1]
	v_pk_fma_f32 v[26:27], v[100:101], v[74:75], v[112:113] op_sel_hi:[0,1,1]
	v_pk_fma_f32 v[28:29], v[100:101], v[76:77], v[114:115] op_sel_hi:[0,1,1]
	v_pk_fma_f32 v[30:31], v[100:101], v[78:79], v[116:117] op_sel_hi:[0,1,1]
	v_pk_fma_f32 v[32:33], v[100:101], v[80:81], v[118:119] op_sel_hi:[0,1,1]
	v_fma_f32 v124, v90, v95, v98
	v_fma_f32 v125, v91, v95, v102
	v_fma_f32 v121, v96, v94, v124
	v_fma_f32 v123, v100, v94, v125
	v_mov_b32_dpp v121, v120 row_shr:1 row_mask:0xf bank_mask:0x3
	v_mov_b32_dpp v121, v120 row_shl:1 row_mask:0xf bank_mask:0xc
	v_mov_b32_dpp v123, v122 row_shr:1 row_mask:0xf bank_mask:0x3
	v_mov_b32_dpp v123, v122 row_shl:1 row_mask:0xf bank_mask:0xc
	ds_read_b128 v[34:37], v127 offset:41600
	ds_read_b128 v[38:41], v127 offset:41616
	ds_read_b128 v[42:45], v127 offset:42624
	ds_read_b128 v[46:49], v127 offset:42640
	ds_read_b128 v[74:77], v127 offset:40512
	ds_read_b128 v[78:81], v127 offset:40528
	ds_read_b64 v[94:95], v129 offset:40000
	v_pk_mul_f32 v[96:97], v[18:19], v[50:51]
	v_pk_mul_f32 v[98:99], v[18:19], v[58:59]
	v_pk_fma_f32 v[96:97], v[20:21], v[52:53], v[96:97]
	v_pk_fma_f32 v[98:99], v[20:21], v[60:61], v[98:99]
	v_pk_fma_f32 v[96:97], v[22:23], v[54:55], v[96:97]
	v_pk_fma_f32 v[98:99], v[22:23], v[62:63], v[98:99]
	v_pk_fma_f32 v[96:97], v[24:25], v[56:57], v[96:97]
	v_pk_fma_f32 v[98:99], v[24:25], v[64:65], v[98:99]
	v_pk_mul_f32 v[100:101], v[26:27], v[50:51]
	v_pk_mul_f32 v[102:103], v[26:27], v[58:59]
	v_pk_fma_f32 v[100:101], v[28:29], v[52:53], v[100:101]
	v_pk_fma_f32 v[102:103], v[28:29], v[60:61], v[102:103]
	v_pk_fma_f32 v[100:101], v[30:31], v[54:55], v[100:101]
	v_pk_fma_f32 v[102:103], v[30:31], v[62:63], v[102:103]
	v_pk_fma_f32 v[100:101], v[32:33], v[56:57], v[100:101]
	v_pk_fma_f32 v[102:103], v[32:33], v[64:65], v[102:103]
	v_add_f32_e32 v96, v96, v97
	v_add_f32_e32 v98, v98, v99
	v_add_f32_e32 v100, v100, v101
	v_add_f32_e32 v102, v102, v103
	s_waitcnt lgkmcnt(7)
	v_add_f32_dpp v96, v96, v96 quad_perm:[1,0,3,2] row_mask:0xf bank_mask:0xf bound_ctrl:1
	v_add_f32_dpp v98, v98, v98 quad_perm:[1,0,3,2] row_mask:0xf bank_mask:0xf bound_ctrl:1
	v_add_f32_dpp v100, v100, v100 quad_perm:[1,0,3,2] row_mask:0xf bank_mask:0xf bound_ctrl:1
	v_add_f32_dpp v102, v102, v102 quad_perm:[1,0,3,2] row_mask:0xf bank_mask:0xf bound_ctrl:1
	v_pk_mul_f32 v[104:105], v[82:83], v[92:93] op_sel_hi:[1,0]
	v_pk_mul_f32 v[106:107], v[84:85], v[92:93] op_sel_hi:[1,0]
	v_pk_mul_f32 v[108:109], v[86:87], v[92:93] op_sel_hi:[1,0]
	v_pk_mul_f32 v[110:111], v[88:89], v[92:93] op_sel_hi:[1,0]
	v_add_f32_dpp v96, v96, v96 quad_perm:[2,3,0,1] row_mask:0xf bank_mask:0xf bound_ctrl:1
	v_add_f32_dpp v98, v98, v98 quad_perm:[2,3,0,1] row_mask:0xf bank_mask:0xf bound_ctrl:1
	v_add_f32_dpp v100, v100, v100 quad_perm:[2,3,0,1] row_mask:0xf bank_mask:0xf bound_ctrl:1
	v_add_f32_dpp v102, v102, v102 quad_perm:[2,3,0,1] row_mask:0xf bank_mask:0xf bound_ctrl:1
	v_pk_mul_f32 v[112:113], v[82:83], v[92:93] op_sel:[0,1] op_sel_hi:[1,1]
	v_pk_mul_f32 v[114:115], v[84:85], v[92:93] op_sel:[0,1] op_sel_hi:[1,1]
	v_pk_mul_f32 v[116:117], v[86:87], v[92:93] op_sel:[0,1] op_sel_hi:[1,1]
	v_pk_mul_f32 v[118:119], v[88:89], v[92:93] op_sel:[0,1] op_sel_hi:[1,1]
	ds_read_b128 v[82:85], v127 offset:42368
	ds_read_b128 v[86:89], v127 offset:42384
	v_add_f32_dpp v96, v96, v96 row_half_mirror row_mask:0xf bank_mask:0xf bound_ctrl:1
	v_add_f32_dpp v98, v98, v98 row_half_mirror row_mask:0xf bank_mask:0xf bound_ctrl:1
	v_add_f32_dpp v100, v100, v100 row_half_mirror row_mask:0xf bank_mask:0xf bound_ctrl:1
	v_add_f32_dpp v102, v102, v102 row_half_mirror row_mask:0xf bank_mask:0xf bound_ctrl:1
	v_pk_fma_f32 v[104:105], v[18:19], v[66:67], v[104:105]
	v_pk_fma_f32 v[106:107], v[20:21], v[68:69], v[106:107]
	v_pk_fma_f32 v[108:109], v[22:23], v[70:71], v[108:109]
	v_pk_fma_f32 v[110:111], v[24:25], v[72:73], v[110:111]
	v_pk_fma_f32 v[112:113], v[26:27], v[66:67], v[112:113]
	v_pk_fma_f32 v[114:115], v[28:29], v[68:69], v[114:115]
	v_pk_fma_f32 v[116:117], v[30:31], v[70:71], v[116:117]
	v_pk_fma_f32 v[118:119], v[32:33], v[72:73], v[118:119]
	ds_read_b128 v[66:69], v127 offset:41856
	ds_read_b128 v[70:73], v127 offset:41872
	ds_read_b32 v90, v128 offset:41600
	ds_read_b32 v91, v128 offset:41632
	s_waitcnt lgkmcnt(6)
	v_pk_fma_f32 v[18:19], v[96:97], v[74:75], v[104:105] op_sel_hi:[0,1,1]
	v_pk_fma_f32 v[20:21], v[96:97], v[76:77], v[106:107] op_sel_hi:[0,1,1]
	v_pk_fma_f32 v[22:23], v[96:97], v[78:79], v[108:109] op_sel_hi:[0,1,1]
	v_pk_fma_f32 v[24:25], v[96:97], v[80:81], v[110:111] op_sel_hi:[0,1,1]
	v_pk_fma_f32 v[26:27], v[100:101], v[74:75], v[112:113] op_sel_hi:[0,1,1]
	v_pk_fma_f32 v[28:29], v[100:101], v[76:77], v[114:115] op_sel_hi:[0,1,1]
	v_pk_fma_f32 v[30:31], v[100:101], v[78:79], v[116:117] op_sel_hi:[0,1,1]
	v_pk_fma_f32 v[32:33], v[100:101], v[80:81], v[118:119] op_sel_hi:[0,1,1]
	v_fma_f32 v124, v92, v95, v98
	v_fma_f32 v125, v93, v95, v102
	v_fma_f32 v120, v96, v94, v124
	v_fma_f32 v122, v100, v94, v125
	v_mov_b32_dpp v120, v121 row_shr:1 row_mask:0xf bank_mask:0x3
	v_mov_b32_dpp v120, v121 row_shl:1 row_mask:0xf bank_mask:0xc
	v_mov_b32_dpp v122, v123 row_shr:1 row_mask:0xf bank_mask:0x3
	v_mov_b32_dpp v122, v123 row_shl:1 row_mask:0xf bank_mask:0xc
	ds_read_b128 v[50:53], v127 offset:43200
	ds_read_b128 v[54:57], v127 offset:43216
	ds_read_b128 v[58:61], v127 offset:44224
	ds_read_b128 v[62:65], v127 offset:44240
	ds_read_b128 v[74:77], v127 offset:42112
	ds_read_b128 v[78:81], v127 offset:42128
	ds_read_b64 v[94:95], v129 offset:41600
	v_pk_mul_f32 v[96:97], v[18:19], v[34:35]
	v_pk_mul_f32 v[98:99], v[18:19], v[42:43]
	v_pk_fma_f32 v[96:97], v[20:21], v[36:37], v[96:97]
	v_pk_fma_f32 v[98:99], v[20:21], v[44:45], v[98:99]
	v_pk_fma_f32 v[96:97], v[22:23], v[38:39], v[96:97]
	v_pk_fma_f32 v[98:99], v[22:23], v[46:47], v[98:99]
	v_pk_fma_f32 v[96:97], v[24:25], v[40:41], v[96:97]
	v_pk_fma_f32 v[98:99], v[24:25], v[48:49], v[98:99]
	v_pk_mul_f32 v[100:101], v[26:27], v[34:35]
	v_pk_mul_f32 v[102:103], v[26:27], v[42:43]
	v_pk_fma_f32 v[100:101], v[28:29], v[36:37], v[100:101]
	v_pk_fma_f32 v[102:103], v[28:29], v[44:45], v[102:103]
	v_pk_fma_f32 v[100:101], v[30:31], v[38:39], v[100:101]
	v_pk_fma_f32 v[102:103], v[30:31], v[46:47], v[102:103]
	v_pk_fma_f32 v[100:101], v[32:33], v[40:41], v[100:101]
	v_pk_fma_f32 v[102:103], v[32:33], v[48:49], v[102:103]
	v_add_f32_e32 v96, v96, v97
	v_add_f32_e32 v98, v98, v99
	v_add_f32_e32 v100, v100, v101
	v_add_f32_e32 v102, v102, v103
	s_waitcnt lgkmcnt(7)
	v_add_f32_dpp v96, v96, v96 quad_perm:[1,0,3,2] row_mask:0xf bank_mask:0xf bound_ctrl:1
	v_add_f32_dpp v98, v98, v98 quad_perm:[1,0,3,2] row_mask:0xf bank_mask:0xf bound_ctrl:1
	v_add_f32_dpp v100, v100, v100 quad_perm:[1,0,3,2] row_mask:0xf bank_mask:0xf bound_ctrl:1
	v_add_f32_dpp v102, v102, v102 quad_perm:[1,0,3,2] row_mask:0xf bank_mask:0xf bound_ctrl:1
	v_pk_mul_f32 v[104:105], v[82:83], v[90:91] op_sel_hi:[1,0]
	v_pk_mul_f32 v[106:107], v[84:85], v[90:91] op_sel_hi:[1,0]
	v_pk_mul_f32 v[108:109], v[86:87], v[90:91] op_sel_hi:[1,0]
	v_pk_mul_f32 v[110:111], v[88:89], v[90:91] op_sel_hi:[1,0]
	v_add_f32_dpp v96, v96, v96 quad_perm:[2,3,0,1] row_mask:0xf bank_mask:0xf bound_ctrl:1
	v_add_f32_dpp v98, v98, v98 quad_perm:[2,3,0,1] row_mask:0xf bank_mask:0xf bound_ctrl:1
	v_add_f32_dpp v100, v100, v100 quad_perm:[2,3,0,1] row_mask:0xf bank_mask:0xf bound_ctrl:1
	v_add_f32_dpp v102, v102, v102 quad_perm:[2,3,0,1] row_mask:0xf bank_mask:0xf bound_ctrl:1
	v_pk_mul_f32 v[112:113], v[82:83], v[90:91] op_sel:[0,1] op_sel_hi:[1,1]
	v_pk_mul_f32 v[114:115], v[84:85], v[90:91] op_sel:[0,1] op_sel_hi:[1,1]
	v_pk_mul_f32 v[116:117], v[86:87], v[90:91] op_sel:[0,1] op_sel_hi:[1,1]
	v_pk_mul_f32 v[118:119], v[88:89], v[90:91] op_sel:[0,1] op_sel_hi:[1,1]
	ds_read_b128 v[82:85], v127 offset:43968
	ds_read_b128 v[86:89], v127 offset:43984
	v_add_f32_dpp v96, v96, v96 row_half_mirror row_mask:0xf bank_mask:0xf bound_ctrl:1
	v_add_f32_dpp v98, v98, v98 row_half_mirror row_mask:0xf bank_mask:0xf bound_ctrl:1
	v_add_f32_dpp v100, v100, v100 row_half_mirror row_mask:0xf bank_mask:0xf bound_ctrl:1
	v_add_f32_dpp v102, v102, v102 row_half_mirror row_mask:0xf bank_mask:0xf bound_ctrl:1
	v_pk_fma_f32 v[104:105], v[18:19], v[66:67], v[104:105]
	v_pk_fma_f32 v[106:107], v[20:21], v[68:69], v[106:107]
	v_pk_fma_f32 v[108:109], v[22:23], v[70:71], v[108:109]
	v_pk_fma_f32 v[110:111], v[24:25], v[72:73], v[110:111]
	v_pk_fma_f32 v[112:113], v[26:27], v[66:67], v[112:113]
	v_pk_fma_f32 v[114:115], v[28:29], v[68:69], v[114:115]
	v_pk_fma_f32 v[116:117], v[30:31], v[70:71], v[116:117]
	v_pk_fma_f32 v[118:119], v[32:33], v[72:73], v[118:119]
	ds_read_b128 v[66:69], v127 offset:43456
	ds_read_b128 v[70:73], v127 offset:43472
	ds_read_b32 v92, v128 offset:43200
	ds_read_b32 v93, v128 offset:43232
	s_waitcnt lgkmcnt(6)
	v_pk_fma_f32 v[18:19], v[96:97], v[74:75], v[104:105] op_sel_hi:[0,1,1]
	v_pk_fma_f32 v[20:21], v[96:97], v[76:77], v[106:107] op_sel_hi:[0,1,1]
	v_pk_fma_f32 v[22:23], v[96:97], v[78:79], v[108:109] op_sel_hi:[0,1,1]
	v_pk_fma_f32 v[24:25], v[96:97], v[80:81], v[110:111] op_sel_hi:[0,1,1]
	v_pk_fma_f32 v[26:27], v[100:101], v[74:75], v[112:113] op_sel_hi:[0,1,1]
	v_pk_fma_f32 v[28:29], v[100:101], v[76:77], v[114:115] op_sel_hi:[0,1,1]
	v_pk_fma_f32 v[30:31], v[100:101], v[78:79], v[116:117] op_sel_hi:[0,1,1]
	v_pk_fma_f32 v[32:33], v[100:101], v[80:81], v[118:119] op_sel_hi:[0,1,1]
	v_fma_f32 v124, v90, v95, v98
	v_fma_f32 v125, v91, v95, v102
	v_fma_f32 v121, v96, v94, v124
	v_fma_f32 v123, v100, v94, v125
	v_mov_b32_dpp v121, v120 row_shr:1 row_mask:0xf bank_mask:0x3
	v_mov_b32_dpp v121, v120 row_shl:1 row_mask:0xf bank_mask:0xc
	v_mov_b32_dpp v123, v122 row_shr:1 row_mask:0xf bank_mask:0x3
	v_mov_b32_dpp v123, v122 row_shl:1 row_mask:0xf bank_mask:0xc
	ds_read_b128 v[34:37], v127 offset:44800
	ds_read_b128 v[38:41], v127 offset:44816
	ds_read_b128 v[42:45], v127 offset:45824
	ds_read_b128 v[46:49], v127 offset:45840
	ds_read_b128 v[74:77], v127 offset:43712
	ds_read_b128 v[78:81], v127 offset:43728
	ds_read_b64 v[94:95], v129 offset:43200
	v_pk_mul_f32 v[96:97], v[18:19], v[50:51]
	v_pk_mul_f32 v[98:99], v[18:19], v[58:59]
	v_pk_fma_f32 v[96:97], v[20:21], v[52:53], v[96:97]
	v_pk_fma_f32 v[98:99], v[20:21], v[60:61], v[98:99]
	v_pk_fma_f32 v[96:97], v[22:23], v[54:55], v[96:97]
	v_pk_fma_f32 v[98:99], v[22:23], v[62:63], v[98:99]
	v_pk_fma_f32 v[96:97], v[24:25], v[56:57], v[96:97]
	v_pk_fma_f32 v[98:99], v[24:25], v[64:65], v[98:99]
	v_pk_mul_f32 v[100:101], v[26:27], v[50:51]
	v_pk_mul_f32 v[102:103], v[26:27], v[58:59]
	v_pk_fma_f32 v[100:101], v[28:29], v[52:53], v[100:101]
	v_pk_fma_f32 v[102:103], v[28:29], v[60:61], v[102:103]
	v_pk_fma_f32 v[100:101], v[30:31], v[54:55], v[100:101]
	v_pk_fma_f32 v[102:103], v[30:31], v[62:63], v[102:103]
	v_pk_fma_f32 v[100:101], v[32:33], v[56:57], v[100:101]
	v_pk_fma_f32 v[102:103], v[32:33], v[64:65], v[102:103]
	v_add_f32_e32 v96, v96, v97
	v_add_f32_e32 v98, v98, v99
	v_add_f32_e32 v100, v100, v101
	v_add_f32_e32 v102, v102, v103
	s_waitcnt lgkmcnt(7)
	v_add_f32_dpp v96, v96, v96 quad_perm:[1,0,3,2] row_mask:0xf bank_mask:0xf bound_ctrl:1
	v_add_f32_dpp v98, v98, v98 quad_perm:[1,0,3,2] row_mask:0xf bank_mask:0xf bound_ctrl:1
	v_add_f32_dpp v100, v100, v100 quad_perm:[1,0,3,2] row_mask:0xf bank_mask:0xf bound_ctrl:1
	v_add_f32_dpp v102, v102, v102 quad_perm:[1,0,3,2] row_mask:0xf bank_mask:0xf bound_ctrl:1
	v_pk_mul_f32 v[104:105], v[82:83], v[92:93] op_sel_hi:[1,0]
	v_pk_mul_f32 v[106:107], v[84:85], v[92:93] op_sel_hi:[1,0]
	v_pk_mul_f32 v[108:109], v[86:87], v[92:93] op_sel_hi:[1,0]
	v_pk_mul_f32 v[110:111], v[88:89], v[92:93] op_sel_hi:[1,0]
	v_add_f32_dpp v96, v96, v96 quad_perm:[2,3,0,1] row_mask:0xf bank_mask:0xf bound_ctrl:1
	v_add_f32_dpp v98, v98, v98 quad_perm:[2,3,0,1] row_mask:0xf bank_mask:0xf bound_ctrl:1
	v_add_f32_dpp v100, v100, v100 quad_perm:[2,3,0,1] row_mask:0xf bank_mask:0xf bound_ctrl:1
	v_add_f32_dpp v102, v102, v102 quad_perm:[2,3,0,1] row_mask:0xf bank_mask:0xf bound_ctrl:1
	v_pk_mul_f32 v[112:113], v[82:83], v[92:93] op_sel:[0,1] op_sel_hi:[1,1]
	v_pk_mul_f32 v[114:115], v[84:85], v[92:93] op_sel:[0,1] op_sel_hi:[1,1]
	v_pk_mul_f32 v[116:117], v[86:87], v[92:93] op_sel:[0,1] op_sel_hi:[1,1]
	v_pk_mul_f32 v[118:119], v[88:89], v[92:93] op_sel:[0,1] op_sel_hi:[1,1]
	ds_read_b128 v[82:85], v127 offset:45568
	ds_read_b128 v[86:89], v127 offset:45584
	v_add_f32_dpp v96, v96, v96 row_half_mirror row_mask:0xf bank_mask:0xf bound_ctrl:1
	v_add_f32_dpp v98, v98, v98 row_half_mirror row_mask:0xf bank_mask:0xf bound_ctrl:1
	v_add_f32_dpp v100, v100, v100 row_half_mirror row_mask:0xf bank_mask:0xf bound_ctrl:1
	v_add_f32_dpp v102, v102, v102 row_half_mirror row_mask:0xf bank_mask:0xf bound_ctrl:1
	v_pk_fma_f32 v[104:105], v[18:19], v[66:67], v[104:105]
	v_pk_fma_f32 v[106:107], v[20:21], v[68:69], v[106:107]
	v_pk_fma_f32 v[108:109], v[22:23], v[70:71], v[108:109]
	v_pk_fma_f32 v[110:111], v[24:25], v[72:73], v[110:111]
	v_pk_fma_f32 v[112:113], v[26:27], v[66:67], v[112:113]
	v_pk_fma_f32 v[114:115], v[28:29], v[68:69], v[114:115]
	v_pk_fma_f32 v[116:117], v[30:31], v[70:71], v[116:117]
	v_pk_fma_f32 v[118:119], v[32:33], v[72:73], v[118:119]
	ds_read_b128 v[66:69], v127 offset:45056
	ds_read_b128 v[70:73], v127 offset:45072
	ds_read_b32 v90, v128 offset:44800
	ds_read_b32 v91, v128 offset:44832
	s_waitcnt lgkmcnt(6)
	v_pk_fma_f32 v[18:19], v[96:97], v[74:75], v[104:105] op_sel_hi:[0,1,1]
	v_pk_fma_f32 v[20:21], v[96:97], v[76:77], v[106:107] op_sel_hi:[0,1,1]
	v_pk_fma_f32 v[22:23], v[96:97], v[78:79], v[108:109] op_sel_hi:[0,1,1]
	v_pk_fma_f32 v[24:25], v[96:97], v[80:81], v[110:111] op_sel_hi:[0,1,1]
	v_pk_fma_f32 v[26:27], v[100:101], v[74:75], v[112:113] op_sel_hi:[0,1,1]
	v_pk_fma_f32 v[28:29], v[100:101], v[76:77], v[114:115] op_sel_hi:[0,1,1]
	v_pk_fma_f32 v[30:31], v[100:101], v[78:79], v[116:117] op_sel_hi:[0,1,1]
	v_pk_fma_f32 v[32:33], v[100:101], v[80:81], v[118:119] op_sel_hi:[0,1,1]
	v_fma_f32 v124, v92, v95, v98
	v_fma_f32 v125, v93, v95, v102
	v_fma_f32 v120, v96, v94, v124
	v_fma_f32 v122, v100, v94, v125
	v_mov_b32_dpp v120, v121 row_shr:1 row_mask:0xf bank_mask:0x3
	v_mov_b32_dpp v120, v121 row_shl:1 row_mask:0xf bank_mask:0xc
	v_mov_b32_dpp v122, v123 row_shr:1 row_mask:0xf bank_mask:0x3
	v_mov_b32_dpp v122, v123 row_shl:1 row_mask:0xf bank_mask:0xc
	ds_read_b128 v[50:53], v127 offset:46400
	ds_read_b128 v[54:57], v127 offset:46416
	ds_read_b128 v[58:61], v127 offset:47424
	ds_read_b128 v[62:65], v127 offset:47440
	ds_read_b128 v[74:77], v127 offset:45312
	ds_read_b128 v[78:81], v127 offset:45328
	ds_read_b64 v[94:95], v129 offset:44800
	v_pk_mul_f32 v[96:97], v[18:19], v[34:35]
	v_pk_mul_f32 v[98:99], v[18:19], v[42:43]
	v_pk_fma_f32 v[96:97], v[20:21], v[36:37], v[96:97]
	v_pk_fma_f32 v[98:99], v[20:21], v[44:45], v[98:99]
	v_pk_fma_f32 v[96:97], v[22:23], v[38:39], v[96:97]
	v_pk_fma_f32 v[98:99], v[22:23], v[46:47], v[98:99]
	v_pk_fma_f32 v[96:97], v[24:25], v[40:41], v[96:97]
	v_pk_fma_f32 v[98:99], v[24:25], v[48:49], v[98:99]
	v_pk_mul_f32 v[100:101], v[26:27], v[34:35]
	v_pk_mul_f32 v[102:103], v[26:27], v[42:43]
	v_pk_fma_f32 v[100:101], v[28:29], v[36:37], v[100:101]
	v_pk_fma_f32 v[102:103], v[28:29], v[44:45], v[102:103]
	v_pk_fma_f32 v[100:101], v[30:31], v[38:39], v[100:101]
	v_pk_fma_f32 v[102:103], v[30:31], v[46:47], v[102:103]
	v_pk_fma_f32 v[100:101], v[32:33], v[40:41], v[100:101]
	v_pk_fma_f32 v[102:103], v[32:33], v[48:49], v[102:103]
	v_add_f32_e32 v96, v96, v97
	v_add_f32_e32 v98, v98, v99
	v_add_f32_e32 v100, v100, v101
	v_add_f32_e32 v102, v102, v103
	s_waitcnt lgkmcnt(7)
	v_add_f32_dpp v96, v96, v96 quad_perm:[1,0,3,2] row_mask:0xf bank_mask:0xf bound_ctrl:1
	v_add_f32_dpp v98, v98, v98 quad_perm:[1,0,3,2] row_mask:0xf bank_mask:0xf bound_ctrl:1
	v_add_f32_dpp v100, v100, v100 quad_perm:[1,0,3,2] row_mask:0xf bank_mask:0xf bound_ctrl:1
	v_add_f32_dpp v102, v102, v102 quad_perm:[1,0,3,2] row_mask:0xf bank_mask:0xf bound_ctrl:1
	v_pk_mul_f32 v[104:105], v[82:83], v[90:91] op_sel_hi:[1,0]
	v_pk_mul_f32 v[106:107], v[84:85], v[90:91] op_sel_hi:[1,0]
	v_pk_mul_f32 v[108:109], v[86:87], v[90:91] op_sel_hi:[1,0]
	v_pk_mul_f32 v[110:111], v[88:89], v[90:91] op_sel_hi:[1,0]
	v_add_f32_dpp v96, v96, v96 quad_perm:[2,3,0,1] row_mask:0xf bank_mask:0xf bound_ctrl:1
	v_add_f32_dpp v98, v98, v98 quad_perm:[2,3,0,1] row_mask:0xf bank_mask:0xf bound_ctrl:1
	v_add_f32_dpp v100, v100, v100 quad_perm:[2,3,0,1] row_mask:0xf bank_mask:0xf bound_ctrl:1
	v_add_f32_dpp v102, v102, v102 quad_perm:[2,3,0,1] row_mask:0xf bank_mask:0xf bound_ctrl:1
	v_pk_mul_f32 v[112:113], v[82:83], v[90:91] op_sel:[0,1] op_sel_hi:[1,1]
	v_pk_mul_f32 v[114:115], v[84:85], v[90:91] op_sel:[0,1] op_sel_hi:[1,1]
	v_pk_mul_f32 v[116:117], v[86:87], v[90:91] op_sel:[0,1] op_sel_hi:[1,1]
	v_pk_mul_f32 v[118:119], v[88:89], v[90:91] op_sel:[0,1] op_sel_hi:[1,1]
	ds_read_b128 v[82:85], v127 offset:47168
	ds_read_b128 v[86:89], v127 offset:47184
	v_add_f32_dpp v96, v96, v96 row_half_mirror row_mask:0xf bank_mask:0xf bound_ctrl:1
	v_add_f32_dpp v98, v98, v98 row_half_mirror row_mask:0xf bank_mask:0xf bound_ctrl:1
	v_add_f32_dpp v100, v100, v100 row_half_mirror row_mask:0xf bank_mask:0xf bound_ctrl:1
	v_add_f32_dpp v102, v102, v102 row_half_mirror row_mask:0xf bank_mask:0xf bound_ctrl:1
	v_pk_fma_f32 v[104:105], v[18:19], v[66:67], v[104:105]
	v_pk_fma_f32 v[106:107], v[20:21], v[68:69], v[106:107]
	v_pk_fma_f32 v[108:109], v[22:23], v[70:71], v[108:109]
	v_pk_fma_f32 v[110:111], v[24:25], v[72:73], v[110:111]
	v_pk_fma_f32 v[112:113], v[26:27], v[66:67], v[112:113]
	v_pk_fma_f32 v[114:115], v[28:29], v[68:69], v[114:115]
	v_pk_fma_f32 v[116:117], v[30:31], v[70:71], v[116:117]
	v_pk_fma_f32 v[118:119], v[32:33], v[72:73], v[118:119]
	ds_read_b128 v[66:69], v127 offset:46656
	ds_read_b128 v[70:73], v127 offset:46672
	ds_read_b32 v92, v128 offset:46400
	ds_read_b32 v93, v128 offset:46432
	s_waitcnt lgkmcnt(6)
	v_pk_fma_f32 v[18:19], v[96:97], v[74:75], v[104:105] op_sel_hi:[0,1,1]
	v_pk_fma_f32 v[20:21], v[96:97], v[76:77], v[106:107] op_sel_hi:[0,1,1]
	v_pk_fma_f32 v[22:23], v[96:97], v[78:79], v[108:109] op_sel_hi:[0,1,1]
	v_pk_fma_f32 v[24:25], v[96:97], v[80:81], v[110:111] op_sel_hi:[0,1,1]
	v_pk_fma_f32 v[26:27], v[100:101], v[74:75], v[112:113] op_sel_hi:[0,1,1]
	v_pk_fma_f32 v[28:29], v[100:101], v[76:77], v[114:115] op_sel_hi:[0,1,1]
	v_pk_fma_f32 v[30:31], v[100:101], v[78:79], v[116:117] op_sel_hi:[0,1,1]
	v_pk_fma_f32 v[32:33], v[100:101], v[80:81], v[118:119] op_sel_hi:[0,1,1]
	v_fma_f32 v124, v90, v95, v98
	v_fma_f32 v125, v91, v95, v102
	v_fma_f32 v121, v96, v94, v124
	v_fma_f32 v123, v100, v94, v125
	v_mov_b32_dpp v121, v120 row_shr:1 row_mask:0xf bank_mask:0x3
	v_mov_b32_dpp v121, v120 row_shl:1 row_mask:0xf bank_mask:0xc
	v_mov_b32_dpp v123, v122 row_shr:1 row_mask:0xf bank_mask:0x3
	v_mov_b32_dpp v123, v122 row_shl:1 row_mask:0xf bank_mask:0xc
	ds_read_b128 v[34:37], v127 offset:48000
	ds_read_b128 v[38:41], v127 offset:48016
	ds_read_b128 v[42:45], v127 offset:49024
	ds_read_b128 v[46:49], v127 offset:49040
	ds_read_b128 v[74:77], v127 offset:46912
	ds_read_b128 v[78:81], v127 offset:46928
	ds_read_b64 v[94:95], v129 offset:46400
	v_pk_mul_f32 v[96:97], v[18:19], v[50:51]
	v_pk_mul_f32 v[98:99], v[18:19], v[58:59]
	v_pk_fma_f32 v[96:97], v[20:21], v[52:53], v[96:97]
	v_pk_fma_f32 v[98:99], v[20:21], v[60:61], v[98:99]
	v_pk_fma_f32 v[96:97], v[22:23], v[54:55], v[96:97]
	v_pk_fma_f32 v[98:99], v[22:23], v[62:63], v[98:99]
	v_pk_fma_f32 v[96:97], v[24:25], v[56:57], v[96:97]
	v_pk_fma_f32 v[98:99], v[24:25], v[64:65], v[98:99]
	v_pk_mul_f32 v[100:101], v[26:27], v[50:51]
	v_pk_mul_f32 v[102:103], v[26:27], v[58:59]
	v_pk_fma_f32 v[100:101], v[28:29], v[52:53], v[100:101]
	v_pk_fma_f32 v[102:103], v[28:29], v[60:61], v[102:103]
	v_pk_fma_f32 v[100:101], v[30:31], v[54:55], v[100:101]
	v_pk_fma_f32 v[102:103], v[30:31], v[62:63], v[102:103]
	v_pk_fma_f32 v[100:101], v[32:33], v[56:57], v[100:101]
	v_pk_fma_f32 v[102:103], v[32:33], v[64:65], v[102:103]
	v_add_f32_e32 v96, v96, v97
	v_add_f32_e32 v98, v98, v99
	v_add_f32_e32 v100, v100, v101
	v_add_f32_e32 v102, v102, v103
	s_waitcnt lgkmcnt(7)
	v_add_f32_dpp v96, v96, v96 quad_perm:[1,0,3,2] row_mask:0xf bank_mask:0xf bound_ctrl:1
	v_add_f32_dpp v98, v98, v98 quad_perm:[1,0,3,2] row_mask:0xf bank_mask:0xf bound_ctrl:1
	v_add_f32_dpp v100, v100, v100 quad_perm:[1,0,3,2] row_mask:0xf bank_mask:0xf bound_ctrl:1
	v_add_f32_dpp v102, v102, v102 quad_perm:[1,0,3,2] row_mask:0xf bank_mask:0xf bound_ctrl:1
	v_pk_mul_f32 v[104:105], v[82:83], v[92:93] op_sel_hi:[1,0]
	v_pk_mul_f32 v[106:107], v[84:85], v[92:93] op_sel_hi:[1,0]
	v_pk_mul_f32 v[108:109], v[86:87], v[92:93] op_sel_hi:[1,0]
	v_pk_mul_f32 v[110:111], v[88:89], v[92:93] op_sel_hi:[1,0]
	v_add_f32_dpp v96, v96, v96 quad_perm:[2,3,0,1] row_mask:0xf bank_mask:0xf bound_ctrl:1
	v_add_f32_dpp v98, v98, v98 quad_perm:[2,3,0,1] row_mask:0xf bank_mask:0xf bound_ctrl:1
	v_add_f32_dpp v100, v100, v100 quad_perm:[2,3,0,1] row_mask:0xf bank_mask:0xf bound_ctrl:1
	v_add_f32_dpp v102, v102, v102 quad_perm:[2,3,0,1] row_mask:0xf bank_mask:0xf bound_ctrl:1
	v_pk_mul_f32 v[112:113], v[82:83], v[92:93] op_sel:[0,1] op_sel_hi:[1,1]
	v_pk_mul_f32 v[114:115], v[84:85], v[92:93] op_sel:[0,1] op_sel_hi:[1,1]
	v_pk_mul_f32 v[116:117], v[86:87], v[92:93] op_sel:[0,1] op_sel_hi:[1,1]
	v_pk_mul_f32 v[118:119], v[88:89], v[92:93] op_sel:[0,1] op_sel_hi:[1,1]
	ds_read_b128 v[82:85], v127 offset:48768
	ds_read_b128 v[86:89], v127 offset:48784
	v_add_f32_dpp v96, v96, v96 row_half_mirror row_mask:0xf bank_mask:0xf bound_ctrl:1
	v_add_f32_dpp v98, v98, v98 row_half_mirror row_mask:0xf bank_mask:0xf bound_ctrl:1
	v_add_f32_dpp v100, v100, v100 row_half_mirror row_mask:0xf bank_mask:0xf bound_ctrl:1
	v_add_f32_dpp v102, v102, v102 row_half_mirror row_mask:0xf bank_mask:0xf bound_ctrl:1
	v_pk_fma_f32 v[104:105], v[18:19], v[66:67], v[104:105]
	v_pk_fma_f32 v[106:107], v[20:21], v[68:69], v[106:107]
	v_pk_fma_f32 v[108:109], v[22:23], v[70:71], v[108:109]
	v_pk_fma_f32 v[110:111], v[24:25], v[72:73], v[110:111]
	v_pk_fma_f32 v[112:113], v[26:27], v[66:67], v[112:113]
	v_pk_fma_f32 v[114:115], v[28:29], v[68:69], v[114:115]
	v_pk_fma_f32 v[116:117], v[30:31], v[70:71], v[116:117]
	v_pk_fma_f32 v[118:119], v[32:33], v[72:73], v[118:119]
	ds_read_b128 v[66:69], v127 offset:48256
	ds_read_b128 v[70:73], v127 offset:48272
	ds_read_b32 v90, v128 offset:48000
	ds_read_b32 v91, v128 offset:48032
	s_waitcnt lgkmcnt(6)
	v_pk_fma_f32 v[18:19], v[96:97], v[74:75], v[104:105] op_sel_hi:[0,1,1]
	v_pk_fma_f32 v[20:21], v[96:97], v[76:77], v[106:107] op_sel_hi:[0,1,1]
	v_pk_fma_f32 v[22:23], v[96:97], v[78:79], v[108:109] op_sel_hi:[0,1,1]
	v_pk_fma_f32 v[24:25], v[96:97], v[80:81], v[110:111] op_sel_hi:[0,1,1]
	v_pk_fma_f32 v[26:27], v[100:101], v[74:75], v[112:113] op_sel_hi:[0,1,1]
	v_pk_fma_f32 v[28:29], v[100:101], v[76:77], v[114:115] op_sel_hi:[0,1,1]
	v_pk_fma_f32 v[30:31], v[100:101], v[78:79], v[116:117] op_sel_hi:[0,1,1]
	v_pk_fma_f32 v[32:33], v[100:101], v[80:81], v[118:119] op_sel_hi:[0,1,1]
	v_fma_f32 v124, v92, v95, v98
	v_fma_f32 v125, v93, v95, v102
	v_fma_f32 v120, v96, v94, v124
	v_fma_f32 v122, v100, v94, v125
	v_mov_b32_dpp v120, v121 row_shr:1 row_mask:0xf bank_mask:0x3
	v_mov_b32_dpp v120, v121 row_shl:1 row_mask:0xf bank_mask:0xc
	v_mov_b32_dpp v122, v123 row_shr:1 row_mask:0xf bank_mask:0x3
	v_mov_b32_dpp v122, v123 row_shl:1 row_mask:0xf bank_mask:0xc
	ds_read_b128 v[50:53], v127 offset:49600
	ds_read_b128 v[54:57], v127 offset:49616
	ds_read_b128 v[58:61], v127 offset:50624
	ds_read_b128 v[62:65], v127 offset:50640
	ds_read_b128 v[74:77], v127 offset:48512
	ds_read_b128 v[78:81], v127 offset:48528
	ds_read_b64 v[94:95], v129 offset:48000
	v_pk_mul_f32 v[96:97], v[18:19], v[34:35]
	v_pk_mul_f32 v[98:99], v[18:19], v[42:43]
	v_pk_fma_f32 v[96:97], v[20:21], v[36:37], v[96:97]
	v_pk_fma_f32 v[98:99], v[20:21], v[44:45], v[98:99]
	v_pk_fma_f32 v[96:97], v[22:23], v[38:39], v[96:97]
	v_pk_fma_f32 v[98:99], v[22:23], v[46:47], v[98:99]
	v_pk_fma_f32 v[96:97], v[24:25], v[40:41], v[96:97]
	v_pk_fma_f32 v[98:99], v[24:25], v[48:49], v[98:99]
	v_pk_mul_f32 v[100:101], v[26:27], v[34:35]
	v_pk_mul_f32 v[102:103], v[26:27], v[42:43]
	v_pk_fma_f32 v[100:101], v[28:29], v[36:37], v[100:101]
	v_pk_fma_f32 v[102:103], v[28:29], v[44:45], v[102:103]
	v_pk_fma_f32 v[100:101], v[30:31], v[38:39], v[100:101]
	v_pk_fma_f32 v[102:103], v[30:31], v[46:47], v[102:103]
	v_pk_fma_f32 v[100:101], v[32:33], v[40:41], v[100:101]
	v_pk_fma_f32 v[102:103], v[32:33], v[48:49], v[102:103]
	v_add_f32_e32 v96, v96, v97
	v_add_f32_e32 v98, v98, v99
	v_add_f32_e32 v100, v100, v101
	v_add_f32_e32 v102, v102, v103
	s_waitcnt lgkmcnt(7)
	v_add_f32_dpp v96, v96, v96 quad_perm:[1,0,3,2] row_mask:0xf bank_mask:0xf bound_ctrl:1
	v_add_f32_dpp v98, v98, v98 quad_perm:[1,0,3,2] row_mask:0xf bank_mask:0xf bound_ctrl:1
	v_add_f32_dpp v100, v100, v100 quad_perm:[1,0,3,2] row_mask:0xf bank_mask:0xf bound_ctrl:1
	v_add_f32_dpp v102, v102, v102 quad_perm:[1,0,3,2] row_mask:0xf bank_mask:0xf bound_ctrl:1
	v_pk_mul_f32 v[104:105], v[82:83], v[90:91] op_sel_hi:[1,0]
	v_pk_mul_f32 v[106:107], v[84:85], v[90:91] op_sel_hi:[1,0]
	v_pk_mul_f32 v[108:109], v[86:87], v[90:91] op_sel_hi:[1,0]
	v_pk_mul_f32 v[110:111], v[88:89], v[90:91] op_sel_hi:[1,0]
	v_add_f32_dpp v96, v96, v96 quad_perm:[2,3,0,1] row_mask:0xf bank_mask:0xf bound_ctrl:1
	v_add_f32_dpp v98, v98, v98 quad_perm:[2,3,0,1] row_mask:0xf bank_mask:0xf bound_ctrl:1
	v_add_f32_dpp v100, v100, v100 quad_perm:[2,3,0,1] row_mask:0xf bank_mask:0xf bound_ctrl:1
	v_add_f32_dpp v102, v102, v102 quad_perm:[2,3,0,1] row_mask:0xf bank_mask:0xf bound_ctrl:1
	v_pk_mul_f32 v[112:113], v[82:83], v[90:91] op_sel:[0,1] op_sel_hi:[1,1]
	v_pk_mul_f32 v[114:115], v[84:85], v[90:91] op_sel:[0,1] op_sel_hi:[1,1]
	v_pk_mul_f32 v[116:117], v[86:87], v[90:91] op_sel:[0,1] op_sel_hi:[1,1]
	v_pk_mul_f32 v[118:119], v[88:89], v[90:91] op_sel:[0,1] op_sel_hi:[1,1]
	ds_read_b128 v[82:85], v127 offset:50368
	ds_read_b128 v[86:89], v127 offset:50384
	v_add_f32_dpp v96, v96, v96 row_half_mirror row_mask:0xf bank_mask:0xf bound_ctrl:1
	v_add_f32_dpp v98, v98, v98 row_half_mirror row_mask:0xf bank_mask:0xf bound_ctrl:1
	v_add_f32_dpp v100, v100, v100 row_half_mirror row_mask:0xf bank_mask:0xf bound_ctrl:1
	v_add_f32_dpp v102, v102, v102 row_half_mirror row_mask:0xf bank_mask:0xf bound_ctrl:1
	v_pk_fma_f32 v[104:105], v[18:19], v[66:67], v[104:105]
	v_pk_fma_f32 v[106:107], v[20:21], v[68:69], v[106:107]
	v_pk_fma_f32 v[108:109], v[22:23], v[70:71], v[108:109]
	v_pk_fma_f32 v[110:111], v[24:25], v[72:73], v[110:111]
	v_pk_fma_f32 v[112:113], v[26:27], v[66:67], v[112:113]
	v_pk_fma_f32 v[114:115], v[28:29], v[68:69], v[114:115]
	v_pk_fma_f32 v[116:117], v[30:31], v[70:71], v[116:117]
	v_pk_fma_f32 v[118:119], v[32:33], v[72:73], v[118:119]
	ds_read_b128 v[66:69], v127 offset:49856
	ds_read_b128 v[70:73], v127 offset:49872
	ds_read_b32 v92, v128 offset:49600
	ds_read_b32 v93, v128 offset:49632
	s_waitcnt lgkmcnt(6)
; #define SCAN_BAR() asm volatile("s_waitcnt lgkmcnt(0)\n\ts_barrier" ::: "memory")
; #define SCAN_LOAD_NW(NA, WR, st_) do { const LAS float* rec_ = lb + (st_) * SSTR; \
;                 _Pragma("unroll") for (int g4 = 0; g4 < NG; ++g4) { const int j0 = g4 * (4 * L); NA[g4] = *(const LAS f32x4*)(rec_ + j0); WR[g4] = *(const LAS f32x4*)(rec_ + 256 + j0); } } while (0)
; template <int L, int NSW, int PW0, int NPAIR, int PD> ...
;     ...
;             SCAN_LOAD_NW(naA, wrA, 0);
; #pragma unroll 1
;             for (int st = 0; st < T; st += 2) {
;                 SCAN_LOAD_REST(st);
;                 SCAN_LOAD_NW(naB, wrB, st + 1);
;                 SCAN_STEP(naA, wrA, st);
;                 __builtin_amdgcn_sched_barrier(0);
;                 SCAN_LOAD_REST(st + 1);
;                 if (st + 2 < T) SCAN_LOAD_NW(naA, wrA, st + 2);
;                 SCAN_STEP(naB, wrB, st + 1);
;                 __builtin_amdgcn_sched_barrier(0);
;             }
;     ...
;         }
;             SCAN_BAR();
;         }
	v_pk_fma_f32 v[18:19], v[96:97], v[74:75], v[104:105] op_sel_hi:[0,1,1]
	v_pk_fma_f32 v[20:21], v[96:97], v[76:77], v[106:107] op_sel_hi:[0,1,1]
	v_pk_fma_f32 v[22:23], v[96:97], v[78:79], v[108:109] op_sel_hi:[0,1,1]
	v_pk_fma_f32 v[24:25], v[96:97], v[80:81], v[110:111] op_sel_hi:[0,1,1]
	v_pk_fma_f32 v[26:27], v[100:101], v[74:75], v[112:113] op_sel_hi:[0,1,1]
	v_pk_fma_f32 v[28:29], v[100:101], v[76:77], v[114:115] op_sel_hi:[0,1,1]
	v_pk_fma_f32 v[30:31], v[100:101], v[78:79], v[116:117] op_sel_hi:[0,1,1]
	v_pk_fma_f32 v[32:33], v[100:101], v[80:81], v[118:119] op_sel_hi:[0,1,1]
	v_fma_f32 v124, v90, v95, v98
	v_fma_f32 v125, v91, v95, v102
	v_fma_f32 v121, v96, v94, v124
	v_fma_f32 v123, v100, v94, v125
	v_mov_b32_dpp v121, v120 row_shr:1 row_mask:0xf bank_mask:0x3
	v_mov_b32_dpp v121, v120 row_shl:1 row_mask:0xf bank_mask:0xc
	v_mov_b32_dpp v123, v122 row_shr:1 row_mask:0xf bank_mask:0x3
	v_mov_b32_dpp v123, v122 row_shl:1 row_mask:0xf bank_mask:0xc
	ds_read_b128 v[74:77], v127 offset:50112
	ds_read_b128 v[78:81], v127 offset:50128
	ds_read_b64 v[94:95], v129 offset:49600
	v_pk_mul_f32 v[96:97], v[18:19], v[50:51]
	v_pk_mul_f32 v[98:99], v[18:19], v[58:59]
	v_pk_fma_f32 v[96:97], v[20:21], v[52:53], v[96:97]
	v_pk_fma_f32 v[98:99], v[20:21], v[60:61], v[98:99]
	v_pk_fma_f32 v[96:97], v[22:23], v[54:55], v[96:97]
	v_pk_fma_f32 v[98:99], v[22:23], v[62:63], v[98:99]
	v_pk_fma_f32 v[96:97], v[24:25], v[56:57], v[96:97]
	v_pk_fma_f32 v[98:99], v[24:25], v[64:65], v[98:99]
	v_pk_mul_f32 v[100:101], v[26:27], v[50:51]
	v_pk_mul_f32 v[102:103], v[26:27], v[58:59]
	v_pk_fma_f32 v[100:101], v[28:29], v[52:53], v[100:101]
	v_pk_fma_f32 v[102:103], v[28:29], v[60:61], v[102:103]
	v_pk_fma_f32 v[100:101], v[30:31], v[54:55], v[100:101]
	v_pk_fma_f32 v[102:103], v[30:31], v[62:63], v[102:103]
	v_pk_fma_f32 v[100:101], v[32:33], v[56:57], v[100:101]
	v_pk_fma_f32 v[102:103], v[32:33], v[64:65], v[102:103]
	v_add_f32_e32 v96, v96, v97
	v_add_f32_e32 v98, v98, v99
	v_add_f32_e32 v100, v100, v101
	v_add_f32_e32 v102, v102, v103
	s_waitcnt lgkmcnt(3)
	v_add_f32_dpp v96, v96, v96 quad_perm:[1,0,3,2] row_mask:0xf bank_mask:0xf bound_ctrl:1
	v_add_f32_dpp v98, v98, v98 quad_perm:[1,0,3,2] row_mask:0xf bank_mask:0xf bound_ctrl:1
	v_add_f32_dpp v100, v100, v100 quad_perm:[1,0,3,2] row_mask:0xf bank_mask:0xf bound_ctrl:1
	v_add_f32_dpp v102, v102, v102 quad_perm:[1,0,3,2] row_mask:0xf bank_mask:0xf bound_ctrl:1
	v_pk_mul_f32 v[104:105], v[82:83], v[92:93] op_sel_hi:[1,0]
	v_pk_mul_f32 v[106:107], v[84:85], v[92:93] op_sel_hi:[1,0]
	v_pk_mul_f32 v[108:109], v[86:87], v[92:93] op_sel_hi:[1,0]
	v_pk_mul_f32 v[110:111], v[88:89], v[92:93] op_sel_hi:[1,0]
	v_add_f32_dpp v96, v96, v96 quad_perm:[2,3,0,1] row_mask:0xf bank_mask:0xf bound_ctrl:1
	v_add_f32_dpp v98, v98, v98 quad_perm:[2,3,0,1] row_mask:0xf bank_mask:0xf bound_ctrl:1
	v_add_f32_dpp v100, v100, v100 quad_perm:[2,3,0,1] row_mask:0xf bank_mask:0xf bound_ctrl:1
	v_add_f32_dpp v102, v102, v102 quad_perm:[2,3,0,1] row_mask:0xf bank_mask:0xf bound_ctrl:1
	v_pk_mul_f32 v[112:113], v[82:83], v[92:93] op_sel:[0,1] op_sel_hi:[1,1]
	v_pk_mul_f32 v[114:115], v[84:85], v[92:93] op_sel:[0,1] op_sel_hi:[1,1]
	v_pk_mul_f32 v[116:117], v[86:87], v[92:93] op_sel:[0,1] op_sel_hi:[1,1]
	v_pk_mul_f32 v[118:119], v[88:89], v[92:93] op_sel:[0,1] op_sel_hi:[1,1]
	v_add_f32_dpp v96, v96, v96 row_half_mirror row_mask:0xf bank_mask:0xf bound_ctrl:1
	v_add_f32_dpp v98, v98, v98 row_half_mirror row_mask:0xf bank_mask:0xf bound_ctrl:1
	v_add_f32_dpp v100, v100, v100 row_half_mirror row_mask:0xf bank_mask:0xf bound_ctrl:1
	v_add_f32_dpp v102, v102, v102 row_half_mirror row_mask:0xf bank_mask:0xf bound_ctrl:1
	v_pk_fma_f32 v[104:105], v[18:19], v[66:67], v[104:105]
	v_pk_fma_f32 v[106:107], v[20:21], v[68:69], v[106:107]
	v_pk_fma_f32 v[108:109], v[22:23], v[70:71], v[108:109]
	v_pk_fma_f32 v[110:111], v[24:25], v[72:73], v[110:111]
	v_pk_fma_f32 v[112:113], v[26:27], v[66:67], v[112:113]
	v_pk_fma_f32 v[114:115], v[28:29], v[68:69], v[114:115]
	v_pk_fma_f32 v[116:117], v[30:31], v[70:71], v[116:117]
	v_pk_fma_f32 v[118:119], v[32:33], v[72:73], v[118:119]
	s_waitcnt lgkmcnt(0)
	v_pk_fma_f32 v[18:19], v[96:97], v[74:75], v[104:105] op_sel_hi:[0,1,1]
	v_pk_fma_f32 v[20:21], v[96:97], v[76:77], v[106:107] op_sel_hi:[0,1,1]
	v_pk_fma_f32 v[22:23], v[96:97], v[78:79], v[108:109] op_sel_hi:[0,1,1]
	v_pk_fma_f32 v[24:25], v[96:97], v[80:81], v[110:111] op_sel_hi:[0,1,1]
	v_pk_fma_f32 v[26:27], v[100:101], v[74:75], v[112:113] op_sel_hi:[0,1,1]
	v_pk_fma_f32 v[28:29], v[100:101], v[76:77], v[114:115] op_sel_hi:[0,1,1]
	v_pk_fma_f32 v[30:31], v[100:101], v[78:79], v[116:117] op_sel_hi:[0,1,1]
	v_pk_fma_f32 v[32:33], v[100:101], v[80:81], v[118:119] op_sel_hi:[0,1,1]
	v_fma_f32 v124, v92, v95, v98
	v_fma_f32 v125, v93, v95, v102
	v_fma_f32 v120, v96, v94, v124
	v_fma_f32 v122, v100, v94, v125
	v_mov_b32_dpp v120, v121 row_shr:1 row_mask:0xf bank_mask:0x3
	v_mov_b32_dpp v120, v121 row_shl:1 row_mask:0xf bank_mask:0xc
	v_mov_b32_dpp v122, v123 row_shr:1 row_mask:0xf bank_mask:0x3
	v_mov_b32_dpp v122, v123 row_shl:1 row_mask:0xf bank_mask:0xc
	v_cvt_pk_bf16_f32 v126, v120, v120
	v_cvt_pk_bf16_f32 v139, v122, v122
	global_store_short v[130:131], v126, off
	global_store_short v[130:131], v139, off offset:16
	v_lshl_add_u64 v[130:131], v[130:131], 0, v[132:133]
.Lsc8_bar:
	s_waitcnt lgkmcnt(0)
	s_barrier
	s_add_i32 s50, s50, 1
	s_cmp_lg_u32 s50, 64
	s_cbranch_scc1 .Lsc8_chunk
	s_branch .LBB0_679
